# re-measure: s_setprio removed from the GEMM K loops (same file as before)
# speedup vs baseline: 1.0079x; 1.0005x over previous
; #define PG8_STAGE(bufoff, gbase, voff) do { _Pragma("unroll") for (int _i = 0; _i < 2; ++_i) \
;         __builtin_amdgcn_global_load_lds((const unsigned*)((const char*)(gbase) + (voff)[_i]), (PG8_LAS unsigned*)(lds + (bufoff) + ldsw + _i * 8192), 16, 0, 0); } while (0)
; #define PG8_LDA(dst, b, h) do { _Pragma("unroll") for (int m = 0; m < 4; ++m) _Pragma("unroll") for (int k = 0; k < 2; ++k) dst[m][k] = *(const PG8_LAS bf16x8*)(lds + PG8_SA(b, h) + aoff + m * 2048 + k * 1024); } while (0)
; #define PG8_LDB(dst, b, h) do { _Pragma("unroll") for (int n = 0; n < 2; ++n) _Pragma("unroll") for (int k = 0; k < 2; ++k) dst[n][k] = *(const PG8_LAS bf16x8*)(lds + PG8_SB(b, h) + boff + n * 2048 + k * 1024); } while (0)
; #define PG8_MMA(ai, bj, At, Bt) do { __builtin_amdgcn_s_setprio(1); _Pragma("unroll") for (int m = 0; m < 4; ++m) _Pragma("unroll") for (int n = 0; n < 2; ++n) _Pragma("unroll") for (int k = 0; k < 2; ++k) \
;         acc[ai][bj][m][n] = __builtin_amdgcn_mfma_f32_16x16x32_bf16(Bt[n][k], At[m][k], acc[ai][bj][m][n], 0, 0, 0); __builtin_amdgcn_s_setprio(0); } while (0)
; #define PG8_WAIT_V(n) asm volatile("s_waitcnt vmcnt(" #n ")" ::: "memory")
; #define PG8_WAIT_L(n) asm volatile("s_waitcnt lgkmcnt(" #n ")" ::: "memory")
; #define PG8_BAR __builtin_amdgcn_s_barrier()
; #define PG8_SCHED __builtin_amdgcn_sched_barrier(0)
; template <class Epi, class Sched, bool ALIGN_EPI = false, bool SP2 = false>
; __device__ __forceinline__ void gemm_phase(PG8_LAS unsigned char* lds, const Gemm g, const Sched& S, const Epi& E, const int tid_in) {
;     ...
;             PG8_LDB(B0, 0, 0); PG8_LDB(B1, 0, 1); PG8_SCHED; PG8_LDA(At, 0, 0); PG8_STAGE(PG8_SA(1, 1), a1 + hstep, voffA);
;             PG8_WAIT_V(8); PG8_WAIT_L(0); PG8_BAR; PG8_MMA(0, 0, At, B0); PG8_MMA(0, 1, At, B1); PG8_BAR; PG8_SCHED;
;             PG8_LDA(At, 0, 1); PG8_STAGE(PG8_SB(0, 0), b2, voffB); PG8_STAGE(PG8_SB(0, 1), b2 + hstep, voffB); PG8_STAGE(PG8_SA(0, 0), a2, voffA);
.LBB0_127:
	ds_read_b128 v[128:131], v190
	ds_read_b128 v[132:135], v190 offset:1024
	ds_read_b128 v[136:139], v190 offset:2048
	ds_read_b128 v[140:143], v190 offset:3072
	ds_read_b128 v[166:169], v191
	ds_read_b128 v[194:197], v191 offset:1024
	ds_read_b128 v[198:201], v191 offset:2048
	ds_read_b128 v[202:205], v191 offset:3072
	s_add_u32 s34, s0, 0xfffc0080
	s_addc_u32 s35, s1, -1
	s_cmp_eq_u32 s59, 12
	s_cselect_b32 s37, s5, s35
	s_cselect_b32 s36, s25, s34
	s_cselect_b32 s35, s23, s58
	s_cselect_b32 s34, s56, s57
	v_lshl_add_u64 v[170:171], s[0:1], 0, v[158:159]
	s_add_i32 m0, s31, 0xc000
	ds_read_b128 v[206:209], v192
	ds_read_b128 v[210:213], v192 offset:1024
	ds_read_b128 v[214:217], v192 offset:2048
	ds_read_b128 v[218:221], v192 offset:3072
	ds_read_b128 v[222:225], v192 offset:4096
	ds_read_b128 v[226:229], v192 offset:5120
	ds_read_b128 v[230:233], v192 offset:6144
	ds_read_b128 v[234:237], v192 offset:7168
	global_load_lds_dwordx4 v[170:171], off
	v_lshl_add_u64 v[170:171], s[0:1], 0, v[160:161]
	s_add_i32 m0, s31, 0xe000
	s_nop 0
	global_load_lds_dwordx4 v[170:171], off
	s_waitcnt vmcnt(8)
	s_waitcnt lgkmcnt(0)
	s_barrier
	s_waitcnt lgkmcnt(0)
	v_mfma_f32_16x16x32_bf16 v[124:127], v[128:131], v[206:209], v[124:127]
	v_mfma_f32_16x16x32_bf16 v[120:123], v[136:139], v[206:209], v[120:123]
	v_mfma_f32_16x16x32_bf16 v[108:111], v[128:131], v[214:217], v[108:111]
	v_mfma_f32_16x16x32_bf16 v[104:107], v[136:139], v[214:217], v[104:107]
	v_mfma_f32_16x16x32_bf16 v[92:95], v[128:131], v[222:225], v[92:95]
	v_mfma_f32_16x16x32_bf16 v[88:91], v[136:139], v[222:225], v[88:91]
	v_mfma_f32_16x16x32_bf16 v[76:79], v[128:131], v[230:233], v[76:79]
	v_mfma_f32_16x16x32_bf16 v[72:75], v[136:139], v[230:233], v[72:75]
	v_mfma_f32_16x16x32_bf16 v[124:127], v[132:135], v[210:213], v[124:127]
	v_mfma_f32_16x16x32_bf16 v[120:123], v[140:143], v[210:213], v[120:123]
	v_mfma_f32_16x16x32_bf16 v[108:111], v[132:135], v[218:221], v[108:111]
	v_mfma_f32_16x16x32_bf16 v[104:107], v[140:143], v[218:221], v[104:107]
	v_mfma_f32_16x16x32_bf16 v[92:95], v[132:135], v[226:229], v[92:95]
	v_mfma_f32_16x16x32_bf16 v[88:91], v[140:143], v[226:229], v[88:91]
	v_mfma_f32_16x16x32_bf16 v[76:79], v[132:135], v[234:237], v[76:79]
	v_mfma_f32_16x16x32_bf16 v[72:75], v[140:143], v[234:237], v[72:75]
	v_mfma_f32_16x16x32_bf16 v[116:119], v[166:169], v[206:209], v[116:119]
	v_mfma_f32_16x16x32_bf16 v[112:115], v[198:201], v[206:209], v[112:115]
	v_mfma_f32_16x16x32_bf16 v[100:103], v[166:169], v[214:217], v[100:103]
	v_mfma_f32_16x16x32_bf16 v[96:99], v[198:201], v[214:217], v[96:99]
	v_mfma_f32_16x16x32_bf16 v[84:87], v[166:169], v[222:225], v[84:87]
	v_mfma_f32_16x16x32_bf16 v[80:83], v[198:201], v[222:225], v[80:83]
	v_mfma_f32_16x16x32_bf16 v[68:71], v[166:169], v[230:233], v[68:71]
	v_mfma_f32_16x16x32_bf16 v[64:67], v[198:201], v[230:233], v[64:67]
	v_mfma_f32_16x16x32_bf16 v[116:119], v[194:197], v[210:213], v[116:119]
	v_mfma_f32_16x16x32_bf16 v[112:115], v[202:205], v[210:213], v[112:115]
	v_mfma_f32_16x16x32_bf16 v[100:103], v[194:197], v[218:221], v[100:103]
	v_mfma_f32_16x16x32_bf16 v[96:99], v[202:205], v[218:221], v[96:99]
	v_mfma_f32_16x16x32_bf16 v[84:87], v[194:197], v[226:229], v[84:87]
	v_mfma_f32_16x16x32_bf16 v[80:83], v[202:205], v[226:229], v[80:83]
	v_mfma_f32_16x16x32_bf16 v[68:71], v[194:197], v[234:237], v[68:71]
	v_mfma_f32_16x16x32_bf16 v[64:67], v[202:205], v[234:237], v[64:67]
	s_barrier
	s_add_i32 s60, s49, s41
	v_lshl_add_u64 v[170:171], s[34:35], 0, v[146:147]
	s_mov_b32 m0, s60
	ds_read_b128 v[206:209], v192 offset:16384
	ds_read_b128 v[210:213], v192 offset:17408
	ds_read_b128 v[214:217], v192 offset:18432
	ds_read_b128 v[218:221], v192 offset:19456
	ds_read_b128 v[222:225], v192 offset:20480
	ds_read_b128 v[226:229], v192 offset:21504
	ds_read_b128 v[230:233], v192 offset:22528
	ds_read_b128 v[234:237], v192 offset:23552
	global_load_lds_dwordx4 v[170:171], off
	s_add_i32 m0, s60, 0x2000
	s_add_u32 s60, s34, 0x40000
	v_lshl_add_u64 v[238:239], s[34:35], 0, v[150:151]
	s_addc_u32 s61, s35, 0
	s_add_i32 s62, s52, s41
	global_load_lds_dwordx4 v[238:239], off
	v_lshl_add_u64 v[240:241], s[60:61], 0, v[146:147]
	s_mov_b32 m0, s62
	v_lshl_add_u64 v[242:243], s[36:37], 0, v[148:149]
	global_load_lds_dwordx4 v[240:241], off
	v_lshl_add_u64 v[240:241], s[60:61], 0, v[150:151]
	s_add_i32 m0, s62, 0x2000
	s_nop 0
	global_load_lds_dwordx4 v[240:241], off
	v_lshl_add_u64 v[240:241], s[36:37], 0, v[144:145]
	s_mov_b32 m0, s31
	s_nop 0
	global_load_lds_dwordx4 v[240:241], off
	s_mov_b32 m0, s42
	s_nop 0
	global_load_lds_dwordx4 v[242:243], off
	s_waitcnt vmcnt(8)
	s_waitcnt lgkmcnt(0)
	s_barrier
; #define PG8_STAGE(bufoff, gbase, voff) do { _Pragma("unroll") for (int _i = 0; _i < 2; ++_i) \
;         __builtin_amdgcn_global_load_lds((const unsigned*)((const char*)(gbase) + (voff)[_i]), (PG8_LAS unsigned*)(lds + (bufoff) + ldsw + _i * 8192), 16, 0, 0); } while (0)
; #define PG8_LDA(dst, b, h) do { _Pragma("unroll") for (int m = 0; m < 4; ++m) _Pragma("unroll") for (int k = 0; k < 2; ++k) dst[m][k] = *(const PG8_LAS bf16x8*)(lds + PG8_SA(b, h) + aoff + m * 2048 + k * 1024); } while (0)
; #define PG8_LDB(dst, b, h) do { _Pragma("unroll") for (int n = 0; n < 2; ++n) _Pragma("unroll") for (int k = 0; k < 2; ++k) dst[n][k] = *(const PG8_LAS bf16x8*)(lds + PG8_SB(b, h) + boff + n * 2048 + k * 1024); } while (0)
; #define PG8_MMA(ai, bj, At, Bt) do { __builtin_amdgcn_s_setprio(1); _Pragma("unroll") for (int m = 0; m < 4; ++m) _Pragma("unroll") for (int n = 0; n < 2; ++n) _Pragma("unroll") for (int k = 0; k < 2; ++k) \
;         acc[ai][bj][m][n] = __builtin_amdgcn_mfma_f32_16x16x32_bf16(Bt[n][k], At[m][k], acc[ai][bj][m][n], 0, 0, 0); __builtin_amdgcn_s_setprio(0); } while (0)
; #define PG8_WAIT_V(n) asm volatile("s_waitcnt vmcnt(" #n ")" ::: "memory")
; #define PG8_WAIT_L(n) asm volatile("s_waitcnt lgkmcnt(" #n ")" ::: "memory")
; #define PG8_BAR __builtin_amdgcn_s_barrier()
; #define PG8_SCHED __builtin_amdgcn_sched_barrier(0)
; template <class Epi, class Sched, bool ALIGN_EPI = false, bool SP2 = false>
; __device__ __forceinline__ void gemm_phase(PG8_LAS unsigned char* lds, const Gemm g, const Sched& S, const Epi& E, const int tid_in) {
;     ...
;             PG8_WAIT_V(8); PG8_WAIT_L(0); PG8_BAR; PG8_MMA(0, 0, At, B0); PG8_MMA(0, 1, At, B1); PG8_BAR; PG8_SCHED;
;             PG8_LDA(At, 0, 1); PG8_STAGE(PG8_SB(0, 0), b2, voffB); PG8_STAGE(PG8_SB(0, 1), b2 + hstep, voffB); PG8_STAGE(PG8_SA(0, 0), a2, voffA);
;             PG8_WAIT_V(8); PG8_WAIT_L(0); PG8_BAR; PG8_MMA(1, 0, At, B0); PG8_MMA(1, 1, At, B1); PG8_BAR; PG8_SCHED;
;             PG8_LDB(B0, 1, 0); PG8_LDB(B1, 1, 1); PG8_SCHED; PG8_LDA(At, 1, 0); PG8_STAGE(PG8_SA(0, 1), a2 + hstep, voffA);
;             PG8_WAIT_V(8); PG8_WAIT_L(0); PG8_BAR; PG8_MMA(0, 0, At, B0); PG8_MMA(0, 1, At, B1); PG8_BAR; PG8_SCHED;
	s_waitcnt lgkmcnt(0)
	v_mfma_f32_16x16x32_bf16 v[60:63], v[128:131], v[206:209], v[60:63]
	v_mfma_f32_16x16x32_bf16 v[56:59], v[136:139], v[206:209], v[56:59]
	v_mfma_f32_16x16x32_bf16 v[44:47], v[128:131], v[214:217], v[44:47]
	v_mfma_f32_16x16x32_bf16 v[40:43], v[136:139], v[214:217], v[40:43]
	v_mfma_f32_16x16x32_bf16 v[28:31], v[128:131], v[222:225], v[28:31]
	v_mfma_f32_16x16x32_bf16 v[24:27], v[136:139], v[222:225], v[24:27]
	v_mfma_f32_16x16x32_bf16 v[12:15], v[128:131], v[230:233], v[12:15]
	v_mfma_f32_16x16x32_bf16 v[8:11], v[136:139], v[230:233], v[8:11]
	v_mfma_f32_16x16x32_bf16 v[60:63], v[132:135], v[210:213], v[60:63]
	v_mfma_f32_16x16x32_bf16 v[56:59], v[140:143], v[210:213], v[56:59]
	v_mfma_f32_16x16x32_bf16 v[44:47], v[132:135], v[218:221], v[44:47]
	v_mfma_f32_16x16x32_bf16 v[40:43], v[140:143], v[218:221], v[40:43]
	v_mfma_f32_16x16x32_bf16 v[28:31], v[132:135], v[226:229], v[28:31]
	v_mfma_f32_16x16x32_bf16 v[24:27], v[140:143], v[226:229], v[24:27]
	v_mfma_f32_16x16x32_bf16 v[12:15], v[132:135], v[234:237], v[12:15]
	v_mfma_f32_16x16x32_bf16 v[8:11], v[140:143], v[234:237], v[8:11]
	v_mfma_f32_16x16x32_bf16 v[52:55], v[166:169], v[206:209], v[52:55]
	v_mfma_f32_16x16x32_bf16 v[48:51], v[198:201], v[206:209], v[48:51]
	v_mfma_f32_16x16x32_bf16 v[36:39], v[166:169], v[214:217], v[36:39]
	v_mfma_f32_16x16x32_bf16 v[32:35], v[198:201], v[214:217], v[32:35]
	v_mfma_f32_16x16x32_bf16 v[20:23], v[166:169], v[222:225], v[20:23]
	v_mfma_f32_16x16x32_bf16 v[16:19], v[198:201], v[222:225], v[16:19]
	v_mfma_f32_16x16x32_bf16 v[4:7], v[166:169], v[230:233], v[4:7]
	v_mfma_f32_16x16x32_bf16 v[0:3], v[198:201], v[230:233], v[0:3]
	v_mfma_f32_16x16x32_bf16 v[52:55], v[194:197], v[210:213], v[52:55]
	v_mfma_f32_16x16x32_bf16 v[48:51], v[202:205], v[210:213], v[48:51]
	v_mfma_f32_16x16x32_bf16 v[36:39], v[194:197], v[218:221], v[36:39]
	v_mfma_f32_16x16x32_bf16 v[32:35], v[202:205], v[218:221], v[32:35]
	v_mfma_f32_16x16x32_bf16 v[20:23], v[194:197], v[226:229], v[20:23]
	v_mfma_f32_16x16x32_bf16 v[16:19], v[202:205], v[226:229], v[16:19]
	v_mfma_f32_16x16x32_bf16 v[4:7], v[194:197], v[234:237], v[4:7]
	v_mfma_f32_16x16x32_bf16 v[0:3], v[202:205], v[234:237], v[0:3]
	s_barrier
	s_add_i32 s60, 0, 0x18000
	s_add_i32 s61, 0, 0x1c000
	v_add_u32_e32 v140, s60, v188
	v_add_u32_e32 v152, s61, v188
	ds_read_b128 v[128:131], v140
	ds_read_b128 v[132:135], v140 offset:1024
	ds_read_b128 v[136:139], v140 offset:2048
	ds_read_b128 v[140:143], v140 offset:3072
	ds_read_b128 v[166:169], v152
	ds_read_b128 v[194:197], v152 offset:1024
	ds_read_b128 v[198:201], v152 offset:2048
	ds_read_b128 v[202:205], v152 offset:3072
	s_add_u32 s36, s36, 0x40000
	s_addc_u32 s37, s37, 0
	s_mov_b32 m0, s43
	v_lshl_add_u64 v[244:245], s[36:37], 0, v[144:145]
	ds_read_b128 v[206:209], v192 offset:32768
	ds_read_b128 v[210:213], v192 offset:33792
	ds_read_b128 v[214:217], v192 offset:34816
	ds_read_b128 v[218:221], v192 offset:35840
	ds_read_b128 v[222:225], v192 offset:36864
	ds_read_b128 v[226:229], v192 offset:37888
	ds_read_b128 v[230:233], v192 offset:38912
	ds_read_b128 v[234:237], v192 offset:39936
	global_load_lds_dwordx4 v[244:245], off
	v_lshl_add_u64 v[244:245], s[36:37], 0, v[148:149]
	s_mov_b32 m0, s44
	s_nop 0
	global_load_lds_dwordx4 v[244:245], off
	s_waitcnt vmcnt(8)
	s_waitcnt lgkmcnt(0)
	s_barrier
	s_waitcnt lgkmcnt(0)
	v_mfma_f32_16x16x32_bf16 v[124:127], v[128:131], v[206:209], v[124:127]
	v_mfma_f32_16x16x32_bf16 v[120:123], v[136:139], v[206:209], v[120:123]
	v_mfma_f32_16x16x32_bf16 v[108:111], v[128:131], v[214:217], v[108:111]
	v_mfma_f32_16x16x32_bf16 v[104:107], v[136:139], v[214:217], v[104:107]
	v_mfma_f32_16x16x32_bf16 v[92:95], v[128:131], v[222:225], v[92:95]
	v_mfma_f32_16x16x32_bf16 v[88:91], v[136:139], v[222:225], v[88:91]
	v_mfma_f32_16x16x32_bf16 v[76:79], v[128:131], v[230:233], v[76:79]
	v_mfma_f32_16x16x32_bf16 v[72:75], v[136:139], v[230:233], v[72:75]
	v_mfma_f32_16x16x32_bf16 v[124:127], v[132:135], v[210:213], v[124:127]
	v_mfma_f32_16x16x32_bf16 v[120:123], v[140:143], v[210:213], v[120:123]
	v_mfma_f32_16x16x32_bf16 v[108:111], v[132:135], v[218:221], v[108:111]
	v_mfma_f32_16x16x32_bf16 v[104:107], v[140:143], v[218:221], v[104:107]
	v_mfma_f32_16x16x32_bf16 v[92:95], v[132:135], v[226:229], v[92:95]
	v_mfma_f32_16x16x32_bf16 v[88:91], v[140:143], v[226:229], v[88:91]
	v_mfma_f32_16x16x32_bf16 v[76:79], v[132:135], v[234:237], v[76:79]
	v_mfma_f32_16x16x32_bf16 v[72:75], v[140:143], v[234:237], v[72:75]
	v_mfma_f32_16x16x32_bf16 v[116:119], v[166:169], v[206:209], v[116:119]
	v_mfma_f32_16x16x32_bf16 v[112:115], v[198:201], v[206:209], v[112:115]
	v_mfma_f32_16x16x32_bf16 v[100:103], v[166:169], v[214:217], v[100:103]
	v_mfma_f32_16x16x32_bf16 v[96:99], v[198:201], v[214:217], v[96:99]
	v_mfma_f32_16x16x32_bf16 v[84:87], v[166:169], v[222:225], v[84:87]
	v_mfma_f32_16x16x32_bf16 v[80:83], v[198:201], v[222:225], v[80:83]
	v_mfma_f32_16x16x32_bf16 v[68:71], v[166:169], v[230:233], v[68:71]
	v_mfma_f32_16x16x32_bf16 v[64:67], v[198:201], v[230:233], v[64:67]
	v_mfma_f32_16x16x32_bf16 v[116:119], v[194:197], v[210:213], v[116:119]
	v_mfma_f32_16x16x32_bf16 v[112:115], v[202:205], v[210:213], v[112:115]
	v_mfma_f32_16x16x32_bf16 v[100:103], v[194:197], v[218:221], v[100:103]
	v_mfma_f32_16x16x32_bf16 v[96:99], v[202:205], v[218:221], v[96:99]
	v_mfma_f32_16x16x32_bf16 v[84:87], v[194:197], v[226:229], v[84:87]
	v_mfma_f32_16x16x32_bf16 v[80:83], v[202:205], v[226:229], v[80:83]
	v_mfma_f32_16x16x32_bf16 v[68:71], v[194:197], v[234:237], v[68:71]
	v_mfma_f32_16x16x32_bf16 v[64:67], v[202:205], v[234:237], v[64:67]
	s_barrier
; #define PG8_STAGE(bufoff, gbase, voff) do { _Pragma("unroll") for (int _i = 0; _i < 2; ++_i) \
;         __builtin_amdgcn_global_load_lds((const unsigned*)((const char*)(gbase) + (voff)[_i]), (PG8_LAS unsigned*)(lds + (bufoff) + ldsw + _i * 8192), 16, 0, 0); } while (0)
; #define PG8_LDA(dst, b, h) do { _Pragma("unroll") for (int m = 0; m < 4; ++m) _Pragma("unroll") for (int k = 0; k < 2; ++k) dst[m][k] = *(const PG8_LAS bf16x8*)(lds + PG8_SA(b, h) + aoff + m * 2048 + k * 1024); } while (0)
; #define PG8_MMA(ai, bj, At, Bt) do { __builtin_amdgcn_s_setprio(1); _Pragma("unroll") for (int m = 0; m < 4; ++m) _Pragma("unroll") for (int n = 0; n < 2; ++n) _Pragma("unroll") for (int k = 0; k < 2; ++k) \
;         acc[ai][bj][m][n] = __builtin_amdgcn_mfma_f32_16x16x32_bf16(Bt[n][k], At[m][k], acc[ai][bj][m][n], 0, 0, 0); __builtin_amdgcn_s_setprio(0); } while (0)
; #define PG8_WAIT_V(n) asm volatile("s_waitcnt vmcnt(" #n ")" ::: "memory")
; #define PG8_WAIT_L(n) asm volatile("s_waitcnt lgkmcnt(" #n ")" ::: "memory")
; #define PG8_BAR __builtin_amdgcn_s_barrier()
; #define PG8_SCHED __builtin_amdgcn_sched_barrier(0)
; template <class Epi, class Sched, bool ALIGN_EPI = false, bool SP2 = false>
; __device__ __forceinline__ void gemm_phase(PG8_LAS unsigned char* lds, const Gemm g, const Sched& S, const Epi& E, const int tid_in) {
;     ...
;             PG8_WAIT_V(8); PG8_WAIT_L(0); PG8_BAR; PG8_MMA(0, 0, At, B0); PG8_MMA(0, 1, At, B1); PG8_BAR; PG8_SCHED;
;             PG8_LDA(At, 1, 1); PG8_STAGE(PG8_SB(1, 0), b3, voffB); PG8_STAGE(PG8_SB(1, 1), b3 + hstep, voffB); PG8_STAGE(PG8_SA(1, 0), a3, voffA);
;             PG8_WAIT_V(8); PG8_WAIT_L(0); PG8_BAR; PG8_MMA(1, 0, At, B0); PG8_MMA(1, 1, At, B1); PG8_BAR; PG8_SCHED;
	s_add_i32 s36, s60, s41
	v_lshl_add_u64 v[170:171], v[170:171], 0, s[18:19]
	s_mov_b32 m0, s36
	ds_read_b128 v[206:209], v192 offset:49152
	ds_read_b128 v[210:213], v192 offset:50176
	ds_read_b128 v[214:217], v192 offset:51200
	ds_read_b128 v[218:221], v192 offset:52224
	ds_read_b128 v[222:225], v192 offset:53248
	ds_read_b128 v[226:229], v192 offset:54272
	ds_read_b128 v[230:233], v192 offset:55296
	ds_read_b128 v[234:237], v192 offset:56320
	global_load_lds_dwordx4 v[170:171], off
	s_add_i32 m0, s36, 0x2000
	s_add_u32 s34, s34, 0x40080
	v_lshl_add_u64 v[170:171], v[238:239], 0, s[18:19]
	s_addc_u32 s35, s35, 0
	s_add_i32 s36, s61, s41
	global_load_lds_dwordx4 v[170:171], off
	v_lshl_add_u64 v[170:171], s[34:35], 0, v[146:147]
	s_mov_b32 m0, s36
	s_nop 0
	global_load_lds_dwordx4 v[170:171], off
	v_lshl_add_u64 v[170:171], s[34:35], 0, v[150:151]
	s_add_i32 m0, s36, 0x2000
	s_nop 0
	global_load_lds_dwordx4 v[170:171], off
	v_lshl_add_u64 v[170:171], v[240:241], 0, s[18:19]
	s_mov_b32 m0, s46
	s_nop 0
	global_load_lds_dwordx4 v[170:171], off
	v_lshl_add_u64 v[170:171], v[242:243], 0, s[18:19]
	s_mov_b32 m0, s47
	s_nop 0
	global_load_lds_dwordx4 v[170:171], off
	s_waitcnt vmcnt(8)
	s_waitcnt lgkmcnt(0)
	s_barrier
	s_waitcnt lgkmcnt(0)
	v_mfma_f32_16x16x32_bf16 v[60:63], v[128:131], v[206:209], v[60:63]
	v_mfma_f32_16x16x32_bf16 v[56:59], v[136:139], v[206:209], v[56:59]
	v_mfma_f32_16x16x32_bf16 v[44:47], v[128:131], v[214:217], v[44:47]
	v_mfma_f32_16x16x32_bf16 v[40:43], v[136:139], v[214:217], v[40:43]
	v_mfma_f32_16x16x32_bf16 v[28:31], v[128:131], v[222:225], v[28:31]
	v_mfma_f32_16x16x32_bf16 v[24:27], v[136:139], v[222:225], v[24:27]
	v_mfma_f32_16x16x32_bf16 v[12:15], v[128:131], v[230:233], v[12:15]
	v_mfma_f32_16x16x32_bf16 v[8:11], v[136:139], v[230:233], v[8:11]
	v_mfma_f32_16x16x32_bf16 v[60:63], v[132:135], v[210:213], v[60:63]
	v_mfma_f32_16x16x32_bf16 v[56:59], v[140:143], v[210:213], v[56:59]
	v_mfma_f32_16x16x32_bf16 v[44:47], v[132:135], v[218:221], v[44:47]
	v_mfma_f32_16x16x32_bf16 v[40:43], v[140:143], v[218:221], v[40:43]
	v_mfma_f32_16x16x32_bf16 v[28:31], v[132:135], v[226:229], v[28:31]
	v_mfma_f32_16x16x32_bf16 v[24:27], v[140:143], v[226:229], v[24:27]
	v_mfma_f32_16x16x32_bf16 v[12:15], v[132:135], v[234:237], v[12:15]
	v_mfma_f32_16x16x32_bf16 v[8:11], v[140:143], v[234:237], v[8:11]
	v_mfma_f32_16x16x32_bf16 v[52:55], v[166:169], v[206:209], v[52:55]
	v_mfma_f32_16x16x32_bf16 v[48:51], v[198:201], v[206:209], v[48:51]
	v_mfma_f32_16x16x32_bf16 v[36:39], v[166:169], v[214:217], v[36:39]
	v_mfma_f32_16x16x32_bf16 v[32:35], v[198:201], v[214:217], v[32:35]
	v_mfma_f32_16x16x32_bf16 v[20:23], v[166:169], v[222:225], v[20:23]
	v_mfma_f32_16x16x32_bf16 v[16:19], v[198:201], v[222:225], v[16:19]
	v_mfma_f32_16x16x32_bf16 v[4:7], v[166:169], v[230:233], v[4:7]
	v_mfma_f32_16x16x32_bf16 v[0:3], v[198:201], v[230:233], v[0:3]
	v_mfma_f32_16x16x32_bf16 v[52:55], v[194:197], v[210:213], v[52:55]
	v_mfma_f32_16x16x32_bf16 v[48:51], v[202:205], v[210:213], v[48:51]
	v_mfma_f32_16x16x32_bf16 v[36:39], v[194:197], v[218:221], v[36:39]
	v_mfma_f32_16x16x32_bf16 v[32:35], v[202:205], v[218:221], v[32:35]
	v_mfma_f32_16x16x32_bf16 v[20:23], v[194:197], v[226:229], v[20:23]
	v_mfma_f32_16x16x32_bf16 v[16:19], v[202:205], v[226:229], v[16:19]
	v_mfma_f32_16x16x32_bf16 v[4:7], v[194:197], v[234:237], v[4:7]
	v_mfma_f32_16x16x32_bf16 v[0:3], v[202:205], v[234:237], v[0:3]
	s_barrier
	s_add_i32 s59, s59, 2
	s_add_u32 s0, s0, 0x100
	s_addc_u32 s1, s1, 0
	s_add_u32 s57, s57, 0x100
	s_addc_u32 s58, s58, 0
	s_cmp_gt_u32 s59, 13
	s_cbranch_scc0 .LBB0_127
	s_and_b64 vcc, exec, s[20:21]
	s_cbranch_vccz .LBB0_130
	s_barrier

; #define PG8_STAGE(bufoff, gbase, voff) do { _Pragma("unroll") for (int _i = 0; _i < 2; ++_i) \
;         __builtin_amdgcn_global_load_lds((const unsigned*)((const char*)(gbase) + (voff)[_i]), (PG8_LAS unsigned*)(lds + (bufoff) + ldsw + _i * 8192), 16, 0, 0); } while (0)
; #define PG8_LDA(dst, b, h) do { _Pragma("unroll") for (int m = 0; m < 4; ++m) _Pragma("unroll") for (int k = 0; k < 2; ++k) dst[m][k] = *(const PG8_LAS bf16x8*)(lds + PG8_SA(b, h) + aoff + m * 2048 + k * 1024); } while (0)
; #define PG8_LDB(dst, b, h) do { _Pragma("unroll") for (int n = 0; n < 2; ++n) _Pragma("unroll") for (int k = 0; k < 2; ++k) dst[n][k] = *(const PG8_LAS bf16x8*)(lds + PG8_SB(b, h) + boff + n * 2048 + k * 1024); } while (0)
; #define PG8_MMA(ai, bj, At, Bt) do { __builtin_amdgcn_s_setprio(1); _Pragma("unroll") for (int m = 0; m < 4; ++m) _Pragma("unroll") for (int n = 0; n < 2; ++n) _Pragma("unroll") for (int k = 0; k < 2; ++k) \
;         acc[ai][bj][m][n] = __builtin_amdgcn_mfma_f32_16x16x32_bf16(Bt[n][k], At[m][k], acc[ai][bj][m][n], 0, 0, 0); __builtin_amdgcn_s_setprio(0); } while (0)
; #define PG8_WAIT_V(n) asm volatile("s_waitcnt vmcnt(" #n ")" ::: "memory")
; #define PG8_WAIT_L(n) asm volatile("s_waitcnt lgkmcnt(" #n ")" ::: "memory")
; template <class Epi, class Sched, bool ALIGN_EPI = false, bool SP2 = false>
; __device__ __forceinline__ void gemm_phase(PG8_LAS unsigned char* lds, const Gemm g, const Sched& S, const Epi& E, const int tid_in) {
;     ...
;         const bool has_next = S.next(ui + 1, nxt);
;         const char* nA = has_next ? (const char*)g.asel(nxt.pn) + (size_t)nxt.pm * tstep : cA; const char* nB = has_next ? (const char*)g.Bt + (size_t)nxt.pn * tstep : cB;
;         for (int t = 0; t < nt; t += 2) {
;             const bool last = (t == nt - 2);
;             const char* a1 = cA + (size_t)(t + 1) * kstep;
;             const char* a2 = last ? nA : cA + (size_t)(t + 2) * kstep; const char* b2 = last ? nB : cB + (size_t)(t + 2) * kstep;
;             const char* a3 = a2 + kstep; const char* b3 = b2 + kstep;
;             if (last && has_next) S.a_ready(nxt);
;             if constexpr (SP2) {
;             PG8_LDB(B0, 0, 0); PG8_LDB(B1, 0, 1); PG8_SCHED; PG8_LDA(At, 0, 0); PG8_STAGE(PG8_SA(1, 1), a1 + hstep, voffA);
;             PG8_WAIT_V(8); PG8_WAIT_L(0); PG8_BAR; PG8_MMA(0, 0, At, B0); PG8_MMA(0, 1, At, B1); PG8_BAR; PG8_SCHED;
.LBB0_163:
	s_add_u32 s41, s36, s40
	s_addc_u32 s46, s37, 0
	s_add_u32 s44, s41, 0x100
	s_addc_u32 s45, s46, 0
	s_and_b64 s[42:43], s[38:39], exec
	s_cselect_b32 s43, s27, s45
	s_cselect_b32 s42, s26, s44
	s_add_u32 s40, s34, s40
	s_addc_u32 s44, s35, 0
	s_add_u32 s40, s40, 0x100
	s_addc_u32 s44, s44, 0
	s_and_b64 s[38:39], s[38:39], exec
	s_cselect_b32 s45, s23, s44
	s_cselect_b32 s44, s25, s40
	s_add_u32 s48, s41, 0x10080
	ds_read_b128 v[148:151], v145
	ds_read_b128 v[152:155], v145 offset:1024
	ds_read_b128 v[156:159], v145 offset:2048
	ds_read_b128 v[160:163], v145 offset:3072
	ds_read_b128 v[164:167], v146
	ds_read_b128 v[168:171], v146 offset:1024
	ds_read_b128 v[172:175], v146 offset:2048
	ds_read_b128 v[176:179], v146 offset:3072
	s_addc_u32 s49, s46, 0
	s_add_i32 s78, s64, s58
	s_add_i32 m0, s31, 0xc000
	s_add_i32 s81, s31, 0xe000
	s_add_i32 s75, s78, 0x2000
	s_add_u32 s46, s44, 0x10000
	s_addc_u32 s47, s45, 0
	s_add_i32 s77, s65, s58
	s_add_i32 s76, s77, 0x2000
	s_add_i32 s74, 0, 0x18000
	s_add_i32 s73, 0, 0x1c000
	s_add_u32 s40, s42, 0x10000
	s_addc_u32 s41, s43, 0
	s_add_i32 s72, s74, s58
	s_add_i32 s71, s72, 0x2000
	s_add_u32 s38, s44, 0x10080
	s_addc_u32 s39, s45, 0
	s_add_i32 s80, s73, s58
	s_add_i32 s79, s80, 0x2000
	v_lshl_add_u64 v[140:141], s[48:49], 0, v[134:135]
	ds_read_b128 v[180:183], v147
	ds_read_b128 v[184:187], v147 offset:1024
	ds_read_b128 v[188:191], v147 offset:2048
	ds_read_b128 v[192:195], v147 offset:3072
	ds_read_b128 v[196:199], v147 offset:4096
	ds_read_b128 v[200:203], v147 offset:5120
	ds_read_b128 v[204:207], v147 offset:6144
	ds_read_b128 v[208:211], v147 offset:7168
	global_load_lds_dwordx4 v[140:141], off
	v_lshl_add_u64 v[140:141], s[48:49], 0, v[130:131]
	s_mov_b32 m0, s81
	s_nop 0
	global_load_lds_dwordx4 v[140:141], off
	s_waitcnt vmcnt(8)
	s_waitcnt lgkmcnt(0)
	s_barrier
	s_waitcnt lgkmcnt(0)
	v_mfma_f32_16x16x32_bf16 v[124:127], v[148:151], v[180:183], v[124:127]
	v_mfma_f32_16x16x32_bf16 v[120:123], v[156:159], v[180:183], v[120:123]
	v_mfma_f32_16x16x32_bf16 v[116:119], v[148:151], v[188:191], v[116:119]
	v_mfma_f32_16x16x32_bf16 v[108:111], v[156:159], v[188:191], v[108:111]
	v_mfma_f32_16x16x32_bf16 v[100:103], v[148:151], v[196:199], v[100:103]
	v_mfma_f32_16x16x32_bf16 v[92:95], v[156:159], v[196:199], v[92:95]
	v_mfma_f32_16x16x32_bf16 v[84:87], v[148:151], v[204:207], v[84:87]
	v_mfma_f32_16x16x32_bf16 v[76:79], v[156:159], v[204:207], v[76:79]
	v_mfma_f32_16x16x32_bf16 v[124:127], v[152:155], v[184:187], v[124:127]
	v_mfma_f32_16x16x32_bf16 v[120:123], v[160:163], v[184:187], v[120:123]
	v_mfma_f32_16x16x32_bf16 v[116:119], v[152:155], v[192:195], v[116:119]
	v_mfma_f32_16x16x32_bf16 v[108:111], v[160:163], v[192:195], v[108:111]
	v_mfma_f32_16x16x32_bf16 v[100:103], v[152:155], v[200:203], v[100:103]
	v_mfma_f32_16x16x32_bf16 v[92:95], v[160:163], v[200:203], v[92:95]
	v_mfma_f32_16x16x32_bf16 v[84:87], v[152:155], v[208:211], v[84:87]
	v_mfma_f32_16x16x32_bf16 v[76:79], v[160:163], v[208:211], v[76:79]
	v_mfma_f32_16x16x32_bf16 v[112:115], v[164:167], v[180:183], v[112:115]
	v_mfma_f32_16x16x32_bf16 v[104:107], v[172:175], v[180:183], v[104:107]
	v_mfma_f32_16x16x32_bf16 v[96:99], v[164:167], v[188:191], v[96:99]
	v_mfma_f32_16x16x32_bf16 v[88:91], v[172:175], v[188:191], v[88:91]
	v_mfma_f32_16x16x32_bf16 v[80:83], v[164:167], v[196:199], v[80:83]
	v_mfma_f32_16x16x32_bf16 v[72:75], v[172:175], v[196:199], v[72:75]
	v_mfma_f32_16x16x32_bf16 v[68:71], v[164:167], v[204:207], v[68:71]
	v_mfma_f32_16x16x32_bf16 v[64:67], v[172:175], v[204:207], v[64:67]
	v_mfma_f32_16x16x32_bf16 v[112:115], v[168:171], v[184:187], v[112:115]
	v_mfma_f32_16x16x32_bf16 v[104:107], v[176:179], v[184:187], v[104:107]
	v_mfma_f32_16x16x32_bf16 v[96:99], v[168:171], v[192:195], v[96:99]
	v_mfma_f32_16x16x32_bf16 v[88:91], v[176:179], v[192:195], v[88:91]
	v_mfma_f32_16x16x32_bf16 v[80:83], v[168:171], v[200:203], v[80:83]
	v_mfma_f32_16x16x32_bf16 v[72:75], v[176:179], v[200:203], v[72:75]
	v_mfma_f32_16x16x32_bf16 v[68:71], v[168:171], v[208:211], v[68:71]
	v_mfma_f32_16x16x32_bf16 v[64:67], v[176:179], v[208:211], v[64:67]
	s_barrier
	s_mov_b32 m0, s78
	v_lshl_add_u64 v[140:141], s[44:45], 0, v[132:133]
	ds_read_b128 v[180:183], v147 offset:16384
	ds_read_b128 v[184:187], v147 offset:17408
	ds_read_b128 v[188:191], v147 offset:18432
	ds_read_b128 v[192:195], v147 offset:19456
	ds_read_b128 v[196:199], v147 offset:20480
	ds_read_b128 v[200:203], v147 offset:21504
	ds_read_b128 v[204:207], v147 offset:22528
	ds_read_b128 v[208:211], v147 offset:23552
	global_load_lds_dwordx4 v[140:141], off
	v_lshl_add_u64 v[212:213], s[44:45], 0, v[128:129]
	s_mov_b32 m0, s75
	v_lshl_add_u64 v[214:215], s[46:47], 0, v[132:133]
	global_load_lds_dwordx4 v[212:213], off
	s_mov_b32 m0, s77
	v_lshl_add_u64 v[216:217], s[42:43], 0, v[130:131]
	global_load_lds_dwordx4 v[214:215], off
	v_lshl_add_u64 v[214:215], s[46:47], 0, v[128:129]
	s_mov_b32 m0, s76
	s_nop 0
	global_load_lds_dwordx4 v[214:215], off
	v_lshl_add_u64 v[214:215], s[42:43], 0, v[134:135]
	s_mov_b32 m0, s31
	s_nop 0
	global_load_lds_dwordx4 v[214:215], off
	s_mov_b32 m0, s33
	s_nop 0
	global_load_lds_dwordx4 v[216:217], off
	s_waitcnt vmcnt(8)
	s_waitcnt lgkmcnt(0)
	s_barrier
; #define PG8_STAGE(bufoff, gbase, voff) do { _Pragma("unroll") for (int _i = 0; _i < 2; ++_i) \
;         __builtin_amdgcn_global_load_lds((const unsigned*)((const char*)(gbase) + (voff)[_i]), (PG8_LAS unsigned*)(lds + (bufoff) + ldsw + _i * 8192), 16, 0, 0); } while (0)
; #define PG8_LDA(dst, b, h) do { _Pragma("unroll") for (int m = 0; m < 4; ++m) _Pragma("unroll") for (int k = 0; k < 2; ++k) dst[m][k] = *(const PG8_LAS bf16x8*)(lds + PG8_SA(b, h) + aoff + m * 2048 + k * 1024); } while (0)
; #define PG8_LDB(dst, b, h) do { _Pragma("unroll") for (int n = 0; n < 2; ++n) _Pragma("unroll") for (int k = 0; k < 2; ++k) dst[n][k] = *(const PG8_LAS bf16x8*)(lds + PG8_SB(b, h) + boff + n * 2048 + k * 1024); } while (0)
; #define PG8_MMA(ai, bj, At, Bt) do { __builtin_amdgcn_s_setprio(1); _Pragma("unroll") for (int m = 0; m < 4; ++m) _Pragma("unroll") for (int n = 0; n < 2; ++n) _Pragma("unroll") for (int k = 0; k < 2; ++k) \
;         acc[ai][bj][m][n] = __builtin_amdgcn_mfma_f32_16x16x32_bf16(Bt[n][k], At[m][k], acc[ai][bj][m][n], 0, 0, 0); __builtin_amdgcn_s_setprio(0); } while (0)
; #define PG8_WAIT_V(n) asm volatile("s_waitcnt vmcnt(" #n ")" ::: "memory")
; #define PG8_WAIT_L(n) asm volatile("s_waitcnt lgkmcnt(" #n ")" ::: "memory")
; #define PG8_BAR __builtin_amdgcn_s_barrier()
; #define PG8_SCHED __builtin_amdgcn_sched_barrier(0)
; template <class Epi, class Sched, bool ALIGN_EPI = false, bool SP2 = false>
; __device__ __forceinline__ void gemm_phase(PG8_LAS unsigned char* lds, const Gemm g, const Sched& S, const Epi& E, const int tid_in) {
;     ...
;             PG8_WAIT_V(8); PG8_WAIT_L(0); PG8_BAR; PG8_MMA(0, 0, At, B0); PG8_MMA(0, 1, At, B1); PG8_BAR; PG8_SCHED;
;             PG8_LDA(At, 0, 1); PG8_STAGE(PG8_SB(0, 0), b2, voffB); PG8_STAGE(PG8_SB(0, 1), b2 + hstep, voffB); PG8_STAGE(PG8_SA(0, 0), a2, voffA);
;             PG8_WAIT_V(8); PG8_WAIT_L(0); PG8_BAR; PG8_MMA(1, 0, At, B0); PG8_MMA(1, 1, At, B1); PG8_BAR; PG8_SCHED;
;             PG8_LDB(B0, 1, 0); PG8_LDB(B1, 1, 1); PG8_SCHED; PG8_LDA(At, 1, 0); PG8_STAGE(PG8_SA(0, 1), a2 + hstep, voffA);
;             PG8_WAIT_V(8); PG8_WAIT_L(0); PG8_BAR; PG8_MMA(0, 0, At, B0); PG8_MMA(0, 1, At, B1); PG8_BAR; PG8_SCHED;
	s_waitcnt lgkmcnt(0)
	v_mfma_f32_16x16x32_bf16 v[60:63], v[148:151], v[180:183], v[60:63]
	v_mfma_f32_16x16x32_bf16 v[56:59], v[156:159], v[180:183], v[56:59]
	v_mfma_f32_16x16x32_bf16 v[52:55], v[148:151], v[188:191], v[52:55]
	v_mfma_f32_16x16x32_bf16 v[44:47], v[156:159], v[188:191], v[44:47]
	v_mfma_f32_16x16x32_bf16 v[36:39], v[148:151], v[196:199], v[36:39]
	v_mfma_f32_16x16x32_bf16 v[28:31], v[156:159], v[196:199], v[28:31]
	v_mfma_f32_16x16x32_bf16 v[20:23], v[148:151], v[204:207], v[20:23]
	v_mfma_f32_16x16x32_bf16 v[12:15], v[156:159], v[204:207], v[12:15]
	v_mfma_f32_16x16x32_bf16 v[60:63], v[152:155], v[184:187], v[60:63]
	v_mfma_f32_16x16x32_bf16 v[56:59], v[160:163], v[184:187], v[56:59]
	v_mfma_f32_16x16x32_bf16 v[52:55], v[152:155], v[192:195], v[52:55]
	v_mfma_f32_16x16x32_bf16 v[44:47], v[160:163], v[192:195], v[44:47]
	v_mfma_f32_16x16x32_bf16 v[36:39], v[152:155], v[200:203], v[36:39]
	v_mfma_f32_16x16x32_bf16 v[28:31], v[160:163], v[200:203], v[28:31]
	v_mfma_f32_16x16x32_bf16 v[20:23], v[152:155], v[208:211], v[20:23]
	v_mfma_f32_16x16x32_bf16 v[12:15], v[160:163], v[208:211], v[12:15]
	v_mfma_f32_16x16x32_bf16 v[48:51], v[164:167], v[180:183], v[48:51]
	v_mfma_f32_16x16x32_bf16 v[40:43], v[172:175], v[180:183], v[40:43]
	v_mfma_f32_16x16x32_bf16 v[32:35], v[164:167], v[188:191], v[32:35]
	v_mfma_f32_16x16x32_bf16 v[24:27], v[172:175], v[188:191], v[24:27]
	v_mfma_f32_16x16x32_bf16 v[16:19], v[164:167], v[196:199], v[16:19]
	v_mfma_f32_16x16x32_bf16 v[8:11], v[172:175], v[196:199], v[8:11]
	v_mfma_f32_16x16x32_bf16 v[4:7], v[164:167], v[204:207], v[4:7]
	v_mfma_f32_16x16x32_bf16 v[0:3], v[172:175], v[204:207], v[0:3]
	v_mfma_f32_16x16x32_bf16 v[48:51], v[168:171], v[184:187], v[48:51]
	v_mfma_f32_16x16x32_bf16 v[40:43], v[176:179], v[184:187], v[40:43]
	v_mfma_f32_16x16x32_bf16 v[32:35], v[168:171], v[192:195], v[32:35]
	v_mfma_f32_16x16x32_bf16 v[24:27], v[176:179], v[192:195], v[24:27]
	v_mfma_f32_16x16x32_bf16 v[16:19], v[168:171], v[200:203], v[16:19]
	v_mfma_f32_16x16x32_bf16 v[8:11], v[176:179], v[200:203], v[8:11]
	v_mfma_f32_16x16x32_bf16 v[4:7], v[168:171], v[208:211], v[4:7]
	v_mfma_f32_16x16x32_bf16 v[0:3], v[176:179], v[208:211], v[0:3]
	s_barrier
	v_add_u32_e32 v160, s74, v143
	v_add_u32_e32 v176, s73, v143
	ds_read_b128 v[148:151], v160
	ds_read_b128 v[152:155], v160 offset:1024
	ds_read_b128 v[156:159], v160 offset:2048
	ds_read_b128 v[160:163], v160 offset:3072
	ds_read_b128 v[164:167], v176
	ds_read_b128 v[168:171], v176 offset:1024
	ds_read_b128 v[172:175], v176 offset:2048
	ds_read_b128 v[176:179], v176 offset:3072
	s_mov_b32 m0, s59
	v_lshl_add_u64 v[218:219], s[40:41], 0, v[134:135]
	ds_read_b128 v[180:183], v147 offset:32768
	ds_read_b128 v[184:187], v147 offset:33792
	ds_read_b128 v[188:191], v147 offset:34816
	ds_read_b128 v[192:195], v147 offset:35840
	ds_read_b128 v[196:199], v147 offset:36864
	ds_read_b128 v[200:203], v147 offset:37888
	ds_read_b128 v[204:207], v147 offset:38912
	ds_read_b128 v[208:211], v147 offset:39936
	global_load_lds_dwordx4 v[218:219], off
	v_lshl_add_u64 v[218:219], s[40:41], 0, v[130:131]
	s_mov_b32 m0, s60
	s_nop 0
	global_load_lds_dwordx4 v[218:219], off
	s_waitcnt vmcnt(8)
	s_waitcnt lgkmcnt(0)
	s_barrier
	s_waitcnt lgkmcnt(0)
	v_mfma_f32_16x16x32_bf16 v[124:127], v[148:151], v[180:183], v[124:127]
	v_mfma_f32_16x16x32_bf16 v[120:123], v[156:159], v[180:183], v[120:123]
	v_mfma_f32_16x16x32_bf16 v[116:119], v[148:151], v[188:191], v[116:119]
	v_mfma_f32_16x16x32_bf16 v[108:111], v[156:159], v[188:191], v[108:111]
	v_mfma_f32_16x16x32_bf16 v[100:103], v[148:151], v[196:199], v[100:103]
	v_mfma_f32_16x16x32_bf16 v[92:95], v[156:159], v[196:199], v[92:95]
	v_mfma_f32_16x16x32_bf16 v[84:87], v[148:151], v[204:207], v[84:87]
	v_mfma_f32_16x16x32_bf16 v[76:79], v[156:159], v[204:207], v[76:79]
	v_mfma_f32_16x16x32_bf16 v[124:127], v[152:155], v[184:187], v[124:127]
	v_mfma_f32_16x16x32_bf16 v[120:123], v[160:163], v[184:187], v[120:123]
	v_mfma_f32_16x16x32_bf16 v[116:119], v[152:155], v[192:195], v[116:119]
	v_mfma_f32_16x16x32_bf16 v[108:111], v[160:163], v[192:195], v[108:111]
	v_mfma_f32_16x16x32_bf16 v[100:103], v[152:155], v[200:203], v[100:103]
	v_mfma_f32_16x16x32_bf16 v[92:95], v[160:163], v[200:203], v[92:95]
	v_mfma_f32_16x16x32_bf16 v[84:87], v[152:155], v[208:211], v[84:87]
	v_mfma_f32_16x16x32_bf16 v[76:79], v[160:163], v[208:211], v[76:79]
	v_mfma_f32_16x16x32_bf16 v[112:115], v[164:167], v[180:183], v[112:115]
	v_mfma_f32_16x16x32_bf16 v[104:107], v[172:175], v[180:183], v[104:107]
	v_mfma_f32_16x16x32_bf16 v[96:99], v[164:167], v[188:191], v[96:99]
	v_mfma_f32_16x16x32_bf16 v[88:91], v[172:175], v[188:191], v[88:91]
	v_mfma_f32_16x16x32_bf16 v[80:83], v[164:167], v[196:199], v[80:83]
	v_mfma_f32_16x16x32_bf16 v[72:75], v[172:175], v[196:199], v[72:75]
	v_mfma_f32_16x16x32_bf16 v[68:71], v[164:167], v[204:207], v[68:71]
	v_mfma_f32_16x16x32_bf16 v[64:67], v[172:175], v[204:207], v[64:67]
	v_mfma_f32_16x16x32_bf16 v[112:115], v[168:171], v[184:187], v[112:115]
	v_mfma_f32_16x16x32_bf16 v[104:107], v[176:179], v[184:187], v[104:107]
	v_mfma_f32_16x16x32_bf16 v[96:99], v[168:171], v[192:195], v[96:99]
	v_mfma_f32_16x16x32_bf16 v[88:91], v[176:179], v[192:195], v[88:91]
	v_mfma_f32_16x16x32_bf16 v[80:83], v[168:171], v[200:203], v[80:83]
	v_mfma_f32_16x16x32_bf16 v[72:75], v[176:179], v[200:203], v[72:75]
	v_mfma_f32_16x16x32_bf16 v[68:71], v[168:171], v[208:211], v[68:71]
	v_mfma_f32_16x16x32_bf16 v[64:67], v[176:179], v[208:211], v[64:67]
	s_barrier
; #define PG8_STAGE(bufoff, gbase, voff) do { _Pragma("unroll") for (int _i = 0; _i < 2; ++_i) \
;         __builtin_amdgcn_global_load_lds((const unsigned*)((const char*)(gbase) + (voff)[_i]), (PG8_LAS unsigned*)(lds + (bufoff) + ldsw + _i * 8192), 16, 0, 0); } while (0)
; #define PG8_LDA(dst, b, h) do { _Pragma("unroll") for (int m = 0; m < 4; ++m) _Pragma("unroll") for (int k = 0; k < 2; ++k) dst[m][k] = *(const PG8_LAS bf16x8*)(lds + PG8_SA(b, h) + aoff + m * 2048 + k * 1024); } while (0)
; #define PG8_MMA(ai, bj, At, Bt) do { __builtin_amdgcn_s_setprio(1); _Pragma("unroll") for (int m = 0; m < 4; ++m) _Pragma("unroll") for (int n = 0; n < 2; ++n) _Pragma("unroll") for (int k = 0; k < 2; ++k) \
;         acc[ai][bj][m][n] = __builtin_amdgcn_mfma_f32_16x16x32_bf16(Bt[n][k], At[m][k], acc[ai][bj][m][n], 0, 0, 0); __builtin_amdgcn_s_setprio(0); } while (0)
; #define PG8_WAIT_V(n) asm volatile("s_waitcnt vmcnt(" #n ")" ::: "memory")
; #define PG8_WAIT_L(n) asm volatile("s_waitcnt lgkmcnt(" #n ")" ::: "memory")
; #define PG8_BAR __builtin_amdgcn_s_barrier()
; #define PG8_SCHED __builtin_amdgcn_sched_barrier(0)
; template <class Epi, class Sched, bool ALIGN_EPI = false, bool SP2 = false>
; __device__ __forceinline__ void gemm_phase(PG8_LAS unsigned char* lds, const Gemm g, const Sched& S, const Epi& E, const int tid_in) {
;     ...
;             PG8_WAIT_V(8); PG8_WAIT_L(0); PG8_BAR; PG8_MMA(0, 0, At, B0); PG8_MMA(0, 1, At, B1); PG8_BAR; PG8_SCHED;
;             PG8_LDA(At, 1, 1); PG8_STAGE(PG8_SB(1, 0), b3, voffB); PG8_STAGE(PG8_SB(1, 1), b3 + hstep, voffB); PG8_STAGE(PG8_SA(1, 0), a3, voffA);
;             PG8_WAIT_V(8); PG8_WAIT_L(0); PG8_BAR; PG8_MMA(1, 0, At, B0); PG8_MMA(1, 1, At, B1); PG8_BAR; PG8_SCHED;
	s_mov_b32 m0, s72
	v_lshl_add_u64 v[140:141], v[140:141], 0, s[10:11]
	ds_read_b128 v[180:183], v147 offset:49152
	ds_read_b128 v[184:187], v147 offset:50176
	ds_read_b128 v[188:191], v147 offset:51200
	ds_read_b128 v[192:195], v147 offset:52224
	ds_read_b128 v[196:199], v147 offset:53248
	ds_read_b128 v[200:203], v147 offset:54272
	ds_read_b128 v[204:207], v147 offset:55296
	ds_read_b128 v[208:211], v147 offset:56320
	global_load_lds_dwordx4 v[140:141], off
	v_lshl_add_u64 v[140:141], v[212:213], 0, s[10:11]
	s_mov_b32 m0, s71
	s_nop 0
	global_load_lds_dwordx4 v[140:141], off
	v_lshl_add_u64 v[140:141], s[38:39], 0, v[132:133]
	s_mov_b32 m0, s80
	s_nop 0
	global_load_lds_dwordx4 v[140:141], off
	v_lshl_add_u64 v[140:141], s[38:39], 0, v[128:129]
	s_mov_b32 m0, s79
	s_nop 0
	global_load_lds_dwordx4 v[140:141], off
	v_lshl_add_u64 v[140:141], v[214:215], 0, s[10:11]
	s_mov_b32 m0, s62
	s_nop 0
	global_load_lds_dwordx4 v[140:141], off
	v_lshl_add_u64 v[140:141], v[216:217], 0, s[10:11]
	s_mov_b32 m0, s63
	s_nop 0
	global_load_lds_dwordx4 v[140:141], off
	s_waitcnt vmcnt(8)
	s_waitcnt lgkmcnt(0)
	s_barrier
	s_waitcnt lgkmcnt(0)
	v_mfma_f32_16x16x32_bf16 v[60:63], v[148:151], v[180:183], v[60:63]
	v_mfma_f32_16x16x32_bf16 v[56:59], v[156:159], v[180:183], v[56:59]
	v_mfma_f32_16x16x32_bf16 v[52:55], v[148:151], v[188:191], v[52:55]
	v_mfma_f32_16x16x32_bf16 v[44:47], v[156:159], v[188:191], v[44:47]
	v_mfma_f32_16x16x32_bf16 v[36:39], v[148:151], v[196:199], v[36:39]
	v_mfma_f32_16x16x32_bf16 v[28:31], v[156:159], v[196:199], v[28:31]
	v_mfma_f32_16x16x32_bf16 v[20:23], v[148:151], v[204:207], v[20:23]
	v_mfma_f32_16x16x32_bf16 v[12:15], v[156:159], v[204:207], v[12:15]
	v_mfma_f32_16x16x32_bf16 v[60:63], v[152:155], v[184:187], v[60:63]
	v_mfma_f32_16x16x32_bf16 v[56:59], v[160:163], v[184:187], v[56:59]
	v_mfma_f32_16x16x32_bf16 v[52:55], v[152:155], v[192:195], v[52:55]
	v_mfma_f32_16x16x32_bf16 v[44:47], v[160:163], v[192:195], v[44:47]
	v_mfma_f32_16x16x32_bf16 v[36:39], v[152:155], v[200:203], v[36:39]
	v_mfma_f32_16x16x32_bf16 v[28:31], v[160:163], v[200:203], v[28:31]
	v_mfma_f32_16x16x32_bf16 v[20:23], v[152:155], v[208:211], v[20:23]
	v_mfma_f32_16x16x32_bf16 v[12:15], v[160:163], v[208:211], v[12:15]
	v_mfma_f32_16x16x32_bf16 v[48:51], v[164:167], v[180:183], v[48:51]
	v_mfma_f32_16x16x32_bf16 v[40:43], v[172:175], v[180:183], v[40:43]
	v_mfma_f32_16x16x32_bf16 v[32:35], v[164:167], v[188:191], v[32:35]
	v_mfma_f32_16x16x32_bf16 v[24:27], v[172:175], v[188:191], v[24:27]
	v_mfma_f32_16x16x32_bf16 v[16:19], v[164:167], v[196:199], v[16:19]
	v_mfma_f32_16x16x32_bf16 v[8:11], v[172:175], v[196:199], v[8:11]
	v_mfma_f32_16x16x32_bf16 v[4:7], v[164:167], v[204:207], v[4:7]
	v_mfma_f32_16x16x32_bf16 v[0:3], v[172:175], v[204:207], v[0:3]
	v_mfma_f32_16x16x32_bf16 v[48:51], v[168:171], v[184:187], v[48:51]
	v_mfma_f32_16x16x32_bf16 v[40:43], v[176:179], v[184:187], v[40:43]
	v_mfma_f32_16x16x32_bf16 v[32:35], v[168:171], v[192:195], v[32:35]
	v_mfma_f32_16x16x32_bf16 v[24:27], v[176:179], v[192:195], v[24:27]
	v_mfma_f32_16x16x32_bf16 v[16:19], v[168:171], v[200:203], v[16:19]
	v_mfma_f32_16x16x32_bf16 v[8:11], v[176:179], v[200:203], v[8:11]
	v_mfma_f32_16x16x32_bf16 v[4:7], v[168:171], v[208:211], v[4:7]
	v_mfma_f32_16x16x32_bf16 v[0:3], v[176:179], v[208:211], v[0:3]
	s_barrier
	s_movk_i32 s40, 0x100
	s_andn2_b64 vcc, exec, s[0:1]
	s_mov_b64 s[38:39], -1
	s_mov_b64 s[0:1], 0
	s_cbranch_vccz .LBB0_163
	s_and_b64 vcc, exec, s[12:13]
	s_cbranch_vccz .LBB0_166
	s_barrier

; __device__ __forceinline__ void unpack8(const u32x4 w, f32x4& a, f32x4& b) { a = (f32x4){bflo(w.x), bfhi(w.x), bflo(w.y), bfhi(w.y)}; b = (f32x4){bflo(w.z), bfhi(w.z), bflo(w.w), bfhi(w.w)}; }
; #define PG8_STAGE(bufoff, gbase, voff) do { _Pragma("unroll") for (int _i = 0; _i < 2; ++_i) \
;         __builtin_amdgcn_global_load_lds((const unsigned*)((const char*)(gbase) + (voff)[_i]), (PG8_LAS unsigned*)(lds + (bufoff) + ldsw + _i * 8192), 16, 0, 0); } while (0)
; #define PG8_LDA(dst, b, h) do { _Pragma("unroll") for (int m = 0; m < 4; ++m) _Pragma("unroll") for (int k = 0; k < 2; ++k) dst[m][k] = *(const PG8_LAS bf16x8*)(lds + PG8_SA(b, h) + aoff + m * 2048 + k * 1024); } while (0)
; #define PG8_LDB(dst, b, h) do { _Pragma("unroll") for (int n = 0; n < 2; ++n) _Pragma("unroll") for (int k = 0; k < 2; ++k) dst[n][k] = *(const PG8_LAS bf16x8*)(lds + PG8_SB(b, h) + boff + n * 2048 + k * 1024); } while (0)
; #define PG8_WAIT_V(n) asm volatile("s_waitcnt vmcnt(" #n ")" ::: "memory")
; #define PG8_WAIT_L(n) asm volatile("s_waitcnt lgkmcnt(" #n ")" ::: "memory")
;     __device__ __forceinline__ void operator()(const f32x4 (&acc)[2][2][4][2], const Unit& u, int wr, int wc, int fr, int fq) const {
;     ...
;             for (int m = 0; m < 4; ++m) { const size_t off = (size_t)(row0 + ai * HALF + m * 16) * 1024 + col0;
; #pragma unroll
;                 for (int bj = 0; bj < 2; ++bj) { f32x4 b0, b1;
;                     if (BF) { unpack8(*(const u32x4*)((const bf16_t*)base + off + bj * HALF), b0, b1); }
;                     else { b0 = *(const f32x4*)((const float*)base + off + bj * HALF); b1 = *(const f32x4*)((const float*)base + off + bj * HALF + 4); }
; template <class Epi, class Sched, bool ALIGN_EPI = false, bool SP2 = false>
; __device__ __forceinline__ void gemm_phase(PG8_LAS unsigned char* lds, const Gemm g, const Sched& S, const Epi& E, const int tid_in) {
;     ...
;             PG8_LDB(B0, 0, 0); PG8_LDB(B1, 0, 1); PG8_SCHED; PG8_LDA(At, 0, 0); PG8_STAGE(PG8_SA(1, 1), a1 + hstep, voffA);
;             PG8_WAIT_V(8); PG8_WAIT_L(0); PG8_BAR; PG8_MMA(0, 0, At, B0); PG8_MMA(0, 1, At, B1); PG8_BAR; PG8_SCHED;
;             PG8_LDA(At, 0, 1); PG8_STAGE(PG8_SB(0, 0), b2, voffB); PG8_STAGE(PG8_SB(0, 1), b2 + hstep, voffB); PG8_STAGE(PG8_SA(0, 0), a2, voffA);
;             PG8_WAIT_V(8); PG8_WAIT_L(0); PG8_BAR; PG8_MMA(1, 0, At, B0); PG8_MMA(1, 1, At, B1); PG8_BAR; PG8_SCHED;
.Lmy_ra_done:
	s_barrier
	s_waitcnt lgkmcnt(0)
	v_mfma_f32_16x16x32_bf16 v[124:127], v[144:147], v[184:187], v[124:127]
	v_mfma_f32_16x16x32_bf16 v[120:123], v[160:163], v[184:187], v[120:123]
	v_mfma_f32_16x16x32_bf16 v[108:111], v[144:147], v[192:195], v[108:111]
	v_mfma_f32_16x16x32_bf16 v[104:107], v[160:163], v[192:195], v[104:107]
	v_mfma_f32_16x16x32_bf16 v[92:95], v[144:147], v[200:203], v[92:95]
	v_mfma_f32_16x16x32_bf16 v[88:91], v[160:163], v[200:203], v[88:91]
	v_mfma_f32_16x16x32_bf16 v[76:79], v[144:147], v[208:211], v[76:79]
	v_mfma_f32_16x16x32_bf16 v[72:75], v[160:163], v[208:211], v[72:75]
	v_mfma_f32_16x16x32_bf16 v[124:127], v[156:159], v[188:191], v[124:127]
	v_mfma_f32_16x16x32_bf16 v[120:123], v[164:167], v[188:191], v[120:123]
	v_mfma_f32_16x16x32_bf16 v[108:111], v[156:159], v[196:199], v[108:111]
	v_mfma_f32_16x16x32_bf16 v[104:107], v[164:167], v[196:199], v[104:107]
	v_mfma_f32_16x16x32_bf16 v[92:95], v[156:159], v[204:207], v[92:95]
	v_mfma_f32_16x16x32_bf16 v[88:91], v[164:167], v[204:207], v[88:91]
	v_mfma_f32_16x16x32_bf16 v[76:79], v[156:159], v[212:215], v[76:79]
	v_mfma_f32_16x16x32_bf16 v[72:75], v[164:167], v[212:215], v[72:75]
	v_mfma_f32_16x16x32_bf16 v[116:119], v[168:171], v[184:187], v[116:119]
	v_mfma_f32_16x16x32_bf16 v[112:115], v[176:179], v[184:187], v[112:115]
	v_mfma_f32_16x16x32_bf16 v[100:103], v[168:171], v[192:195], v[100:103]
	v_mfma_f32_16x16x32_bf16 v[96:99], v[176:179], v[192:195], v[96:99]
	v_mfma_f32_16x16x32_bf16 v[84:87], v[168:171], v[200:203], v[84:87]
	v_mfma_f32_16x16x32_bf16 v[80:83], v[176:179], v[200:203], v[80:83]
	v_mfma_f32_16x16x32_bf16 v[68:71], v[168:171], v[208:211], v[68:71]
	v_mfma_f32_16x16x32_bf16 v[64:67], v[176:179], v[208:211], v[64:67]
	v_mfma_f32_16x16x32_bf16 v[116:119], v[172:175], v[188:191], v[116:119]
	v_mfma_f32_16x16x32_bf16 v[112:115], v[180:183], v[188:191], v[112:115]
	v_mfma_f32_16x16x32_bf16 v[100:103], v[172:175], v[196:199], v[100:103]
	v_mfma_f32_16x16x32_bf16 v[96:99], v[180:183], v[196:199], v[96:99]
	v_mfma_f32_16x16x32_bf16 v[84:87], v[172:175], v[204:207], v[84:87]
	v_mfma_f32_16x16x32_bf16 v[80:83], v[180:183], v[204:207], v[80:83]
	v_mfma_f32_16x16x32_bf16 v[68:71], v[172:175], v[212:215], v[68:71]
	v_mfma_f32_16x16x32_bf16 v[64:67], v[180:183], v[212:215], v[64:67]
	s_barrier
	s_add_i32 s63, s53, s43
	v_lshl_add_u64 v[148:149], s[36:37], 0, v[132:133]
	s_mov_b32 m0, s63
	ds_read_b128 v[184:187], v155 offset:16384
	ds_read_b128 v[188:191], v155 offset:17408
	ds_read_b128 v[192:195], v155 offset:18432
	ds_read_b128 v[196:199], v155 offset:19456
	ds_read_b128 v[200:203], v155 offset:20480
	ds_read_b128 v[204:207], v155 offset:21504
	ds_read_b128 v[208:211], v155 offset:22528
	ds_read_b128 v[212:215], v155 offset:23552
	global_load_lds_dwordx4 v[148:149], off
	s_add_i32 m0, s63, 0x2000
	s_add_u32 s64, s36, 0x40000
	v_lshl_add_u64 v[216:217], s[36:37], 0, v[128:129]
	s_addc_u32 s65, s37, 0
	s_add_i32 s63, s56, s43
	global_load_lds_dwordx4 v[216:217], off
	v_lshl_add_u64 v[218:219], s[64:65], 0, v[132:133]
	s_mov_b32 m0, s63
	v_lshl_add_u64 v[220:221], s[38:39], 0, v[130:131]
	global_load_lds_dwordx4 v[218:219], off
	v_lshl_add_u64 v[218:219], s[64:65], 0, v[128:129]
	s_add_i32 m0, s63, 0x2000
	s_nop 0
	global_load_lds_dwordx4 v[218:219], off
	v_lshl_add_u64 v[218:219], s[38:39], 0, v[134:135]
	s_mov_b32 m0, s35
	s_nop 0
	global_load_lds_dwordx4 v[218:219], off
	s_mov_b32 m0, s45
	s_nop 0
	global_load_lds_dwordx4 v[220:221], off
	s_waitcnt vmcnt(8)
	s_waitcnt lgkmcnt(0)
	global_load_dwordx4 v[228:231], v[224:225], off
	global_load_dwordx4 v[232:235], v[224:225], off offset:16
	global_load_dwordx4 v[236:239], v[224:225], off offset:512
	global_load_dwordx4 v[240:243], v[224:225], off offset:528
	s_mov_b32 s98, 0x10000
	s_cmp_eq_u32 s62, 4
	s_cselect_b32 s98, 0x50000, s98
	v_add_co_u32_e32 v224, vcc, s98, v224
	s_nop 1
	v_addc_co_u32_e32 v225, vcc, 0, v225, vcc
	s_barrier
	s_waitcnt lgkmcnt(0)
	v_mfma_f32_16x16x32_bf16 v[60:63], v[144:147], v[184:187], v[60:63]
	v_mfma_f32_16x16x32_bf16 v[56:59], v[160:163], v[184:187], v[56:59]
	v_mfma_f32_16x16x32_bf16 v[44:47], v[144:147], v[192:195], v[44:47]
	v_mfma_f32_16x16x32_bf16 v[40:43], v[160:163], v[192:195], v[40:43]
	v_mfma_f32_16x16x32_bf16 v[28:31], v[144:147], v[200:203], v[28:31]
	v_mfma_f32_16x16x32_bf16 v[24:27], v[160:163], v[200:203], v[24:27]
	v_mfma_f32_16x16x32_bf16 v[12:15], v[144:147], v[208:211], v[12:15]
	v_mfma_f32_16x16x32_bf16 v[8:11], v[160:163], v[208:211], v[8:11]
	v_mfma_f32_16x16x32_bf16 v[60:63], v[156:159], v[188:191], v[60:63]
	v_mfma_f32_16x16x32_bf16 v[56:59], v[164:167], v[188:191], v[56:59]
	v_mfma_f32_16x16x32_bf16 v[44:47], v[156:159], v[196:199], v[44:47]
	v_mfma_f32_16x16x32_bf16 v[40:43], v[164:167], v[196:199], v[40:43]
	v_mfma_f32_16x16x32_bf16 v[28:31], v[156:159], v[204:207], v[28:31]
	v_mfma_f32_16x16x32_bf16 v[24:27], v[164:167], v[204:207], v[24:27]
	v_mfma_f32_16x16x32_bf16 v[12:15], v[156:159], v[212:215], v[12:15]
	v_mfma_f32_16x16x32_bf16 v[8:11], v[164:167], v[212:215], v[8:11]
	v_mfma_f32_16x16x32_bf16 v[52:55], v[168:171], v[184:187], v[52:55]
	v_mfma_f32_16x16x32_bf16 v[48:51], v[176:179], v[184:187], v[48:51]
	v_mfma_f32_16x16x32_bf16 v[36:39], v[168:171], v[192:195], v[36:39]
	v_mfma_f32_16x16x32_bf16 v[32:35], v[176:179], v[192:195], v[32:35]
	v_mfma_f32_16x16x32_bf16 v[20:23], v[168:171], v[200:203], v[20:23]
	v_mfma_f32_16x16x32_bf16 v[16:19], v[176:179], v[200:203], v[16:19]
	v_mfma_f32_16x16x32_bf16 v[4:7], v[168:171], v[208:211], v[4:7]
	v_mfma_f32_16x16x32_bf16 v[0:3], v[176:179], v[208:211], v[0:3]
	v_mfma_f32_16x16x32_bf16 v[52:55], v[172:175], v[188:191], v[52:55]
	v_mfma_f32_16x16x32_bf16 v[48:51], v[180:183], v[188:191], v[48:51]
	v_mfma_f32_16x16x32_bf16 v[36:39], v[172:175], v[196:199], v[36:39]
	v_mfma_f32_16x16x32_bf16 v[32:35], v[180:183], v[196:199], v[32:35]
	v_mfma_f32_16x16x32_bf16 v[20:23], v[172:175], v[204:207], v[20:23]
	v_mfma_f32_16x16x32_bf16 v[16:19], v[180:183], v[204:207], v[16:19]
	v_mfma_f32_16x16x32_bf16 v[4:7], v[172:175], v[212:215], v[4:7]
	v_mfma_f32_16x16x32_bf16 v[0:3], v[180:183], v[212:215], v[0:3]
	s_barrier
; #define PG8_STAGE(bufoff, gbase, voff) do { _Pragma("unroll") for (int _i = 0; _i < 2; ++_i) \
;         __builtin_amdgcn_global_load_lds((const unsigned*)((const char*)(gbase) + (voff)[_i]), (PG8_LAS unsigned*)(lds + (bufoff) + ldsw + _i * 8192), 16, 0, 0); } while (0)
; #define PG8_LDA(dst, b, h) do { _Pragma("unroll") for (int m = 0; m < 4; ++m) _Pragma("unroll") for (int k = 0; k < 2; ++k) dst[m][k] = *(const PG8_LAS bf16x8*)(lds + PG8_SA(b, h) + aoff + m * 2048 + k * 1024); } while (0)
; #define PG8_LDB(dst, b, h) do { _Pragma("unroll") for (int n = 0; n < 2; ++n) _Pragma("unroll") for (int k = 0; k < 2; ++k) dst[n][k] = *(const PG8_LAS bf16x8*)(lds + PG8_SB(b, h) + boff + n * 2048 + k * 1024); } while (0)
; #define PG8_MMA(ai, bj, At, Bt) do { __builtin_amdgcn_s_setprio(1); _Pragma("unroll") for (int m = 0; m < 4; ++m) _Pragma("unroll") for (int n = 0; n < 2; ++n) _Pragma("unroll") for (int k = 0; k < 2; ++k) \
;         acc[ai][bj][m][n] = __builtin_amdgcn_mfma_f32_16x16x32_bf16(Bt[n][k], At[m][k], acc[ai][bj][m][n], 0, 0, 0); __builtin_amdgcn_s_setprio(0); } while (0)
; #define PG8_WAIT_V(n) asm volatile("s_waitcnt vmcnt(" #n ")" ::: "memory")
; #define PG8_WAIT_L(n) asm volatile("s_waitcnt lgkmcnt(" #n ")" ::: "memory")
; #define PG8_BAR __builtin_amdgcn_s_barrier()
; #define PG8_SCHED __builtin_amdgcn_sched_barrier(0)
; template <class Epi, class Sched, bool ALIGN_EPI = false, bool SP2 = false>
; __device__ __forceinline__ void gemm_phase(PG8_LAS unsigned char* lds, const Gemm g, const Sched& S, const Epi& E, const int tid_in) {
;     ...
;             PG8_WAIT_V(8); PG8_WAIT_L(0); PG8_BAR; PG8_MMA(1, 0, At, B0); PG8_MMA(1, 1, At, B1); PG8_BAR; PG8_SCHED;
;             PG8_LDB(B0, 1, 0); PG8_LDB(B1, 1, 1); PG8_SCHED; PG8_LDA(At, 1, 0); PG8_STAGE(PG8_SA(0, 1), a2 + hstep, voffA);
;             PG8_WAIT_V(8); PG8_WAIT_L(0); PG8_BAR; PG8_MMA(0, 0, At, B0); PG8_MMA(0, 1, At, B1); PG8_BAR; PG8_SCHED;
	s_add_i32 s63, 0, 0x18000
	s_add_i32 s64, 0, 0x1c000
	v_add_u32_e32 v164, s63, v151
	v_add_u32_e32 v180, s64, v151
	ds_read_b128 v[144:147], v164
	ds_read_b128 v[156:159], v164 offset:1024
	ds_read_b128 v[160:163], v164 offset:2048
	ds_read_b128 v[164:167], v164 offset:3072
	ds_read_b128 v[168:171], v180
	ds_read_b128 v[172:175], v180 offset:1024
	ds_read_b128 v[176:179], v180 offset:2048
	ds_read_b128 v[180:183], v180 offset:3072
	s_add_u32 s38, s38, 0x40000
	s_addc_u32 s39, s39, 0
	s_mov_b32 m0, s46
	v_lshl_add_u64 v[222:223], s[38:39], 0, v[134:135]
	ds_read_b128 v[184:187], v155 offset:32768
	ds_read_b128 v[188:191], v155 offset:33792
	ds_read_b128 v[192:195], v155 offset:34816
	ds_read_b128 v[196:199], v155 offset:35840
	ds_read_b128 v[200:203], v155 offset:36864
	ds_read_b128 v[204:207], v155 offset:37888
	ds_read_b128 v[208:211], v155 offset:38912
	ds_read_b128 v[212:215], v155 offset:39936
	global_load_lds_dwordx4 v[222:223], off
	v_lshl_add_u64 v[222:223], s[38:39], 0, v[130:131]
	s_mov_b32 m0, s47
	s_nop 0
	global_load_lds_dwordx4 v[222:223], off
	s_waitcnt vmcnt(12)
	s_waitcnt lgkmcnt(0)
	s_barrier
	s_waitcnt lgkmcnt(0)
	v_mfma_f32_16x16x32_bf16 v[124:127], v[144:147], v[184:187], v[124:127]
	v_mfma_f32_16x16x32_bf16 v[120:123], v[160:163], v[184:187], v[120:123]
	v_mfma_f32_16x16x32_bf16 v[108:111], v[144:147], v[192:195], v[108:111]
	v_mfma_f32_16x16x32_bf16 v[104:107], v[160:163], v[192:195], v[104:107]
	v_mfma_f32_16x16x32_bf16 v[92:95], v[144:147], v[200:203], v[92:95]
	v_mfma_f32_16x16x32_bf16 v[88:91], v[160:163], v[200:203], v[88:91]
	v_mfma_f32_16x16x32_bf16 v[76:79], v[144:147], v[208:211], v[76:79]
	v_mfma_f32_16x16x32_bf16 v[72:75], v[160:163], v[208:211], v[72:75]
	v_mfma_f32_16x16x32_bf16 v[124:127], v[156:159], v[188:191], v[124:127]
	v_mfma_f32_16x16x32_bf16 v[120:123], v[164:167], v[188:191], v[120:123]
	v_mfma_f32_16x16x32_bf16 v[108:111], v[156:159], v[196:199], v[108:111]
	v_mfma_f32_16x16x32_bf16 v[104:107], v[164:167], v[196:199], v[104:107]
	v_mfma_f32_16x16x32_bf16 v[92:95], v[156:159], v[204:207], v[92:95]
	v_mfma_f32_16x16x32_bf16 v[88:91], v[164:167], v[204:207], v[88:91]
	v_mfma_f32_16x16x32_bf16 v[76:79], v[156:159], v[212:215], v[76:79]
	v_mfma_f32_16x16x32_bf16 v[72:75], v[164:167], v[212:215], v[72:75]
	v_mfma_f32_16x16x32_bf16 v[116:119], v[168:171], v[184:187], v[116:119]
	v_mfma_f32_16x16x32_bf16 v[112:115], v[176:179], v[184:187], v[112:115]
	v_mfma_f32_16x16x32_bf16 v[100:103], v[168:171], v[192:195], v[100:103]
	v_mfma_f32_16x16x32_bf16 v[96:99], v[176:179], v[192:195], v[96:99]
	v_mfma_f32_16x16x32_bf16 v[84:87], v[168:171], v[200:203], v[84:87]
	v_mfma_f32_16x16x32_bf16 v[80:83], v[176:179], v[200:203], v[80:83]
	v_mfma_f32_16x16x32_bf16 v[68:71], v[168:171], v[208:211], v[68:71]
	v_mfma_f32_16x16x32_bf16 v[64:67], v[176:179], v[208:211], v[64:67]
	v_mfma_f32_16x16x32_bf16 v[116:119], v[172:175], v[188:191], v[116:119]
	v_mfma_f32_16x16x32_bf16 v[112:115], v[180:183], v[188:191], v[112:115]
	v_mfma_f32_16x16x32_bf16 v[100:103], v[172:175], v[196:199], v[100:103]
	v_mfma_f32_16x16x32_bf16 v[96:99], v[180:183], v[196:199], v[96:99]
	v_mfma_f32_16x16x32_bf16 v[84:87], v[172:175], v[204:207], v[84:87]
	v_mfma_f32_16x16x32_bf16 v[80:83], v[180:183], v[204:207], v[80:83]
	v_mfma_f32_16x16x32_bf16 v[68:71], v[172:175], v[212:215], v[68:71]
	v_mfma_f32_16x16x32_bf16 v[64:67], v[180:183], v[212:215], v[64:67]
	s_barrier
; #define PG8_STAGE(bufoff, gbase, voff) do { _Pragma("unroll") for (int _i = 0; _i < 2; ++_i) \
;         __builtin_amdgcn_global_load_lds((const unsigned*)((const char*)(gbase) + (voff)[_i]), (PG8_LAS unsigned*)(lds + (bufoff) + ldsw + _i * 8192), 16, 0, 0); } while (0)
; #define PG8_LDA(dst, b, h) do { _Pragma("unroll") for (int m = 0; m < 4; ++m) _Pragma("unroll") for (int k = 0; k < 2; ++k) dst[m][k] = *(const PG8_LAS bf16x8*)(lds + PG8_SA(b, h) + aoff + m * 2048 + k * 1024); } while (0)
; #define PG8_MMA(ai, bj, At, Bt) do { __builtin_amdgcn_s_setprio(1); _Pragma("unroll") for (int m = 0; m < 4; ++m) _Pragma("unroll") for (int n = 0; n < 2; ++n) _Pragma("unroll") for (int k = 0; k < 2; ++k) \
;         acc[ai][bj][m][n] = __builtin_amdgcn_mfma_f32_16x16x32_bf16(Bt[n][k], At[m][k], acc[ai][bj][m][n], 0, 0, 0); __builtin_amdgcn_s_setprio(0); } while (0)
; #define PG8_WAIT_V(n) asm volatile("s_waitcnt vmcnt(" #n ")" ::: "memory")
; #define PG8_WAIT_L(n) asm volatile("s_waitcnt lgkmcnt(" #n ")" ::: "memory")
; #define PG8_BAR __builtin_amdgcn_s_barrier()
; #define PG8_SCHED __builtin_amdgcn_sched_barrier(0)
; template <class Epi, class Sched, bool ALIGN_EPI = false, bool SP2 = false>
; __device__ __forceinline__ void gemm_phase(PG8_LAS unsigned char* lds, const Gemm g, const Sched& S, const Epi& E, const int tid_in) {
;     ...
;             PG8_WAIT_V(8); PG8_WAIT_L(0); PG8_BAR; PG8_MMA(0, 0, At, B0); PG8_MMA(0, 1, At, B1); PG8_BAR; PG8_SCHED;
;             PG8_LDA(At, 1, 1); PG8_STAGE(PG8_SB(1, 0), b3, voffB); PG8_STAGE(PG8_SB(1, 1), b3 + hstep, voffB); PG8_STAGE(PG8_SA(1, 0), a3, voffA);
;             PG8_WAIT_V(8); PG8_WAIT_L(0); PG8_BAR; PG8_MMA(1, 0, At, B0); PG8_MMA(1, 1, At, B1); PG8_BAR; PG8_SCHED;
	s_add_i32 s38, s63, s43
	v_lshl_add_u64 v[148:149], v[148:149], 0, s[12:13]
	s_mov_b32 m0, s38
	ds_read_b128 v[184:187], v155 offset:49152
	ds_read_b128 v[188:191], v155 offset:50176
	ds_read_b128 v[192:195], v155 offset:51200
	ds_read_b128 v[196:199], v155 offset:52224
	ds_read_b128 v[200:203], v155 offset:53248
	ds_read_b128 v[204:207], v155 offset:54272
	ds_read_b128 v[208:211], v155 offset:55296
	ds_read_b128 v[212:215], v155 offset:56320
	global_load_lds_dwordx4 v[148:149], off
	s_add_i32 m0, s38, 0x2000
	s_add_u32 s36, s36, 0x40080
	v_lshl_add_u64 v[148:149], v[216:217], 0, s[12:13]
	s_addc_u32 s37, s37, 0
	s_add_i32 s38, s64, s43
	global_load_lds_dwordx4 v[148:149], off
	v_lshl_add_u64 v[148:149], s[36:37], 0, v[132:133]
	s_mov_b32 m0, s38
	s_nop 0
	global_load_lds_dwordx4 v[148:149], off
	v_lshl_add_u64 v[148:149], s[36:37], 0, v[128:129]
	s_add_i32 m0, s38, 0x2000
	s_nop 0
	global_load_lds_dwordx4 v[148:149], off
	v_lshl_add_u64 v[148:149], v[218:219], 0, s[12:13]
	s_mov_b32 m0, s50
	s_nop 0
	global_load_lds_dwordx4 v[148:149], off
	v_lshl_add_u64 v[148:149], v[220:221], 0, s[12:13]
	s_mov_b32 m0, s51
	s_nop 0
	global_load_lds_dwordx4 v[148:149], off
	s_waitcnt vmcnt(12)
	s_waitcnt lgkmcnt(0)
	s_barrier
	s_waitcnt lgkmcnt(0)
	v_mfma_f32_16x16x32_bf16 v[60:63], v[144:147], v[184:187], v[60:63]
	v_mfma_f32_16x16x32_bf16 v[56:59], v[160:163], v[184:187], v[56:59]
	v_mfma_f32_16x16x32_bf16 v[44:47], v[144:147], v[192:195], v[44:47]
	v_mfma_f32_16x16x32_bf16 v[40:43], v[160:163], v[192:195], v[40:43]
	v_mfma_f32_16x16x32_bf16 v[28:31], v[144:147], v[200:203], v[28:31]
	v_mfma_f32_16x16x32_bf16 v[24:27], v[160:163], v[200:203], v[24:27]
	v_mfma_f32_16x16x32_bf16 v[12:15], v[144:147], v[208:211], v[12:15]
	v_mfma_f32_16x16x32_bf16 v[8:11], v[160:163], v[208:211], v[8:11]
	v_mfma_f32_16x16x32_bf16 v[60:63], v[156:159], v[188:191], v[60:63]
	v_mfma_f32_16x16x32_bf16 v[56:59], v[164:167], v[188:191], v[56:59]
	v_mfma_f32_16x16x32_bf16 v[44:47], v[156:159], v[196:199], v[44:47]
	v_mfma_f32_16x16x32_bf16 v[40:43], v[164:167], v[196:199], v[40:43]
	v_mfma_f32_16x16x32_bf16 v[28:31], v[156:159], v[204:207], v[28:31]
	v_mfma_f32_16x16x32_bf16 v[24:27], v[164:167], v[204:207], v[24:27]
	v_mfma_f32_16x16x32_bf16 v[12:15], v[156:159], v[212:215], v[12:15]
	v_mfma_f32_16x16x32_bf16 v[8:11], v[164:167], v[212:215], v[8:11]
	v_mfma_f32_16x16x32_bf16 v[52:55], v[168:171], v[184:187], v[52:55]
	v_mfma_f32_16x16x32_bf16 v[48:51], v[176:179], v[184:187], v[48:51]
	v_mfma_f32_16x16x32_bf16 v[36:39], v[168:171], v[192:195], v[36:39]
	v_mfma_f32_16x16x32_bf16 v[32:35], v[176:179], v[192:195], v[32:35]
	v_mfma_f32_16x16x32_bf16 v[20:23], v[168:171], v[200:203], v[20:23]
	v_mfma_f32_16x16x32_bf16 v[16:19], v[176:179], v[200:203], v[16:19]
	v_mfma_f32_16x16x32_bf16 v[4:7], v[168:171], v[208:211], v[4:7]
	v_mfma_f32_16x16x32_bf16 v[0:3], v[176:179], v[208:211], v[0:3]
	v_mfma_f32_16x16x32_bf16 v[52:55], v[172:175], v[188:191], v[52:55]
	v_mfma_f32_16x16x32_bf16 v[48:51], v[180:183], v[188:191], v[48:51]
	v_mfma_f32_16x16x32_bf16 v[36:39], v[172:175], v[196:199], v[36:39]
	v_mfma_f32_16x16x32_bf16 v[32:35], v[180:183], v[196:199], v[32:35]
	v_mfma_f32_16x16x32_bf16 v[20:23], v[172:175], v[204:207], v[20:23]
	v_mfma_f32_16x16x32_bf16 v[16:19], v[180:183], v[204:207], v[16:19]
	v_mfma_f32_16x16x32_bf16 v[4:7], v[172:175], v[212:215], v[4:7]
	v_mfma_f32_16x16x32_bf16 v[0:3], v[180:183], v[212:215], v[0:3]
	s_barrier
	s_add_i32 s62, s62, 2
	s_add_u32 s0, s0, 0x100
	s_addc_u32 s1, s1, 0
	s_add_u32 s60, s60, 0x100
	s_addc_u32 s61, s61, 0
	s_cmp_gt_u32 s62, 13
	s_cbranch_scc0 .LBB0_316
	s_and_b64 vcc, exec, s[14:15]
	s_cbranch_vccz .LBB0_319
	s_barrier

; #define PG8_STAGE(bufoff, gbase, voff) do { _Pragma("unroll") for (int _i = 0; _i < 2; ++_i) \
;         __builtin_amdgcn_global_load_lds((const unsigned*)((const char*)(gbase) + (voff)[_i]), (PG8_LAS unsigned*)(lds + (bufoff) + ldsw + _i * 8192), 16, 0, 0); } while (0)
; #define PG8_LDA(dst, b, h) do { _Pragma("unroll") for (int m = 0; m < 4; ++m) _Pragma("unroll") for (int k = 0; k < 2; ++k) dst[m][k] = *(const PG8_LAS bf16x8*)(lds + PG8_SA(b, h) + aoff + m * 2048 + k * 1024); } while (0)
; #define PG8_LDB(dst, b, h) do { _Pragma("unroll") for (int n = 0; n < 2; ++n) _Pragma("unroll") for (int k = 0; k < 2; ++k) dst[n][k] = *(const PG8_LAS bf16x8*)(lds + PG8_SB(b, h) + boff + n * 2048 + k * 1024); } while (0)
; #define PG8_MMA(ai, bj, At, Bt) do { __builtin_amdgcn_s_setprio(1); _Pragma("unroll") for (int m = 0; m < 4; ++m) _Pragma("unroll") for (int n = 0; n < 2; ++n) _Pragma("unroll") for (int k = 0; k < 2; ++k) \
;         acc[ai][bj][m][n] = __builtin_amdgcn_mfma_f32_16x16x32_bf16(Bt[n][k], At[m][k], acc[ai][bj][m][n], 0, 0, 0); __builtin_amdgcn_s_setprio(0); } while (0)
; #define PG8_WAIT_V(n) asm volatile("s_waitcnt vmcnt(" #n ")" ::: "memory")
; #define PG8_WAIT_L(n) asm volatile("s_waitcnt lgkmcnt(" #n ")" ::: "memory")
; #define PG8_BAR __builtin_amdgcn_s_barrier()
; #define PG8_SCHED __builtin_amdgcn_sched_barrier(0)
; template <class Epi, class Sched, bool ALIGN_EPI = false, bool SP2 = false>
; __device__ __forceinline__ void gemm_phase(PG8_LAS unsigned char* lds, const Gemm g, const Sched& S, const Epi& E, const int tid_in) {
;     ...
;             PG8_LDB(B0, 0, 0); PG8_LDB(B1, 0, 1); PG8_SCHED; PG8_LDA(At, 0, 0); PG8_STAGE(PG8_SA(1, 1), a1 + hstep, voffA);
;             PG8_WAIT_V(8); PG8_WAIT_L(0); PG8_BAR; PG8_MMA(0, 0, At, B0); PG8_MMA(0, 1, At, B1); PG8_BAR; PG8_SCHED;
;             PG8_LDA(At, 0, 1); PG8_STAGE(PG8_SB(0, 0), b2, voffB); PG8_STAGE(PG8_SB(0, 1), b2 + hstep, voffB); PG8_STAGE(PG8_SA(0, 0), a2, voffA);
.LBB0_391:
	ds_read_b128 v[144:147], v153
	ds_read_b128 v[156:159], v153 offset:1024
	ds_read_b128 v[160:163], v153 offset:2048
	ds_read_b128 v[164:167], v153 offset:3072
	ds_read_b128 v[168:171], v154
	ds_read_b128 v[172:175], v154 offset:1024
	ds_read_b128 v[176:179], v154 offset:2048
	ds_read_b128 v[180:183], v154 offset:3072
	s_add_u32 s38, s0, 0xfffc0080
	s_addc_u32 s39, s1, -1
	s_cmp_eq_u32 s62, 12
	s_cselect_b32 s41, s29, s39
	s_cselect_b32 s40, s58, s38
	s_cselect_b32 s39, s27, s61
	s_cselect_b32 s38, s59, s60
	v_lshl_add_u64 v[148:149], s[0:1], 0, v[136:137]
	s_add_i32 m0, s37, 0xc000
	ds_read_b128 v[184:187], v155
	ds_read_b128 v[188:191], v155 offset:1024
	ds_read_b128 v[192:195], v155 offset:2048
	ds_read_b128 v[196:199], v155 offset:3072
	ds_read_b128 v[200:203], v155 offset:4096
	ds_read_b128 v[204:207], v155 offset:5120
	ds_read_b128 v[208:211], v155 offset:6144
	ds_read_b128 v[212:215], v155 offset:7168
	global_load_lds_dwordx4 v[148:149], off
	v_lshl_add_u64 v[148:149], s[0:1], 0, v[138:139]
	s_add_i32 m0, s37, 0xe000
	s_nop 0
	global_load_lds_dwordx4 v[148:149], off
	s_waitcnt vmcnt(8)
	s_waitcnt lgkmcnt(0)
	s_barrier
	s_waitcnt lgkmcnt(0)
	v_mfma_f32_16x16x32_bf16 v[124:127], v[144:147], v[184:187], v[124:127]
	v_mfma_f32_16x16x32_bf16 v[120:123], v[160:163], v[184:187], v[120:123]
	v_mfma_f32_16x16x32_bf16 v[108:111], v[144:147], v[192:195], v[108:111]
	v_mfma_f32_16x16x32_bf16 v[104:107], v[160:163], v[192:195], v[104:107]
	v_mfma_f32_16x16x32_bf16 v[92:95], v[144:147], v[200:203], v[92:95]
	v_mfma_f32_16x16x32_bf16 v[88:91], v[160:163], v[200:203], v[88:91]
	v_mfma_f32_16x16x32_bf16 v[76:79], v[144:147], v[208:211], v[76:79]
	v_mfma_f32_16x16x32_bf16 v[72:75], v[160:163], v[208:211], v[72:75]
	v_mfma_f32_16x16x32_bf16 v[124:127], v[156:159], v[188:191], v[124:127]
	v_mfma_f32_16x16x32_bf16 v[120:123], v[164:167], v[188:191], v[120:123]
	v_mfma_f32_16x16x32_bf16 v[108:111], v[156:159], v[196:199], v[108:111]
	v_mfma_f32_16x16x32_bf16 v[104:107], v[164:167], v[196:199], v[104:107]
	v_mfma_f32_16x16x32_bf16 v[92:95], v[156:159], v[204:207], v[92:95]
	v_mfma_f32_16x16x32_bf16 v[88:91], v[164:167], v[204:207], v[88:91]
	v_mfma_f32_16x16x32_bf16 v[76:79], v[156:159], v[212:215], v[76:79]
	v_mfma_f32_16x16x32_bf16 v[72:75], v[164:167], v[212:215], v[72:75]
	v_mfma_f32_16x16x32_bf16 v[116:119], v[168:171], v[184:187], v[116:119]
	v_mfma_f32_16x16x32_bf16 v[112:115], v[176:179], v[184:187], v[112:115]
	v_mfma_f32_16x16x32_bf16 v[100:103], v[168:171], v[192:195], v[100:103]
	v_mfma_f32_16x16x32_bf16 v[96:99], v[176:179], v[192:195], v[96:99]
	v_mfma_f32_16x16x32_bf16 v[84:87], v[168:171], v[200:203], v[84:87]
	v_mfma_f32_16x16x32_bf16 v[80:83], v[176:179], v[200:203], v[80:83]
	v_mfma_f32_16x16x32_bf16 v[68:71], v[168:171], v[208:211], v[68:71]
	v_mfma_f32_16x16x32_bf16 v[64:67], v[176:179], v[208:211], v[64:67]
	v_mfma_f32_16x16x32_bf16 v[116:119], v[172:175], v[188:191], v[116:119]
	v_mfma_f32_16x16x32_bf16 v[112:115], v[180:183], v[188:191], v[112:115]
	v_mfma_f32_16x16x32_bf16 v[100:103], v[172:175], v[196:199], v[100:103]
	v_mfma_f32_16x16x32_bf16 v[96:99], v[180:183], v[196:199], v[96:99]
	v_mfma_f32_16x16x32_bf16 v[84:87], v[172:175], v[204:207], v[84:87]
	v_mfma_f32_16x16x32_bf16 v[80:83], v[180:183], v[204:207], v[80:83]
	v_mfma_f32_16x16x32_bf16 v[68:71], v[172:175], v[212:215], v[68:71]
	v_mfma_f32_16x16x32_bf16 v[64:67], v[180:183], v[212:215], v[64:67]
	s_barrier
	s_add_i32 s63, s53, s43
	v_lshl_add_u64 v[148:149], s[38:39], 0, v[132:133]
	s_mov_b32 m0, s63
	ds_read_b128 v[184:187], v155 offset:16384
	ds_read_b128 v[188:191], v155 offset:17408
	ds_read_b128 v[192:195], v155 offset:18432
	ds_read_b128 v[196:199], v155 offset:19456
	ds_read_b128 v[200:203], v155 offset:20480
	ds_read_b128 v[204:207], v155 offset:21504
	ds_read_b128 v[208:211], v155 offset:22528
	ds_read_b128 v[212:215], v155 offset:23552
	global_load_lds_dwordx4 v[148:149], off
	s_add_i32 m0, s63, 0x2000
	s_add_u32 s64, s38, 0x40000
	v_lshl_add_u64 v[216:217], s[38:39], 0, v[128:129]
	s_addc_u32 s65, s39, 0
	s_add_i32 s63, s56, s43
	global_load_lds_dwordx4 v[216:217], off
	v_lshl_add_u64 v[218:219], s[64:65], 0, v[132:133]
	s_mov_b32 m0, s63
	v_lshl_add_u64 v[220:221], s[40:41], 0, v[130:131]
	global_load_lds_dwordx4 v[218:219], off
	v_lshl_add_u64 v[218:219], s[64:65], 0, v[128:129]
	s_add_i32 m0, s63, 0x2000
	s_nop 0
	global_load_lds_dwordx4 v[218:219], off
	v_lshl_add_u64 v[218:219], s[40:41], 0, v[134:135]
	s_mov_b32 m0, s37
	s_nop 0
	global_load_lds_dwordx4 v[218:219], off
	s_mov_b32 m0, s45
	s_nop 0
	global_load_lds_dwordx4 v[220:221], off
	s_waitcnt vmcnt(8)
	s_waitcnt lgkmcnt(0)
	s_barrier
; #define PG8_STAGE(bufoff, gbase, voff) do { _Pragma("unroll") for (int _i = 0; _i < 2; ++_i) \
;         __builtin_amdgcn_global_load_lds((const unsigned*)((const char*)(gbase) + (voff)[_i]), (PG8_LAS unsigned*)(lds + (bufoff) + ldsw + _i * 8192), 16, 0, 0); } while (0)
; #define PG8_LDA(dst, b, h) do { _Pragma("unroll") for (int m = 0; m < 4; ++m) _Pragma("unroll") for (int k = 0; k < 2; ++k) dst[m][k] = *(const PG8_LAS bf16x8*)(lds + PG8_SA(b, h) + aoff + m * 2048 + k * 1024); } while (0)
; #define PG8_LDB(dst, b, h) do { _Pragma("unroll") for (int n = 0; n < 2; ++n) _Pragma("unroll") for (int k = 0; k < 2; ++k) dst[n][k] = *(const PG8_LAS bf16x8*)(lds + PG8_SB(b, h) + boff + n * 2048 + k * 1024); } while (0)
; #define PG8_MMA(ai, bj, At, Bt) do { __builtin_amdgcn_s_setprio(1); _Pragma("unroll") for (int m = 0; m < 4; ++m) _Pragma("unroll") for (int n = 0; n < 2; ++n) _Pragma("unroll") for (int k = 0; k < 2; ++k) \
;         acc[ai][bj][m][n] = __builtin_amdgcn_mfma_f32_16x16x32_bf16(Bt[n][k], At[m][k], acc[ai][bj][m][n], 0, 0, 0); __builtin_amdgcn_s_setprio(0); } while (0)
; #define PG8_WAIT_V(n) asm volatile("s_waitcnt vmcnt(" #n ")" ::: "memory")
; #define PG8_WAIT_L(n) asm volatile("s_waitcnt lgkmcnt(" #n ")" ::: "memory")
; #define PG8_BAR __builtin_amdgcn_s_barrier()
; #define PG8_SCHED __builtin_amdgcn_sched_barrier(0)
; template <class Epi, class Sched, bool ALIGN_EPI = false, bool SP2 = false>
; __device__ __forceinline__ void gemm_phase(PG8_LAS unsigned char* lds, const Gemm g, const Sched& S, const Epi& E, const int tid_in) {
;     ...
;             PG8_LDA(At, 0, 1); PG8_STAGE(PG8_SB(0, 0), b2, voffB); PG8_STAGE(PG8_SB(0, 1), b2 + hstep, voffB); PG8_STAGE(PG8_SA(0, 0), a2, voffA);
;             PG8_WAIT_V(8); PG8_WAIT_L(0); PG8_BAR; PG8_MMA(1, 0, At, B0); PG8_MMA(1, 1, At, B1); PG8_BAR; PG8_SCHED;
;             PG8_LDB(B0, 1, 0); PG8_LDB(B1, 1, 1); PG8_SCHED; PG8_LDA(At, 1, 0); PG8_STAGE(PG8_SA(0, 1), a2 + hstep, voffA);
;             PG8_WAIT_V(8); PG8_WAIT_L(0); PG8_BAR; PG8_MMA(0, 0, At, B0); PG8_MMA(0, 1, At, B1); PG8_BAR; PG8_SCHED;
	s_waitcnt lgkmcnt(0)
	v_mfma_f32_16x16x32_bf16 v[60:63], v[144:147], v[184:187], v[60:63]
	v_mfma_f32_16x16x32_bf16 v[56:59], v[160:163], v[184:187], v[56:59]
	v_mfma_f32_16x16x32_bf16 v[44:47], v[144:147], v[192:195], v[44:47]
	v_mfma_f32_16x16x32_bf16 v[40:43], v[160:163], v[192:195], v[40:43]
	v_mfma_f32_16x16x32_bf16 v[28:31], v[144:147], v[200:203], v[28:31]
	v_mfma_f32_16x16x32_bf16 v[24:27], v[160:163], v[200:203], v[24:27]
	v_mfma_f32_16x16x32_bf16 v[12:15], v[144:147], v[208:211], v[12:15]
	v_mfma_f32_16x16x32_bf16 v[8:11], v[160:163], v[208:211], v[8:11]
	v_mfma_f32_16x16x32_bf16 v[60:63], v[156:159], v[188:191], v[60:63]
	v_mfma_f32_16x16x32_bf16 v[56:59], v[164:167], v[188:191], v[56:59]
	v_mfma_f32_16x16x32_bf16 v[44:47], v[156:159], v[196:199], v[44:47]
	v_mfma_f32_16x16x32_bf16 v[40:43], v[164:167], v[196:199], v[40:43]
	v_mfma_f32_16x16x32_bf16 v[28:31], v[156:159], v[204:207], v[28:31]
	v_mfma_f32_16x16x32_bf16 v[24:27], v[164:167], v[204:207], v[24:27]
	v_mfma_f32_16x16x32_bf16 v[12:15], v[156:159], v[212:215], v[12:15]
	v_mfma_f32_16x16x32_bf16 v[8:11], v[164:167], v[212:215], v[8:11]
	v_mfma_f32_16x16x32_bf16 v[52:55], v[168:171], v[184:187], v[52:55]
	v_mfma_f32_16x16x32_bf16 v[48:51], v[176:179], v[184:187], v[48:51]
	v_mfma_f32_16x16x32_bf16 v[36:39], v[168:171], v[192:195], v[36:39]
	v_mfma_f32_16x16x32_bf16 v[32:35], v[176:179], v[192:195], v[32:35]
	v_mfma_f32_16x16x32_bf16 v[20:23], v[168:171], v[200:203], v[20:23]
	v_mfma_f32_16x16x32_bf16 v[16:19], v[176:179], v[200:203], v[16:19]
	v_mfma_f32_16x16x32_bf16 v[4:7], v[168:171], v[208:211], v[4:7]
	v_mfma_f32_16x16x32_bf16 v[0:3], v[176:179], v[208:211], v[0:3]
	v_mfma_f32_16x16x32_bf16 v[52:55], v[172:175], v[188:191], v[52:55]
	v_mfma_f32_16x16x32_bf16 v[48:51], v[180:183], v[188:191], v[48:51]
	v_mfma_f32_16x16x32_bf16 v[36:39], v[172:175], v[196:199], v[36:39]
	v_mfma_f32_16x16x32_bf16 v[32:35], v[180:183], v[196:199], v[32:35]
	v_mfma_f32_16x16x32_bf16 v[20:23], v[172:175], v[204:207], v[20:23]
	v_mfma_f32_16x16x32_bf16 v[16:19], v[180:183], v[204:207], v[16:19]
	v_mfma_f32_16x16x32_bf16 v[4:7], v[172:175], v[212:215], v[4:7]
	v_mfma_f32_16x16x32_bf16 v[0:3], v[180:183], v[212:215], v[0:3]
	s_barrier
	s_add_i32 s63, 0, 0x18000
	s_add_i32 s64, 0, 0x1c000
	v_add_u32_e32 v164, s63, v151
	v_add_u32_e32 v180, s64, v151
	ds_read_b128 v[144:147], v164
	ds_read_b128 v[156:159], v164 offset:1024
	ds_read_b128 v[160:163], v164 offset:2048
	ds_read_b128 v[164:167], v164 offset:3072
	ds_read_b128 v[168:171], v180
	ds_read_b128 v[172:175], v180 offset:1024
	ds_read_b128 v[176:179], v180 offset:2048
	ds_read_b128 v[180:183], v180 offset:3072
	s_add_u32 s40, s40, 0x40000
	s_addc_u32 s41, s41, 0
	s_mov_b32 m0, s46
	v_lshl_add_u64 v[222:223], s[40:41], 0, v[134:135]
	ds_read_b128 v[184:187], v155 offset:32768
	ds_read_b128 v[188:191], v155 offset:33792
	ds_read_b128 v[192:195], v155 offset:34816
	ds_read_b128 v[196:199], v155 offset:35840
	ds_read_b128 v[200:203], v155 offset:36864
	ds_read_b128 v[204:207], v155 offset:37888
	ds_read_b128 v[208:211], v155 offset:38912
	ds_read_b128 v[212:215], v155 offset:39936
	global_load_lds_dwordx4 v[222:223], off
	v_lshl_add_u64 v[222:223], s[40:41], 0, v[130:131]
	s_mov_b32 m0, s47
	s_nop 0
	global_load_lds_dwordx4 v[222:223], off
	s_waitcnt vmcnt(8)
	s_waitcnt lgkmcnt(0)
	s_barrier
	s_waitcnt lgkmcnt(0)
	v_mfma_f32_16x16x32_bf16 v[124:127], v[144:147], v[184:187], v[124:127]
	v_mfma_f32_16x16x32_bf16 v[120:123], v[160:163], v[184:187], v[120:123]
	v_mfma_f32_16x16x32_bf16 v[108:111], v[144:147], v[192:195], v[108:111]
	v_mfma_f32_16x16x32_bf16 v[104:107], v[160:163], v[192:195], v[104:107]
	v_mfma_f32_16x16x32_bf16 v[92:95], v[144:147], v[200:203], v[92:95]
	v_mfma_f32_16x16x32_bf16 v[88:91], v[160:163], v[200:203], v[88:91]
	v_mfma_f32_16x16x32_bf16 v[76:79], v[144:147], v[208:211], v[76:79]
	v_mfma_f32_16x16x32_bf16 v[72:75], v[160:163], v[208:211], v[72:75]
	v_mfma_f32_16x16x32_bf16 v[124:127], v[156:159], v[188:191], v[124:127]
	v_mfma_f32_16x16x32_bf16 v[120:123], v[164:167], v[188:191], v[120:123]
	v_mfma_f32_16x16x32_bf16 v[108:111], v[156:159], v[196:199], v[108:111]
	v_mfma_f32_16x16x32_bf16 v[104:107], v[164:167], v[196:199], v[104:107]
	v_mfma_f32_16x16x32_bf16 v[92:95], v[156:159], v[204:207], v[92:95]
	v_mfma_f32_16x16x32_bf16 v[88:91], v[164:167], v[204:207], v[88:91]
	v_mfma_f32_16x16x32_bf16 v[76:79], v[156:159], v[212:215], v[76:79]
	v_mfma_f32_16x16x32_bf16 v[72:75], v[164:167], v[212:215], v[72:75]
	v_mfma_f32_16x16x32_bf16 v[116:119], v[168:171], v[184:187], v[116:119]
	v_mfma_f32_16x16x32_bf16 v[112:115], v[176:179], v[184:187], v[112:115]
	v_mfma_f32_16x16x32_bf16 v[100:103], v[168:171], v[192:195], v[100:103]
	v_mfma_f32_16x16x32_bf16 v[96:99], v[176:179], v[192:195], v[96:99]
	v_mfma_f32_16x16x32_bf16 v[84:87], v[168:171], v[200:203], v[84:87]
	v_mfma_f32_16x16x32_bf16 v[80:83], v[176:179], v[200:203], v[80:83]
	v_mfma_f32_16x16x32_bf16 v[68:71], v[168:171], v[208:211], v[68:71]
	v_mfma_f32_16x16x32_bf16 v[64:67], v[176:179], v[208:211], v[64:67]
	v_mfma_f32_16x16x32_bf16 v[116:119], v[172:175], v[188:191], v[116:119]
	v_mfma_f32_16x16x32_bf16 v[112:115], v[180:183], v[188:191], v[112:115]
	v_mfma_f32_16x16x32_bf16 v[100:103], v[172:175], v[196:199], v[100:103]
	v_mfma_f32_16x16x32_bf16 v[96:99], v[180:183], v[196:199], v[96:99]
	v_mfma_f32_16x16x32_bf16 v[84:87], v[172:175], v[204:207], v[84:87]
	v_mfma_f32_16x16x32_bf16 v[80:83], v[180:183], v[204:207], v[80:83]
	v_mfma_f32_16x16x32_bf16 v[68:71], v[172:175], v[212:215], v[68:71]
	v_mfma_f32_16x16x32_bf16 v[64:67], v[180:183], v[212:215], v[64:67]
	s_barrier
; #define PG8_STAGE(bufoff, gbase, voff) do { _Pragma("unroll") for (int _i = 0; _i < 2; ++_i) \
;         __builtin_amdgcn_global_load_lds((const unsigned*)((const char*)(gbase) + (voff)[_i]), (PG8_LAS unsigned*)(lds + (bufoff) + ldsw + _i * 8192), 16, 0, 0); } while (0)
; #define PG8_LDA(dst, b, h) do { _Pragma("unroll") for (int m = 0; m < 4; ++m) _Pragma("unroll") for (int k = 0; k < 2; ++k) dst[m][k] = *(const PG8_LAS bf16x8*)(lds + PG8_SA(b, h) + aoff + m * 2048 + k * 1024); } while (0)
; #define PG8_MMA(ai, bj, At, Bt) do { __builtin_amdgcn_s_setprio(1); _Pragma("unroll") for (int m = 0; m < 4; ++m) _Pragma("unroll") for (int n = 0; n < 2; ++n) _Pragma("unroll") for (int k = 0; k < 2; ++k) \
;         acc[ai][bj][m][n] = __builtin_amdgcn_mfma_f32_16x16x32_bf16(Bt[n][k], At[m][k], acc[ai][bj][m][n], 0, 0, 0); __builtin_amdgcn_s_setprio(0); } while (0)
; #define PG8_WAIT_V(n) asm volatile("s_waitcnt vmcnt(" #n ")" ::: "memory")
; #define PG8_WAIT_L(n) asm volatile("s_waitcnt lgkmcnt(" #n ")" ::: "memory")
; #define PG8_BAR __builtin_amdgcn_s_barrier()
; #define PG8_SCHED __builtin_amdgcn_sched_barrier(0)
; template <class Epi, class Sched, bool ALIGN_EPI = false, bool SP2 = false>
; __device__ __forceinline__ void gemm_phase(PG8_LAS unsigned char* lds, const Gemm g, const Sched& S, const Epi& E, const int tid_in) {
;     ...
;             PG8_WAIT_V(8); PG8_WAIT_L(0); PG8_BAR; PG8_MMA(0, 0, At, B0); PG8_MMA(0, 1, At, B1); PG8_BAR; PG8_SCHED;
;             PG8_LDA(At, 1, 1); PG8_STAGE(PG8_SB(1, 0), b3, voffB); PG8_STAGE(PG8_SB(1, 1), b3 + hstep, voffB); PG8_STAGE(PG8_SA(1, 0), a3, voffA);
;             PG8_WAIT_V(8); PG8_WAIT_L(0); PG8_BAR; PG8_MMA(1, 0, At, B0); PG8_MMA(1, 1, At, B1); PG8_BAR; PG8_SCHED;
	s_add_i32 s40, s63, s43
	v_lshl_add_u64 v[148:149], v[148:149], 0, s[16:17]
	s_mov_b32 m0, s40
	ds_read_b128 v[184:187], v155 offset:49152
	ds_read_b128 v[188:191], v155 offset:50176
	ds_read_b128 v[192:195], v155 offset:51200
	ds_read_b128 v[196:199], v155 offset:52224
	ds_read_b128 v[200:203], v155 offset:53248
	ds_read_b128 v[204:207], v155 offset:54272
	ds_read_b128 v[208:211], v155 offset:55296
	ds_read_b128 v[212:215], v155 offset:56320
	global_load_lds_dwordx4 v[148:149], off
	s_add_i32 m0, s40, 0x2000
	s_add_u32 s38, s38, 0x40080
	v_lshl_add_u64 v[148:149], v[216:217], 0, s[16:17]
	s_addc_u32 s39, s39, 0
	s_add_i32 s40, s64, s43
	global_load_lds_dwordx4 v[148:149], off
	v_lshl_add_u64 v[148:149], s[38:39], 0, v[132:133]
	s_mov_b32 m0, s40
	s_nop 0
	global_load_lds_dwordx4 v[148:149], off
	v_lshl_add_u64 v[148:149], s[38:39], 0, v[128:129]
	s_add_i32 m0, s40, 0x2000
	s_nop 0
	global_load_lds_dwordx4 v[148:149], off
	v_lshl_add_u64 v[148:149], v[218:219], 0, s[16:17]
	s_mov_b32 m0, s50
	s_nop 0
	global_load_lds_dwordx4 v[148:149], off
	v_lshl_add_u64 v[148:149], v[220:221], 0, s[16:17]
	s_mov_b32 m0, s51
	s_nop 0
	global_load_lds_dwordx4 v[148:149], off
	s_waitcnt vmcnt(8)
	s_waitcnt lgkmcnt(0)
	s_barrier
	s_waitcnt lgkmcnt(0)
	v_mfma_f32_16x16x32_bf16 v[60:63], v[144:147], v[184:187], v[60:63]
	v_mfma_f32_16x16x32_bf16 v[56:59], v[160:163], v[184:187], v[56:59]
	v_mfma_f32_16x16x32_bf16 v[44:47], v[144:147], v[192:195], v[44:47]
	v_mfma_f32_16x16x32_bf16 v[40:43], v[160:163], v[192:195], v[40:43]
	v_mfma_f32_16x16x32_bf16 v[28:31], v[144:147], v[200:203], v[28:31]
	v_mfma_f32_16x16x32_bf16 v[24:27], v[160:163], v[200:203], v[24:27]
	v_mfma_f32_16x16x32_bf16 v[12:15], v[144:147], v[208:211], v[12:15]
	v_mfma_f32_16x16x32_bf16 v[8:11], v[160:163], v[208:211], v[8:11]
	v_mfma_f32_16x16x32_bf16 v[60:63], v[156:159], v[188:191], v[60:63]
	v_mfma_f32_16x16x32_bf16 v[56:59], v[164:167], v[188:191], v[56:59]
	v_mfma_f32_16x16x32_bf16 v[44:47], v[156:159], v[196:199], v[44:47]
	v_mfma_f32_16x16x32_bf16 v[40:43], v[164:167], v[196:199], v[40:43]
	v_mfma_f32_16x16x32_bf16 v[28:31], v[156:159], v[204:207], v[28:31]
	v_mfma_f32_16x16x32_bf16 v[24:27], v[164:167], v[204:207], v[24:27]
	v_mfma_f32_16x16x32_bf16 v[12:15], v[156:159], v[212:215], v[12:15]
	v_mfma_f32_16x16x32_bf16 v[8:11], v[164:167], v[212:215], v[8:11]
	v_mfma_f32_16x16x32_bf16 v[52:55], v[168:171], v[184:187], v[52:55]
	v_mfma_f32_16x16x32_bf16 v[48:51], v[176:179], v[184:187], v[48:51]
	v_mfma_f32_16x16x32_bf16 v[36:39], v[168:171], v[192:195], v[36:39]
	v_mfma_f32_16x16x32_bf16 v[32:35], v[176:179], v[192:195], v[32:35]
	v_mfma_f32_16x16x32_bf16 v[20:23], v[168:171], v[200:203], v[20:23]
	v_mfma_f32_16x16x32_bf16 v[16:19], v[176:179], v[200:203], v[16:19]
	v_mfma_f32_16x16x32_bf16 v[4:7], v[168:171], v[208:211], v[4:7]
	v_mfma_f32_16x16x32_bf16 v[0:3], v[176:179], v[208:211], v[0:3]
	v_mfma_f32_16x16x32_bf16 v[52:55], v[172:175], v[188:191], v[52:55]
	v_mfma_f32_16x16x32_bf16 v[48:51], v[180:183], v[188:191], v[48:51]
	v_mfma_f32_16x16x32_bf16 v[36:39], v[172:175], v[196:199], v[36:39]
	v_mfma_f32_16x16x32_bf16 v[32:35], v[180:183], v[196:199], v[32:35]
	v_mfma_f32_16x16x32_bf16 v[20:23], v[172:175], v[204:207], v[20:23]
	v_mfma_f32_16x16x32_bf16 v[16:19], v[180:183], v[204:207], v[16:19]
	v_mfma_f32_16x16x32_bf16 v[4:7], v[172:175], v[212:215], v[4:7]
	v_mfma_f32_16x16x32_bf16 v[0:3], v[180:183], v[212:215], v[0:3]
	s_barrier
	s_add_i32 s62, s62, 2
	s_add_u32 s0, s0, 0x100
	s_addc_u32 s1, s1, 0
	s_add_u32 s60, s60, 0x100
	s_addc_u32 s61, s61, 0
	s_cmp_gt_u32 s62, 13
	s_cbranch_scc0 .LBB0_391
	s_and_b64 vcc, exec, s[18:19]
	s_cbranch_vccz .LBB0_394
	s_barrier

; #define PG8_STAGE(bufoff, gbase, voff) do { _Pragma("unroll") for (int _i = 0; _i < 2; ++_i) \
;         __builtin_amdgcn_global_load_lds((const unsigned*)((const char*)(gbase) + (voff)[_i]), (PG8_LAS unsigned*)(lds + (bufoff) + ldsw + _i * 8192), 16, 0, 0); } while (0)
; #define PG8_LDA(dst, b, h) do { _Pragma("unroll") for (int m = 0; m < 4; ++m) _Pragma("unroll") for (int k = 0; k < 2; ++k) dst[m][k] = *(const PG8_LAS bf16x8*)(lds + PG8_SA(b, h) + aoff + m * 2048 + k * 1024); } while (0)
; #define PG8_LDB(dst, b, h) do { _Pragma("unroll") for (int n = 0; n < 2; ++n) _Pragma("unroll") for (int k = 0; k < 2; ++k) dst[n][k] = *(const PG8_LAS bf16x8*)(lds + PG8_SB(b, h) + boff + n * 2048 + k * 1024); } while (0)
; #define PG8_MMA(ai, bj, At, Bt) do { __builtin_amdgcn_s_setprio(1); _Pragma("unroll") for (int m = 0; m < 4; ++m) _Pragma("unroll") for (int n = 0; n < 2; ++n) _Pragma("unroll") for (int k = 0; k < 2; ++k) \
;         acc[ai][bj][m][n] = __builtin_amdgcn_mfma_f32_16x16x32_bf16(Bt[n][k], At[m][k], acc[ai][bj][m][n], 0, 0, 0); __builtin_amdgcn_s_setprio(0); } while (0)
; #define PG8_WAIT_V(n) asm volatile("s_waitcnt vmcnt(" #n ")" ::: "memory")
; #define PG8_WAIT_L(n) asm volatile("s_waitcnt lgkmcnt(" #n ")" ::: "memory")
; #define PG8_BAR __builtin_amdgcn_s_barrier()
; #define PG8_SCHED __builtin_amdgcn_sched_barrier(0)
; template <class Epi, class Sched, bool ALIGN_EPI = false, bool SP2 = false>
; __device__ __forceinline__ void gemm_phase(PG8_LAS unsigned char* lds, const Gemm g, const Sched& S, const Epi& E, const int tid_in) {
;     ...
;             PG8_LDB(B0, 0, 0); PG8_LDB(B1, 0, 1); PG8_SCHED; PG8_LDA(At, 0, 0); PG8_STAGE(PG8_SA(1, 1), a1 + hstep, voffA);
;             PG8_WAIT_V(8); PG8_WAIT_L(0); PG8_BAR; PG8_MMA(0, 0, At, B0); PG8_MMA(0, 1, At, B1); PG8_BAR; PG8_SCHED;
;             PG8_LDA(At, 0, 1); PG8_STAGE(PG8_SB(0, 0), b2, voffB); PG8_STAGE(PG8_SB(0, 1), b2 + hstep, voffB); PG8_STAGE(PG8_SA(0, 0), a2, voffA);
.LBB0_535:
	ds_read_b128 v[174:177], v170
	ds_read_b128 v[178:181], v170 offset:1024
	ds_read_b128 v[182:185], v170 offset:2048
	ds_read_b128 v[186:189], v170 offset:3072
	ds_read_b128 v[190:193], v171
	ds_read_b128 v[194:197], v171 offset:1024
	ds_read_b128 v[198:201], v171 offset:2048
	ds_read_b128 v[202:205], v171 offset:3072
	s_add_u32 s38, s0, 0xfffc0080
	s_addc_u32 s39, s1, -1
	s_cmp_eq_u32 s73, 12
	s_cselect_b32 s41, s29, s39
	s_cselect_b32 s40, s69, s38
	s_cselect_b32 s39, s27, s72
	s_cselect_b32 s38, s70, s71
	v_lshl_add_u64 v[144:145], s[0:1], 0, v[136:137]
	s_add_i32 m0, s37, 0xc000
	ds_read_b128 v[206:209], v172
	ds_read_b128 v[210:213], v172 offset:1024
	ds_read_b128 v[214:217], v172 offset:2048
	ds_read_b128 v[218:221], v172 offset:3072
	ds_read_b128 v[222:225], v172 offset:4096
	ds_read_b128 v[226:229], v172 offset:5120
	ds_read_b128 v[230:233], v172 offset:6144
	ds_read_b128 v[234:237], v172 offset:7168
	global_load_lds_dwordx4 v[144:145], off
	v_lshl_add_u64 v[144:145], s[0:1], 0, v[138:139]
	s_add_i32 m0, s37, 0xe000
	s_nop 0
	global_load_lds_dwordx4 v[144:145], off
	s_waitcnt vmcnt(8)
	s_waitcnt lgkmcnt(0)
	s_barrier
	s_waitcnt lgkmcnt(0)
	v_mfma_f32_16x16x32_bf16 v[124:127], v[174:177], v[206:209], v[124:127]
	v_mfma_f32_16x16x32_bf16 v[120:123], v[182:185], v[206:209], v[120:123]
	v_mfma_f32_16x16x32_bf16 v[116:119], v[174:177], v[214:217], v[116:119]
	v_mfma_f32_16x16x32_bf16 v[108:111], v[182:185], v[214:217], v[108:111]
	v_mfma_f32_16x16x32_bf16 v[100:103], v[174:177], v[222:225], v[100:103]
	v_mfma_f32_16x16x32_bf16 v[92:95], v[182:185], v[222:225], v[92:95]
	v_mfma_f32_16x16x32_bf16 v[84:87], v[174:177], v[230:233], v[84:87]
	v_mfma_f32_16x16x32_bf16 v[76:79], v[182:185], v[230:233], v[76:79]
	v_mfma_f32_16x16x32_bf16 v[124:127], v[178:181], v[210:213], v[124:127]
	v_mfma_f32_16x16x32_bf16 v[120:123], v[186:189], v[210:213], v[120:123]
	v_mfma_f32_16x16x32_bf16 v[116:119], v[178:181], v[218:221], v[116:119]
	v_mfma_f32_16x16x32_bf16 v[108:111], v[186:189], v[218:221], v[108:111]
	v_mfma_f32_16x16x32_bf16 v[100:103], v[178:181], v[226:229], v[100:103]
	v_mfma_f32_16x16x32_bf16 v[92:95], v[186:189], v[226:229], v[92:95]
	v_mfma_f32_16x16x32_bf16 v[84:87], v[178:181], v[234:237], v[84:87]
	v_mfma_f32_16x16x32_bf16 v[76:79], v[186:189], v[234:237], v[76:79]
	v_mfma_f32_16x16x32_bf16 v[112:115], v[190:193], v[206:209], v[112:115]
	v_mfma_f32_16x16x32_bf16 v[104:107], v[198:201], v[206:209], v[104:107]
	v_mfma_f32_16x16x32_bf16 v[96:99], v[190:193], v[214:217], v[96:99]
	v_mfma_f32_16x16x32_bf16 v[88:91], v[198:201], v[214:217], v[88:91]
	v_mfma_f32_16x16x32_bf16 v[80:83], v[190:193], v[222:225], v[80:83]
	v_mfma_f32_16x16x32_bf16 v[72:75], v[198:201], v[222:225], v[72:75]
	v_mfma_f32_16x16x32_bf16 v[68:71], v[190:193], v[230:233], v[68:71]
	v_mfma_f32_16x16x32_bf16 v[64:67], v[198:201], v[230:233], v[64:67]
	v_mfma_f32_16x16x32_bf16 v[112:115], v[194:197], v[210:213], v[112:115]
	v_mfma_f32_16x16x32_bf16 v[104:107], v[202:205], v[210:213], v[104:107]
	v_mfma_f32_16x16x32_bf16 v[96:99], v[194:197], v[218:221], v[96:99]
	v_mfma_f32_16x16x32_bf16 v[88:91], v[202:205], v[218:221], v[88:91]
	v_mfma_f32_16x16x32_bf16 v[80:83], v[194:197], v[226:229], v[80:83]
	v_mfma_f32_16x16x32_bf16 v[72:75], v[202:205], v[226:229], v[72:75]
	v_mfma_f32_16x16x32_bf16 v[68:71], v[194:197], v[234:237], v[68:71]
	v_mfma_f32_16x16x32_bf16 v[64:67], v[202:205], v[234:237], v[64:67]
	s_barrier
	s_add_i32 s74, s62, s51
	v_lshl_add_u64 v[144:145], s[38:39], 0, v[132:133]
	s_mov_b32 m0, s74
	ds_read_b128 v[206:209], v172 offset:16384
	ds_read_b128 v[210:213], v172 offset:17408
	ds_read_b128 v[214:217], v172 offset:18432
	ds_read_b128 v[218:221], v172 offset:19456
	ds_read_b128 v[222:225], v172 offset:20480
	ds_read_b128 v[226:229], v172 offset:21504
	ds_read_b128 v[230:233], v172 offset:22528
	ds_read_b128 v[234:237], v172 offset:23552
	global_load_lds_dwordx4 v[144:145], off
	s_add_i32 m0, s74, 0x2000
	s_add_u32 s74, s38, 0x40000
	v_lshl_add_u64 v[238:239], s[38:39], 0, v[128:129]
	s_addc_u32 s75, s39, 0
	s_add_i32 s76, s63, s51
	global_load_lds_dwordx4 v[238:239], off
	v_lshl_add_u64 v[240:241], s[74:75], 0, v[132:133]
	s_mov_b32 m0, s76
	v_lshl_add_u64 v[242:243], s[40:41], 0, v[130:131]
	global_load_lds_dwordx4 v[240:241], off
	v_lshl_add_u64 v[240:241], s[74:75], 0, v[128:129]
	s_add_i32 m0, s76, 0x2000
	s_nop 0
	global_load_lds_dwordx4 v[240:241], off
	v_lshl_add_u64 v[240:241], s[40:41], 0, v[134:135]
	s_mov_b32 m0, s37
	s_nop 0
	global_load_lds_dwordx4 v[240:241], off
	s_mov_b32 m0, s52
	s_nop 0
	global_load_lds_dwordx4 v[242:243], off
	s_waitcnt vmcnt(8)
	s_waitcnt lgkmcnt(0)
	s_barrier
; #define PG8_STAGE(bufoff, gbase, voff) do { _Pragma("unroll") for (int _i = 0; _i < 2; ++_i) \
;         __builtin_amdgcn_global_load_lds((const unsigned*)((const char*)(gbase) + (voff)[_i]), (PG8_LAS unsigned*)(lds + (bufoff) + ldsw + _i * 8192), 16, 0, 0); } while (0)
; #define PG8_LDA(dst, b, h) do { _Pragma("unroll") for (int m = 0; m < 4; ++m) _Pragma("unroll") for (int k = 0; k < 2; ++k) dst[m][k] = *(const PG8_LAS bf16x8*)(lds + PG8_SA(b, h) + aoff + m * 2048 + k * 1024); } while (0)
; #define PG8_LDB(dst, b, h) do { _Pragma("unroll") for (int n = 0; n < 2; ++n) _Pragma("unroll") for (int k = 0; k < 2; ++k) dst[n][k] = *(const PG8_LAS bf16x8*)(lds + PG8_SB(b, h) + boff + n * 2048 + k * 1024); } while (0)
; #define PG8_MMA(ai, bj, At, Bt) do { __builtin_amdgcn_s_setprio(1); _Pragma("unroll") for (int m = 0; m < 4; ++m) _Pragma("unroll") for (int n = 0; n < 2; ++n) _Pragma("unroll") for (int k = 0; k < 2; ++k) \
;         acc[ai][bj][m][n] = __builtin_amdgcn_mfma_f32_16x16x32_bf16(Bt[n][k], At[m][k], acc[ai][bj][m][n], 0, 0, 0); __builtin_amdgcn_s_setprio(0); } while (0)
; #define PG8_WAIT_V(n) asm volatile("s_waitcnt vmcnt(" #n ")" ::: "memory")
; #define PG8_WAIT_L(n) asm volatile("s_waitcnt lgkmcnt(" #n ")" ::: "memory")
; #define PG8_BAR __builtin_amdgcn_s_barrier()
; #define PG8_SCHED __builtin_amdgcn_sched_barrier(0)
; template <class Epi, class Sched, bool ALIGN_EPI = false, bool SP2 = false>
; __device__ __forceinline__ void gemm_phase(PG8_LAS unsigned char* lds, const Gemm g, const Sched& S, const Epi& E, const int tid_in) {
;     ...
;             PG8_LDA(At, 0, 1); PG8_STAGE(PG8_SB(0, 0), b2, voffB); PG8_STAGE(PG8_SB(0, 1), b2 + hstep, voffB); PG8_STAGE(PG8_SA(0, 0), a2, voffA);
;             PG8_WAIT_V(8); PG8_WAIT_L(0); PG8_BAR; PG8_MMA(1, 0, At, B0); PG8_MMA(1, 1, At, B1); PG8_BAR; PG8_SCHED;
;             PG8_LDB(B0, 1, 0); PG8_LDB(B1, 1, 1); PG8_SCHED; PG8_LDA(At, 1, 0); PG8_STAGE(PG8_SA(0, 1), a2 + hstep, voffA);
;             PG8_WAIT_V(8); PG8_WAIT_L(0); PG8_BAR; PG8_MMA(0, 0, At, B0); PG8_MMA(0, 1, At, B1); PG8_BAR; PG8_SCHED;
	s_waitcnt lgkmcnt(0)
	v_mfma_f32_16x16x32_bf16 v[60:63], v[174:177], v[206:209], v[60:63]
	v_mfma_f32_16x16x32_bf16 v[56:59], v[182:185], v[206:209], v[56:59]
	v_mfma_f32_16x16x32_bf16 v[52:55], v[174:177], v[214:217], v[52:55]
	v_mfma_f32_16x16x32_bf16 v[44:47], v[182:185], v[214:217], v[44:47]
	v_mfma_f32_16x16x32_bf16 v[36:39], v[174:177], v[222:225], v[36:39]
	v_mfma_f32_16x16x32_bf16 v[28:31], v[182:185], v[222:225], v[28:31]
	v_mfma_f32_16x16x32_bf16 v[20:23], v[174:177], v[230:233], v[20:23]
	v_mfma_f32_16x16x32_bf16 v[12:15], v[182:185], v[230:233], v[12:15]
	v_mfma_f32_16x16x32_bf16 v[60:63], v[178:181], v[210:213], v[60:63]
	v_mfma_f32_16x16x32_bf16 v[56:59], v[186:189], v[210:213], v[56:59]
	v_mfma_f32_16x16x32_bf16 v[52:55], v[178:181], v[218:221], v[52:55]
	v_mfma_f32_16x16x32_bf16 v[44:47], v[186:189], v[218:221], v[44:47]
	v_mfma_f32_16x16x32_bf16 v[36:39], v[178:181], v[226:229], v[36:39]
	v_mfma_f32_16x16x32_bf16 v[28:31], v[186:189], v[226:229], v[28:31]
	v_mfma_f32_16x16x32_bf16 v[20:23], v[178:181], v[234:237], v[20:23]
	v_mfma_f32_16x16x32_bf16 v[12:15], v[186:189], v[234:237], v[12:15]
	v_mfma_f32_16x16x32_bf16 v[48:51], v[190:193], v[206:209], v[48:51]
	v_mfma_f32_16x16x32_bf16 v[40:43], v[198:201], v[206:209], v[40:43]
	v_mfma_f32_16x16x32_bf16 v[32:35], v[190:193], v[214:217], v[32:35]
	v_mfma_f32_16x16x32_bf16 v[24:27], v[198:201], v[214:217], v[24:27]
	v_mfma_f32_16x16x32_bf16 v[16:19], v[190:193], v[222:225], v[16:19]
	v_mfma_f32_16x16x32_bf16 v[8:11], v[198:201], v[222:225], v[8:11]
	v_mfma_f32_16x16x32_bf16 v[4:7], v[190:193], v[230:233], v[4:7]
	v_mfma_f32_16x16x32_bf16 v[0:3], v[198:201], v[230:233], v[0:3]
	v_mfma_f32_16x16x32_bf16 v[48:51], v[194:197], v[210:213], v[48:51]
	v_mfma_f32_16x16x32_bf16 v[40:43], v[202:205], v[210:213], v[40:43]
	v_mfma_f32_16x16x32_bf16 v[32:35], v[194:197], v[218:221], v[32:35]
	v_mfma_f32_16x16x32_bf16 v[24:27], v[202:205], v[218:221], v[24:27]
	v_mfma_f32_16x16x32_bf16 v[16:19], v[194:197], v[226:229], v[16:19]
	v_mfma_f32_16x16x32_bf16 v[8:11], v[202:205], v[226:229], v[8:11]
	v_mfma_f32_16x16x32_bf16 v[4:7], v[194:197], v[234:237], v[4:7]
	v_mfma_f32_16x16x32_bf16 v[0:3], v[202:205], v[234:237], v[0:3]
	s_barrier
	s_add_i32 s74, 0, 0x18000
	v_add_u32_e32 v173, s74, v168
	s_add_i32 s75, 0, 0x1c000
	ds_read_b128 v[174:177], v173
	ds_read_b128 v[178:181], v173 offset:1024
	ds_read_b128 v[182:185], v173 offset:2048
	ds_read_b128 v[186:189], v173 offset:3072
	v_add_u32_e32 v173, s75, v168
	ds_read_b128 v[190:193], v173
	ds_read_b128 v[194:197], v173 offset:1024
	ds_read_b128 v[198:201], v173 offset:2048
	ds_read_b128 v[202:205], v173 offset:3072
	s_add_u32 s40, s40, 0x40000
	s_addc_u32 s41, s41, 0
	s_mov_b32 m0, s53
	v_lshl_add_u64 v[244:245], s[40:41], 0, v[134:135]
	ds_read_b128 v[206:209], v172 offset:32768
	ds_read_b128 v[210:213], v172 offset:33792
	ds_read_b128 v[214:217], v172 offset:34816
	ds_read_b128 v[218:221], v172 offset:35840
	ds_read_b128 v[222:225], v172 offset:36864
	ds_read_b128 v[226:229], v172 offset:37888
	ds_read_b128 v[230:233], v172 offset:38912
	ds_read_b128 v[234:237], v172 offset:39936
	global_load_lds_dwordx4 v[244:245], off
	v_lshl_add_u64 v[244:245], s[40:41], 0, v[130:131]
	s_mov_b32 m0, s56
	s_nop 0
	global_load_lds_dwordx4 v[244:245], off
	s_waitcnt vmcnt(8)
	s_waitcnt lgkmcnt(0)
	s_barrier
	s_waitcnt lgkmcnt(0)
	v_mfma_f32_16x16x32_bf16 v[124:127], v[174:177], v[206:209], v[124:127]
	v_mfma_f32_16x16x32_bf16 v[120:123], v[182:185], v[206:209], v[120:123]
	v_mfma_f32_16x16x32_bf16 v[116:119], v[174:177], v[214:217], v[116:119]
	v_mfma_f32_16x16x32_bf16 v[108:111], v[182:185], v[214:217], v[108:111]
	v_mfma_f32_16x16x32_bf16 v[100:103], v[174:177], v[222:225], v[100:103]
	v_mfma_f32_16x16x32_bf16 v[92:95], v[182:185], v[222:225], v[92:95]
	v_mfma_f32_16x16x32_bf16 v[84:87], v[174:177], v[230:233], v[84:87]
	v_mfma_f32_16x16x32_bf16 v[76:79], v[182:185], v[230:233], v[76:79]
	v_mfma_f32_16x16x32_bf16 v[124:127], v[178:181], v[210:213], v[124:127]
	v_mfma_f32_16x16x32_bf16 v[120:123], v[186:189], v[210:213], v[120:123]
	v_mfma_f32_16x16x32_bf16 v[116:119], v[178:181], v[218:221], v[116:119]
	v_mfma_f32_16x16x32_bf16 v[108:111], v[186:189], v[218:221], v[108:111]
	v_mfma_f32_16x16x32_bf16 v[100:103], v[178:181], v[226:229], v[100:103]
	v_mfma_f32_16x16x32_bf16 v[92:95], v[186:189], v[226:229], v[92:95]
	v_mfma_f32_16x16x32_bf16 v[84:87], v[178:181], v[234:237], v[84:87]
	v_mfma_f32_16x16x32_bf16 v[76:79], v[186:189], v[234:237], v[76:79]
	v_mfma_f32_16x16x32_bf16 v[112:115], v[190:193], v[206:209], v[112:115]
	v_mfma_f32_16x16x32_bf16 v[104:107], v[198:201], v[206:209], v[104:107]
	v_mfma_f32_16x16x32_bf16 v[96:99], v[190:193], v[214:217], v[96:99]
	v_mfma_f32_16x16x32_bf16 v[88:91], v[198:201], v[214:217], v[88:91]
	v_mfma_f32_16x16x32_bf16 v[80:83], v[190:193], v[222:225], v[80:83]
	v_mfma_f32_16x16x32_bf16 v[72:75], v[198:201], v[222:225], v[72:75]
	v_mfma_f32_16x16x32_bf16 v[68:71], v[190:193], v[230:233], v[68:71]
	v_mfma_f32_16x16x32_bf16 v[64:67], v[198:201], v[230:233], v[64:67]
	v_mfma_f32_16x16x32_bf16 v[112:115], v[194:197], v[210:213], v[112:115]
	v_mfma_f32_16x16x32_bf16 v[104:107], v[202:205], v[210:213], v[104:107]
	v_mfma_f32_16x16x32_bf16 v[96:99], v[194:197], v[218:221], v[96:99]
	v_mfma_f32_16x16x32_bf16 v[88:91], v[202:205], v[218:221], v[88:91]
	v_mfma_f32_16x16x32_bf16 v[80:83], v[194:197], v[226:229], v[80:83]
	v_mfma_f32_16x16x32_bf16 v[72:75], v[202:205], v[226:229], v[72:75]
	v_mfma_f32_16x16x32_bf16 v[68:71], v[194:197], v[234:237], v[68:71]
	v_mfma_f32_16x16x32_bf16 v[64:67], v[202:205], v[234:237], v[64:67]
	s_barrier
; #define PG8_STAGE(bufoff, gbase, voff) do { _Pragma("unroll") for (int _i = 0; _i < 2; ++_i) \
;         __builtin_amdgcn_global_load_lds((const unsigned*)((const char*)(gbase) + (voff)[_i]), (PG8_LAS unsigned*)(lds + (bufoff) + ldsw + _i * 8192), 16, 0, 0); } while (0)
; #define PG8_LDA(dst, b, h) do { _Pragma("unroll") for (int m = 0; m < 4; ++m) _Pragma("unroll") for (int k = 0; k < 2; ++k) dst[m][k] = *(const PG8_LAS bf16x8*)(lds + PG8_SA(b, h) + aoff + m * 2048 + k * 1024); } while (0)
; #define PG8_MMA(ai, bj, At, Bt) do { __builtin_amdgcn_s_setprio(1); _Pragma("unroll") for (int m = 0; m < 4; ++m) _Pragma("unroll") for (int n = 0; n < 2; ++n) _Pragma("unroll") for (int k = 0; k < 2; ++k) \
;         acc[ai][bj][m][n] = __builtin_amdgcn_mfma_f32_16x16x32_bf16(Bt[n][k], At[m][k], acc[ai][bj][m][n], 0, 0, 0); __builtin_amdgcn_s_setprio(0); } while (0)
; #define PG8_WAIT_V(n) asm volatile("s_waitcnt vmcnt(" #n ")" ::: "memory")
; #define PG8_WAIT_L(n) asm volatile("s_waitcnt lgkmcnt(" #n ")" ::: "memory")
; #define PG8_BAR __builtin_amdgcn_s_barrier()
; #define PG8_SCHED __builtin_amdgcn_sched_barrier(0)
; template <class Epi, class Sched, bool ALIGN_EPI = false, bool SP2 = false>
; __device__ __forceinline__ void gemm_phase(PG8_LAS unsigned char* lds, const Gemm g, const Sched& S, const Epi& E, const int tid_in) {
;     ...
;             PG8_WAIT_V(8); PG8_WAIT_L(0); PG8_BAR; PG8_MMA(0, 0, At, B0); PG8_MMA(0, 1, At, B1); PG8_BAR; PG8_SCHED;
;             PG8_LDA(At, 1, 1); PG8_STAGE(PG8_SB(1, 0), b3, voffB); PG8_STAGE(PG8_SB(1, 1), b3 + hstep, voffB); PG8_STAGE(PG8_SA(1, 0), a3, voffA);
;             PG8_WAIT_V(8); PG8_WAIT_L(0); PG8_BAR; PG8_MMA(1, 0, At, B0); PG8_MMA(1, 1, At, B1); PG8_BAR; PG8_SCHED;
	s_add_i32 s40, s74, s51
	v_lshl_add_u64 v[144:145], v[144:145], 0, s[16:17]
	s_mov_b32 m0, s40
	ds_read_b128 v[206:209], v172 offset:49152
	ds_read_b128 v[210:213], v172 offset:50176
	ds_read_b128 v[214:217], v172 offset:51200
	ds_read_b128 v[218:221], v172 offset:52224
	ds_read_b128 v[222:225], v172 offset:53248
	ds_read_b128 v[226:229], v172 offset:54272
	ds_read_b128 v[230:233], v172 offset:55296
	ds_read_b128 v[234:237], v172 offset:56320
	global_load_lds_dwordx4 v[144:145], off
	s_add_i32 m0, s40, 0x2000
	s_add_u32 s38, s38, 0x40080
	v_lshl_add_u64 v[144:145], v[238:239], 0, s[16:17]
	s_addc_u32 s39, s39, 0
	s_add_i32 s40, s75, s51
	global_load_lds_dwordx4 v[144:145], off
	v_lshl_add_u64 v[144:145], s[38:39], 0, v[132:133]
	s_mov_b32 m0, s40
	s_nop 0
	global_load_lds_dwordx4 v[144:145], off
	v_lshl_add_u64 v[144:145], s[38:39], 0, v[128:129]
	s_add_i32 m0, s40, 0x2000
	s_nop 0
	global_load_lds_dwordx4 v[144:145], off
	v_lshl_add_u64 v[144:145], v[240:241], 0, s[16:17]
	s_mov_b32 m0, s59
	s_nop 0
	global_load_lds_dwordx4 v[144:145], off
	v_lshl_add_u64 v[144:145], v[242:243], 0, s[16:17]
	s_mov_b32 m0, s60
	s_nop 0
	global_load_lds_dwordx4 v[144:145], off
	s_waitcnt vmcnt(8)
	s_waitcnt lgkmcnt(0)
	s_barrier
	s_waitcnt lgkmcnt(0)
	v_mfma_f32_16x16x32_bf16 v[60:63], v[174:177], v[206:209], v[60:63]
	v_mfma_f32_16x16x32_bf16 v[56:59], v[182:185], v[206:209], v[56:59]
	v_mfma_f32_16x16x32_bf16 v[52:55], v[174:177], v[214:217], v[52:55]
	v_mfma_f32_16x16x32_bf16 v[44:47], v[182:185], v[214:217], v[44:47]
	v_mfma_f32_16x16x32_bf16 v[36:39], v[174:177], v[222:225], v[36:39]
	v_mfma_f32_16x16x32_bf16 v[28:31], v[182:185], v[222:225], v[28:31]
	v_mfma_f32_16x16x32_bf16 v[20:23], v[174:177], v[230:233], v[20:23]
	v_mfma_f32_16x16x32_bf16 v[12:15], v[182:185], v[230:233], v[12:15]
	v_mfma_f32_16x16x32_bf16 v[60:63], v[178:181], v[210:213], v[60:63]
	v_mfma_f32_16x16x32_bf16 v[56:59], v[186:189], v[210:213], v[56:59]
	v_mfma_f32_16x16x32_bf16 v[52:55], v[178:181], v[218:221], v[52:55]
	v_mfma_f32_16x16x32_bf16 v[44:47], v[186:189], v[218:221], v[44:47]
	v_mfma_f32_16x16x32_bf16 v[36:39], v[178:181], v[226:229], v[36:39]
	v_mfma_f32_16x16x32_bf16 v[28:31], v[186:189], v[226:229], v[28:31]
	v_mfma_f32_16x16x32_bf16 v[20:23], v[178:181], v[234:237], v[20:23]
	v_mfma_f32_16x16x32_bf16 v[12:15], v[186:189], v[234:237], v[12:15]
	v_mfma_f32_16x16x32_bf16 v[48:51], v[190:193], v[206:209], v[48:51]
	v_mfma_f32_16x16x32_bf16 v[40:43], v[198:201], v[206:209], v[40:43]
	v_mfma_f32_16x16x32_bf16 v[32:35], v[190:193], v[214:217], v[32:35]
	v_mfma_f32_16x16x32_bf16 v[24:27], v[198:201], v[214:217], v[24:27]
	v_mfma_f32_16x16x32_bf16 v[16:19], v[190:193], v[222:225], v[16:19]
	v_mfma_f32_16x16x32_bf16 v[8:11], v[198:201], v[222:225], v[8:11]
	v_mfma_f32_16x16x32_bf16 v[4:7], v[190:193], v[230:233], v[4:7]
	v_mfma_f32_16x16x32_bf16 v[0:3], v[198:201], v[230:233], v[0:3]
	v_mfma_f32_16x16x32_bf16 v[48:51], v[194:197], v[210:213], v[48:51]
	v_mfma_f32_16x16x32_bf16 v[40:43], v[202:205], v[210:213], v[40:43]
	v_mfma_f32_16x16x32_bf16 v[32:35], v[194:197], v[218:221], v[32:35]
	v_mfma_f32_16x16x32_bf16 v[24:27], v[202:205], v[218:221], v[24:27]
	v_mfma_f32_16x16x32_bf16 v[16:19], v[194:197], v[226:229], v[16:19]
	v_mfma_f32_16x16x32_bf16 v[8:11], v[202:205], v[226:229], v[8:11]
	v_mfma_f32_16x16x32_bf16 v[4:7], v[194:197], v[234:237], v[4:7]
	v_mfma_f32_16x16x32_bf16 v[0:3], v[202:205], v[234:237], v[0:3]
	s_barrier
	s_add_i32 s73, s73, 2
	s_add_u32 s0, s0, 0x100
	s_addc_u32 s1, s1, 0
	s_add_u32 s71, s71, 0x100
	s_addc_u32 s72, s72, 0
	s_cmp_gt_u32 s73, 13
	s_cbranch_scc0 .LBB0_535
	s_and_b64 vcc, exec, s[18:19]
	s_cbranch_vccz .LBB0_538
	s_barrier

; #define PG8_STAGE(bufoff, gbase, voff) do { _Pragma("unroll") for (int _i = 0; _i < 2; ++_i) \
;         __builtin_amdgcn_global_load_lds((const unsigned*)((const char*)(gbase) + (voff)[_i]), (PG8_LAS unsigned*)(lds + (bufoff) + ldsw + _i * 8192), 16, 0, 0); } while (0)
; #define PG8_LDA(dst, b, h) do { _Pragma("unroll") for (int m = 0; m < 4; ++m) _Pragma("unroll") for (int k = 0; k < 2; ++k) dst[m][k] = *(const PG8_LAS bf16x8*)(lds + PG8_SA(b, h) + aoff + m * 2048 + k * 1024); } while (0)
; #define PG8_LDB(dst, b, h) do { _Pragma("unroll") for (int n = 0; n < 2; ++n) _Pragma("unroll") for (int k = 0; k < 2; ++k) dst[n][k] = *(const PG8_LAS bf16x8*)(lds + PG8_SB(b, h) + boff + n * 2048 + k * 1024); } while (0)
; #define PG8_MMA(ai, bj, At, Bt) do { __builtin_amdgcn_s_setprio(1); _Pragma("unroll") for (int m = 0; m < 4; ++m) _Pragma("unroll") for (int n = 0; n < 2; ++n) _Pragma("unroll") for (int k = 0; k < 2; ++k) \
;         acc[ai][bj][m][n] = __builtin_amdgcn_mfma_f32_16x16x32_bf16(Bt[n][k], At[m][k], acc[ai][bj][m][n], 0, 0, 0); __builtin_amdgcn_s_setprio(0); } while (0)
; #define PG8_WAIT_V(n) asm volatile("s_waitcnt vmcnt(" #n ")" ::: "memory")
; #define PG8_WAIT_L(n) asm volatile("s_waitcnt lgkmcnt(" #n ")" ::: "memory")
; #define PG8_BAR __builtin_amdgcn_s_barrier()
; #define PG8_SCHED __builtin_amdgcn_sched_barrier(0)
; template <class Epi, class Sched, bool ALIGN_EPI = false, bool SP2 = false>
; __device__ __forceinline__ void gemm_phase(PG8_LAS unsigned char* lds, const Gemm g, const Sched& S, const Epi& E, const int tid_in) {
;     ...
;             PG8_LDB(B0, 0, 0); PG8_LDB(B1, 0, 1); PG8_SCHED; PG8_LDA(At, 0, 0); PG8_STAGE(PG8_SA(1, 1), a1 + hstep, voffA);
;             PG8_WAIT_V(8); PG8_WAIT_L(0); PG8_BAR; PG8_MMA(0, 0, At, B0); PG8_MMA(0, 1, At, B1); PG8_BAR; PG8_SCHED;
;             PG8_LDA(At, 0, 1); PG8_STAGE(PG8_SB(0, 0), b2, voffB); PG8_STAGE(PG8_SB(0, 1), b2 + hstep, voffB); PG8_STAGE(PG8_SA(0, 0), a2, voffA);
.LBB0_555:
	ds_read_b128 v[158:161], v146
	ds_read_b128 v[162:165], v146 offset:1024
	ds_read_b128 v[166:169], v146 offset:2048
	ds_read_b128 v[170:173], v146 offset:3072
	ds_read_b128 v[174:177], v147
	ds_read_b128 v[178:181], v147 offset:1024
	ds_read_b128 v[182:185], v147 offset:2048
	ds_read_b128 v[186:189], v147 offset:3072
	s_add_u32 s34, s0, 0xfffc0080
	s_addc_u32 s35, s1, -1
	s_cmp_eq_u32 s61, 12
	s_cselect_b32 s37, s27, s35
	s_cselect_b32 s36, s26, s34
	s_cselect_b32 s35, s23, s60
	s_cselect_b32 s34, s25, s59
	v_lshl_add_u64 v[144:145], s[0:1], 0, v[136:137]
	s_add_i32 m0, s31, 0xc000
	ds_read_b128 v[190:193], v148
	ds_read_b128 v[194:197], v148 offset:1024
	ds_read_b128 v[198:201], v148 offset:2048
	ds_read_b128 v[202:205], v148 offset:3072
	ds_read_b128 v[206:209], v148 offset:4096
	ds_read_b128 v[210:213], v148 offset:5120
	ds_read_b128 v[214:217], v148 offset:6144
	ds_read_b128 v[218:221], v148 offset:7168
	global_load_lds_dwordx4 v[144:145], off
	v_lshl_add_u64 v[144:145], s[0:1], 0, v[138:139]
	s_add_i32 m0, s31, 0xe000
	s_nop 0
	global_load_lds_dwordx4 v[144:145], off
	s_waitcnt vmcnt(8)
	s_waitcnt lgkmcnt(0)
	s_barrier
	s_waitcnt lgkmcnt(0)
	v_mfma_f32_16x16x32_bf16 v[124:127], v[158:161], v[190:193], v[124:127]
	v_mfma_f32_16x16x32_bf16 v[120:123], v[166:169], v[190:193], v[120:123]
	v_mfma_f32_16x16x32_bf16 v[116:119], v[158:161], v[198:201], v[116:119]
	v_mfma_f32_16x16x32_bf16 v[108:111], v[166:169], v[198:201], v[108:111]
	v_mfma_f32_16x16x32_bf16 v[100:103], v[158:161], v[206:209], v[100:103]
	v_mfma_f32_16x16x32_bf16 v[92:95], v[166:169], v[206:209], v[92:95]
	v_mfma_f32_16x16x32_bf16 v[84:87], v[158:161], v[214:217], v[84:87]
	v_mfma_f32_16x16x32_bf16 v[76:79], v[166:169], v[214:217], v[76:79]
	v_mfma_f32_16x16x32_bf16 v[124:127], v[162:165], v[194:197], v[124:127]
	v_mfma_f32_16x16x32_bf16 v[120:123], v[170:173], v[194:197], v[120:123]
	v_mfma_f32_16x16x32_bf16 v[116:119], v[162:165], v[202:205], v[116:119]
	v_mfma_f32_16x16x32_bf16 v[108:111], v[170:173], v[202:205], v[108:111]
	v_mfma_f32_16x16x32_bf16 v[100:103], v[162:165], v[210:213], v[100:103]
	v_mfma_f32_16x16x32_bf16 v[92:95], v[170:173], v[210:213], v[92:95]
	v_mfma_f32_16x16x32_bf16 v[84:87], v[162:165], v[218:221], v[84:87]
	v_mfma_f32_16x16x32_bf16 v[76:79], v[170:173], v[218:221], v[76:79]
	v_mfma_f32_16x16x32_bf16 v[112:115], v[174:177], v[190:193], v[112:115]
	v_mfma_f32_16x16x32_bf16 v[104:107], v[182:185], v[190:193], v[104:107]
	v_mfma_f32_16x16x32_bf16 v[96:99], v[174:177], v[198:201], v[96:99]
	v_mfma_f32_16x16x32_bf16 v[88:91], v[182:185], v[198:201], v[88:91]
	v_mfma_f32_16x16x32_bf16 v[80:83], v[174:177], v[206:209], v[80:83]
	v_mfma_f32_16x16x32_bf16 v[72:75], v[182:185], v[206:209], v[72:75]
	v_mfma_f32_16x16x32_bf16 v[68:71], v[174:177], v[214:217], v[68:71]
	v_mfma_f32_16x16x32_bf16 v[64:67], v[182:185], v[214:217], v[64:67]
	v_mfma_f32_16x16x32_bf16 v[112:115], v[178:181], v[194:197], v[112:115]
	v_mfma_f32_16x16x32_bf16 v[104:107], v[186:189], v[194:197], v[104:107]
	v_mfma_f32_16x16x32_bf16 v[96:99], v[178:181], v[202:205], v[96:99]
	v_mfma_f32_16x16x32_bf16 v[88:91], v[186:189], v[202:205], v[88:91]
	v_mfma_f32_16x16x32_bf16 v[80:83], v[178:181], v[210:213], v[80:83]
	v_mfma_f32_16x16x32_bf16 v[72:75], v[186:189], v[210:213], v[72:75]
	v_mfma_f32_16x16x32_bf16 v[68:71], v[178:181], v[218:221], v[68:71]
	v_mfma_f32_16x16x32_bf16 v[64:67], v[186:189], v[218:221], v[64:67]
	s_barrier
	s_add_i32 s62, s56, s45
	v_lshl_add_u64 v[144:145], s[34:35], 0, v[132:133]
	s_mov_b32 m0, s62
	ds_read_b128 v[190:193], v148 offset:16384
	ds_read_b128 v[194:197], v148 offset:17408
	ds_read_b128 v[198:201], v148 offset:18432
	ds_read_b128 v[202:205], v148 offset:19456
	ds_read_b128 v[206:209], v148 offset:20480
	ds_read_b128 v[210:213], v148 offset:21504
	ds_read_b128 v[214:217], v148 offset:22528
	ds_read_b128 v[218:221], v148 offset:23552
	global_load_lds_dwordx4 v[144:145], off
	s_add_i32 m0, s62, 0x2000
	s_add_u32 s62, s34, 0x40000
	v_lshl_add_u64 v[150:151], s[34:35], 0, v[128:129]
	s_addc_u32 s63, s35, 0
	s_add_i32 s64, s57, s45
	global_load_lds_dwordx4 v[150:151], off
	v_lshl_add_u64 v[154:155], s[62:63], 0, v[132:133]
	s_mov_b32 m0, s64
	v_lshl_add_u64 v[222:223], s[36:37], 0, v[130:131]
	global_load_lds_dwordx4 v[154:155], off
	v_lshl_add_u64 v[154:155], s[62:63], 0, v[128:129]
	s_add_i32 m0, s64, 0x2000
	s_nop 0
	global_load_lds_dwordx4 v[154:155], off
	v_lshl_add_u64 v[154:155], s[36:37], 0, v[134:135]
	s_mov_b32 m0, s31
	s_nop 0
	global_load_lds_dwordx4 v[154:155], off
	s_mov_b32 m0, s43
	s_nop 0
	global_load_lds_dwordx4 v[222:223], off
	s_waitcnt vmcnt(8)
	s_waitcnt lgkmcnt(0)
	s_barrier
; #define PG8_STAGE(bufoff, gbase, voff) do { _Pragma("unroll") for (int _i = 0; _i < 2; ++_i) \
;         __builtin_amdgcn_global_load_lds((const unsigned*)((const char*)(gbase) + (voff)[_i]), (PG8_LAS unsigned*)(lds + (bufoff) + ldsw + _i * 8192), 16, 0, 0); } while (0)
; #define PG8_LDA(dst, b, h) do { _Pragma("unroll") for (int m = 0; m < 4; ++m) _Pragma("unroll") for (int k = 0; k < 2; ++k) dst[m][k] = *(const PG8_LAS bf16x8*)(lds + PG8_SA(b, h) + aoff + m * 2048 + k * 1024); } while (0)
; #define PG8_LDB(dst, b, h) do { _Pragma("unroll") for (int n = 0; n < 2; ++n) _Pragma("unroll") for (int k = 0; k < 2; ++k) dst[n][k] = *(const PG8_LAS bf16x8*)(lds + PG8_SB(b, h) + boff + n * 2048 + k * 1024); } while (0)
; #define PG8_MMA(ai, bj, At, Bt) do { __builtin_amdgcn_s_setprio(1); _Pragma("unroll") for (int m = 0; m < 4; ++m) _Pragma("unroll") for (int n = 0; n < 2; ++n) _Pragma("unroll") for (int k = 0; k < 2; ++k) \
;         acc[ai][bj][m][n] = __builtin_amdgcn_mfma_f32_16x16x32_bf16(Bt[n][k], At[m][k], acc[ai][bj][m][n], 0, 0, 0); __builtin_amdgcn_s_setprio(0); } while (0)
; #define PG8_WAIT_V(n) asm volatile("s_waitcnt vmcnt(" #n ")" ::: "memory")
; #define PG8_WAIT_L(n) asm volatile("s_waitcnt lgkmcnt(" #n ")" ::: "memory")
; #define PG8_BAR __builtin_amdgcn_s_barrier()
; #define PG8_SCHED __builtin_amdgcn_sched_barrier(0)
; template <class Epi, class Sched, bool ALIGN_EPI = false, bool SP2 = false>
; __device__ __forceinline__ void gemm_phase(PG8_LAS unsigned char* lds, const Gemm g, const Sched& S, const Epi& E, const int tid_in) {
;     ...
;             PG8_WAIT_V(8); PG8_WAIT_L(0); PG8_BAR; PG8_MMA(1, 0, At, B0); PG8_MMA(1, 1, At, B1); PG8_BAR; PG8_SCHED;
;             PG8_LDB(B0, 1, 0); PG8_LDB(B1, 1, 1); PG8_SCHED; PG8_LDA(At, 1, 0); PG8_STAGE(PG8_SA(0, 1), a2 + hstep, voffA);
;             PG8_WAIT_V(8); PG8_WAIT_L(0); PG8_BAR; PG8_MMA(0, 0, At, B0); PG8_MMA(0, 1, At, B1); PG8_BAR; PG8_SCHED;
	s_waitcnt lgkmcnt(0)
	v_mfma_f32_16x16x32_bf16 v[60:63], v[158:161], v[190:193], v[60:63]
	v_mfma_f32_16x16x32_bf16 v[56:59], v[166:169], v[190:193], v[56:59]
	v_mfma_f32_16x16x32_bf16 v[52:55], v[158:161], v[198:201], v[52:55]
	v_mfma_f32_16x16x32_bf16 v[44:47], v[166:169], v[198:201], v[44:47]
	v_mfma_f32_16x16x32_bf16 v[36:39], v[158:161], v[206:209], v[36:39]
	v_mfma_f32_16x16x32_bf16 v[28:31], v[166:169], v[206:209], v[28:31]
	v_mfma_f32_16x16x32_bf16 v[20:23], v[158:161], v[214:217], v[20:23]
	v_mfma_f32_16x16x32_bf16 v[12:15], v[166:169], v[214:217], v[12:15]
	v_mfma_f32_16x16x32_bf16 v[60:63], v[162:165], v[194:197], v[60:63]
	v_mfma_f32_16x16x32_bf16 v[56:59], v[170:173], v[194:197], v[56:59]
	v_mfma_f32_16x16x32_bf16 v[52:55], v[162:165], v[202:205], v[52:55]
	v_mfma_f32_16x16x32_bf16 v[44:47], v[170:173], v[202:205], v[44:47]
	v_mfma_f32_16x16x32_bf16 v[36:39], v[162:165], v[210:213], v[36:39]
	v_mfma_f32_16x16x32_bf16 v[28:31], v[170:173], v[210:213], v[28:31]
	v_mfma_f32_16x16x32_bf16 v[20:23], v[162:165], v[218:221], v[20:23]
	v_mfma_f32_16x16x32_bf16 v[12:15], v[170:173], v[218:221], v[12:15]
	v_mfma_f32_16x16x32_bf16 v[48:51], v[174:177], v[190:193], v[48:51]
	v_mfma_f32_16x16x32_bf16 v[40:43], v[182:185], v[190:193], v[40:43]
	v_mfma_f32_16x16x32_bf16 v[32:35], v[174:177], v[198:201], v[32:35]
	v_mfma_f32_16x16x32_bf16 v[24:27], v[182:185], v[198:201], v[24:27]
	v_mfma_f32_16x16x32_bf16 v[16:19], v[174:177], v[206:209], v[16:19]
	v_mfma_f32_16x16x32_bf16 v[8:11], v[182:185], v[206:209], v[8:11]
	v_mfma_f32_16x16x32_bf16 v[4:7], v[174:177], v[214:217], v[4:7]
	v_mfma_f32_16x16x32_bf16 v[0:3], v[182:185], v[214:217], v[0:3]
	v_mfma_f32_16x16x32_bf16 v[48:51], v[178:181], v[194:197], v[48:51]
	v_mfma_f32_16x16x32_bf16 v[40:43], v[186:189], v[194:197], v[40:43]
	v_mfma_f32_16x16x32_bf16 v[32:35], v[178:181], v[202:205], v[32:35]
	v_mfma_f32_16x16x32_bf16 v[24:27], v[186:189], v[202:205], v[24:27]
	v_mfma_f32_16x16x32_bf16 v[16:19], v[178:181], v[210:213], v[16:19]
	v_mfma_f32_16x16x32_bf16 v[8:11], v[186:189], v[210:213], v[8:11]
	v_mfma_f32_16x16x32_bf16 v[4:7], v[178:181], v[218:221], v[4:7]
	v_mfma_f32_16x16x32_bf16 v[0:3], v[186:189], v[218:221], v[0:3]
	s_barrier
	s_add_i32 s62, 0, 0x18000
	v_add_u32_e32 v149, s62, v153
	s_add_i32 s63, 0, 0x1c000
	ds_read_b128 v[158:161], v149
	ds_read_b128 v[162:165], v149 offset:1024
	ds_read_b128 v[166:169], v149 offset:2048
	ds_read_b128 v[170:173], v149 offset:3072
	v_add_u32_e32 v149, s63, v153
	ds_read_b128 v[174:177], v149
	ds_read_b128 v[178:181], v149 offset:1024
	ds_read_b128 v[182:185], v149 offset:2048
	ds_read_b128 v[186:189], v149 offset:3072
	s_add_u32 s36, s36, 0x40000
	s_addc_u32 s37, s37, 0
	s_mov_b32 m0, s44
	v_lshl_add_u64 v[224:225], s[36:37], 0, v[134:135]
	ds_read_b128 v[190:193], v148 offset:32768
	ds_read_b128 v[194:197], v148 offset:33792
	ds_read_b128 v[198:201], v148 offset:34816
	ds_read_b128 v[202:205], v148 offset:35840
	ds_read_b128 v[206:209], v148 offset:36864
	ds_read_b128 v[210:213], v148 offset:37888
	ds_read_b128 v[214:217], v148 offset:38912
	ds_read_b128 v[218:221], v148 offset:39936
	global_load_lds_dwordx4 v[224:225], off
	v_lshl_add_u64 v[224:225], s[36:37], 0, v[130:131]
	s_mov_b32 m0, s46
	s_nop 0
	global_load_lds_dwordx4 v[224:225], off
	s_waitcnt vmcnt(8)
	s_waitcnt lgkmcnt(0)
	s_barrier
	s_waitcnt lgkmcnt(0)
	v_mfma_f32_16x16x32_bf16 v[124:127], v[158:161], v[190:193], v[124:127]
	v_mfma_f32_16x16x32_bf16 v[120:123], v[166:169], v[190:193], v[120:123]
	v_mfma_f32_16x16x32_bf16 v[116:119], v[158:161], v[198:201], v[116:119]
	v_mfma_f32_16x16x32_bf16 v[108:111], v[166:169], v[198:201], v[108:111]
	v_mfma_f32_16x16x32_bf16 v[100:103], v[158:161], v[206:209], v[100:103]
	v_mfma_f32_16x16x32_bf16 v[92:95], v[166:169], v[206:209], v[92:95]
	v_mfma_f32_16x16x32_bf16 v[84:87], v[158:161], v[214:217], v[84:87]
	v_mfma_f32_16x16x32_bf16 v[76:79], v[166:169], v[214:217], v[76:79]
	v_mfma_f32_16x16x32_bf16 v[124:127], v[162:165], v[194:197], v[124:127]
	v_mfma_f32_16x16x32_bf16 v[120:123], v[170:173], v[194:197], v[120:123]
	v_mfma_f32_16x16x32_bf16 v[116:119], v[162:165], v[202:205], v[116:119]
	v_mfma_f32_16x16x32_bf16 v[108:111], v[170:173], v[202:205], v[108:111]
	v_mfma_f32_16x16x32_bf16 v[100:103], v[162:165], v[210:213], v[100:103]
	v_mfma_f32_16x16x32_bf16 v[92:95], v[170:173], v[210:213], v[92:95]
	v_mfma_f32_16x16x32_bf16 v[84:87], v[162:165], v[218:221], v[84:87]
	v_mfma_f32_16x16x32_bf16 v[76:79], v[170:173], v[218:221], v[76:79]
	v_mfma_f32_16x16x32_bf16 v[112:115], v[174:177], v[190:193], v[112:115]
	v_mfma_f32_16x16x32_bf16 v[104:107], v[182:185], v[190:193], v[104:107]
	v_mfma_f32_16x16x32_bf16 v[96:99], v[174:177], v[198:201], v[96:99]
	v_mfma_f32_16x16x32_bf16 v[88:91], v[182:185], v[198:201], v[88:91]
	v_mfma_f32_16x16x32_bf16 v[80:83], v[174:177], v[206:209], v[80:83]
	v_mfma_f32_16x16x32_bf16 v[72:75], v[182:185], v[206:209], v[72:75]
	v_mfma_f32_16x16x32_bf16 v[68:71], v[174:177], v[214:217], v[68:71]
	v_mfma_f32_16x16x32_bf16 v[64:67], v[182:185], v[214:217], v[64:67]
	v_mfma_f32_16x16x32_bf16 v[112:115], v[178:181], v[194:197], v[112:115]
	v_mfma_f32_16x16x32_bf16 v[104:107], v[186:189], v[194:197], v[104:107]
	v_mfma_f32_16x16x32_bf16 v[96:99], v[178:181], v[202:205], v[96:99]
	v_mfma_f32_16x16x32_bf16 v[88:91], v[186:189], v[202:205], v[88:91]
	v_mfma_f32_16x16x32_bf16 v[80:83], v[178:181], v[210:213], v[80:83]
	v_mfma_f32_16x16x32_bf16 v[72:75], v[186:189], v[210:213], v[72:75]
	v_mfma_f32_16x16x32_bf16 v[68:71], v[178:181], v[218:221], v[68:71]
	v_mfma_f32_16x16x32_bf16 v[64:67], v[186:189], v[218:221], v[64:67]
	s_barrier
; #define PG8_STAGE(bufoff, gbase, voff) do { _Pragma("unroll") for (int _i = 0; _i < 2; ++_i) \
;         __builtin_amdgcn_global_load_lds((const unsigned*)((const char*)(gbase) + (voff)[_i]), (PG8_LAS unsigned*)(lds + (bufoff) + ldsw + _i * 8192), 16, 0, 0); } while (0)
; #define PG8_LDA(dst, b, h) do { _Pragma("unroll") for (int m = 0; m < 4; ++m) _Pragma("unroll") for (int k = 0; k < 2; ++k) dst[m][k] = *(const PG8_LAS bf16x8*)(lds + PG8_SA(b, h) + aoff + m * 2048 + k * 1024); } while (0)
; #define PG8_MMA(ai, bj, At, Bt) do { __builtin_amdgcn_s_setprio(1); _Pragma("unroll") for (int m = 0; m < 4; ++m) _Pragma("unroll") for (int n = 0; n < 2; ++n) _Pragma("unroll") for (int k = 0; k < 2; ++k) \
;         acc[ai][bj][m][n] = __builtin_amdgcn_mfma_f32_16x16x32_bf16(Bt[n][k], At[m][k], acc[ai][bj][m][n], 0, 0, 0); __builtin_amdgcn_s_setprio(0); } while (0)
; #define PG8_WAIT_V(n) asm volatile("s_waitcnt vmcnt(" #n ")" ::: "memory")
; #define PG8_WAIT_L(n) asm volatile("s_waitcnt lgkmcnt(" #n ")" ::: "memory")
; #define PG8_BAR __builtin_amdgcn_s_barrier()
; #define PG8_SCHED __builtin_amdgcn_sched_barrier(0)
; template <class Epi, class Sched, bool ALIGN_EPI = false, bool SP2 = false>
; __device__ __forceinline__ void gemm_phase(PG8_LAS unsigned char* lds, const Gemm g, const Sched& S, const Epi& E, const int tid_in) {
;     ...
;             PG8_LDA(At, 1, 1); PG8_STAGE(PG8_SB(1, 0), b3, voffB); PG8_STAGE(PG8_SB(1, 1), b3 + hstep, voffB); PG8_STAGE(PG8_SA(1, 0), a3, voffA);
;             PG8_WAIT_V(8); PG8_WAIT_L(0); PG8_BAR; PG8_MMA(1, 0, At, B0); PG8_MMA(1, 1, At, B1); PG8_BAR; PG8_SCHED;
	s_add_i32 s36, s62, s45
	v_lshl_add_u64 v[144:145], v[144:145], 0, s[10:11]
	s_mov_b32 m0, s36
	ds_read_b128 v[190:193], v148 offset:49152
	ds_read_b128 v[194:197], v148 offset:50176
	ds_read_b128 v[198:201], v148 offset:51200
	ds_read_b128 v[202:205], v148 offset:52224
	ds_read_b128 v[206:209], v148 offset:53248
	ds_read_b128 v[210:213], v148 offset:54272
	ds_read_b128 v[214:217], v148 offset:55296
	ds_read_b128 v[218:221], v148 offset:56320
	global_load_lds_dwordx4 v[144:145], off
	s_add_i32 m0, s36, 0x2000
	s_add_u32 s34, s34, 0x40080
	v_lshl_add_u64 v[144:145], v[150:151], 0, s[10:11]
	s_addc_u32 s35, s35, 0
	s_add_i32 s36, s63, s45
	global_load_lds_dwordx4 v[144:145], off
	v_lshl_add_u64 v[144:145], s[34:35], 0, v[132:133]
	s_mov_b32 m0, s36
	s_nop 0
	global_load_lds_dwordx4 v[144:145], off
	v_lshl_add_u64 v[144:145], s[34:35], 0, v[128:129]
	s_add_i32 m0, s36, 0x2000
	s_nop 0
	global_load_lds_dwordx4 v[144:145], off
	v_lshl_add_u64 v[144:145], v[154:155], 0, s[10:11]
	s_mov_b32 m0, s52
	s_nop 0
	global_load_lds_dwordx4 v[144:145], off
	v_lshl_add_u64 v[144:145], v[222:223], 0, s[10:11]
	s_mov_b32 m0, s53
	s_nop 0
	global_load_lds_dwordx4 v[144:145], off
	s_waitcnt vmcnt(8)
	s_waitcnt lgkmcnt(0)
	s_barrier
	s_waitcnt lgkmcnt(0)
	v_mfma_f32_16x16x32_bf16 v[60:63], v[158:161], v[190:193], v[60:63]
	v_mfma_f32_16x16x32_bf16 v[56:59], v[166:169], v[190:193], v[56:59]
	v_mfma_f32_16x16x32_bf16 v[52:55], v[158:161], v[198:201], v[52:55]
	v_mfma_f32_16x16x32_bf16 v[44:47], v[166:169], v[198:201], v[44:47]
	v_mfma_f32_16x16x32_bf16 v[36:39], v[158:161], v[206:209], v[36:39]
	v_mfma_f32_16x16x32_bf16 v[28:31], v[166:169], v[206:209], v[28:31]
	v_mfma_f32_16x16x32_bf16 v[20:23], v[158:161], v[214:217], v[20:23]
	v_mfma_f32_16x16x32_bf16 v[12:15], v[166:169], v[214:217], v[12:15]
	v_mfma_f32_16x16x32_bf16 v[60:63], v[162:165], v[194:197], v[60:63]
	v_mfma_f32_16x16x32_bf16 v[56:59], v[170:173], v[194:197], v[56:59]
	v_mfma_f32_16x16x32_bf16 v[52:55], v[162:165], v[202:205], v[52:55]
	v_mfma_f32_16x16x32_bf16 v[44:47], v[170:173], v[202:205], v[44:47]
	v_mfma_f32_16x16x32_bf16 v[36:39], v[162:165], v[210:213], v[36:39]
	v_mfma_f32_16x16x32_bf16 v[28:31], v[170:173], v[210:213], v[28:31]
	v_mfma_f32_16x16x32_bf16 v[20:23], v[162:165], v[218:221], v[20:23]
	v_mfma_f32_16x16x32_bf16 v[12:15], v[170:173], v[218:221], v[12:15]
	v_mfma_f32_16x16x32_bf16 v[48:51], v[174:177], v[190:193], v[48:51]
	v_mfma_f32_16x16x32_bf16 v[40:43], v[182:185], v[190:193], v[40:43]
	v_mfma_f32_16x16x32_bf16 v[32:35], v[174:177], v[198:201], v[32:35]
	v_mfma_f32_16x16x32_bf16 v[24:27], v[182:185], v[198:201], v[24:27]
	v_mfma_f32_16x16x32_bf16 v[16:19], v[174:177], v[206:209], v[16:19]
	v_mfma_f32_16x16x32_bf16 v[8:11], v[182:185], v[206:209], v[8:11]
	v_mfma_f32_16x16x32_bf16 v[4:7], v[174:177], v[214:217], v[4:7]
	v_mfma_f32_16x16x32_bf16 v[0:3], v[182:185], v[214:217], v[0:3]
	v_mfma_f32_16x16x32_bf16 v[48:51], v[178:181], v[194:197], v[48:51]
	v_mfma_f32_16x16x32_bf16 v[40:43], v[186:189], v[194:197], v[40:43]
	v_mfma_f32_16x16x32_bf16 v[32:35], v[178:181], v[202:205], v[32:35]
	v_mfma_f32_16x16x32_bf16 v[24:27], v[186:189], v[202:205], v[24:27]
	v_mfma_f32_16x16x32_bf16 v[16:19], v[178:181], v[210:213], v[16:19]
	v_mfma_f32_16x16x32_bf16 v[8:11], v[186:189], v[210:213], v[8:11]
	v_mfma_f32_16x16x32_bf16 v[4:7], v[178:181], v[218:221], v[4:7]
	v_mfma_f32_16x16x32_bf16 v[0:3], v[186:189], v[218:221], v[0:3]
	s_barrier
	s_add_i32 s61, s61, 2
	s_add_u32 s0, s0, 0x100
	s_addc_u32 s1, s1, 0
	s_add_u32 s59, s59, 0x100
	s_addc_u32 s60, s60, 0
	s_cmp_gt_u32 s61, 13
	s_cbranch_scc0 .LBB0_555
	s_and_b64 vcc, exec, s[12:13]
	s_cbranch_vccz .LBB0_558
	s_barrier

; #define PG8_STAGE(bufoff, gbase, voff) do { _Pragma("unroll") for (int _i = 0; _i < 2; ++_i) \
;         __builtin_amdgcn_global_load_lds((const unsigned*)((const char*)(gbase) + (voff)[_i]), (PG8_LAS unsigned*)(lds + (bufoff) + ldsw + _i * 8192), 16, 0, 0); } while (0)
; #define PG8_LDA(dst, b, h) do { _Pragma("unroll") for (int m = 0; m < 4; ++m) _Pragma("unroll") for (int k = 0; k < 2; ++k) dst[m][k] = *(const PG8_LAS bf16x8*)(lds + PG8_SA(b, h) + aoff + m * 2048 + k * 1024); } while (0)
; #define PG8_LDB(dst, b, h) do { _Pragma("unroll") for (int n = 0; n < 2; ++n) _Pragma("unroll") for (int k = 0; k < 2; ++k) dst[n][k] = *(const PG8_LAS bf16x8*)(lds + PG8_SB(b, h) + boff + n * 2048 + k * 1024); } while (0)
; #define PG8_MMA(ai, bj, At, Bt) do { __builtin_amdgcn_s_setprio(1); _Pragma("unroll") for (int m = 0; m < 4; ++m) _Pragma("unroll") for (int n = 0; n < 2; ++n) _Pragma("unroll") for (int k = 0; k < 2; ++k) \
;         acc[ai][bj][m][n] = __builtin_amdgcn_mfma_f32_16x16x32_bf16(Bt[n][k], At[m][k], acc[ai][bj][m][n], 0, 0, 0); __builtin_amdgcn_s_setprio(0); } while (0)
; #define PG8_WAIT_V(n) asm volatile("s_waitcnt vmcnt(" #n ")" ::: "memory")
; #define PG8_WAIT_L(n) asm volatile("s_waitcnt lgkmcnt(" #n ")" ::: "memory")
; #define PG8_BAR __builtin_amdgcn_s_barrier()
; #define PG8_SCHED __builtin_amdgcn_sched_barrier(0)
; template <class Epi, class Sched, bool ALIGN_EPI = false, bool SP2 = false>
; __device__ __forceinline__ void gemm_phase(PG8_LAS unsigned char* lds, const Gemm g, const Sched& S, const Epi& E, const int tid_in) {
;     ...
;             const bool last = (t == nt - 2);
;             const char* a1 = cA + (size_t)(t + 1) * kstep;
;             const char* a2 = last ? nA : cA + (size_t)(t + 2) * kstep; const char* b2 = last ? nB : cB + (size_t)(t + 2) * kstep;
;             const char* a3 = a2 + kstep; const char* b3 = b2 + kstep;
;             if (last && has_next) S.a_ready(nxt);
;             if constexpr (SP2) {
;             PG8_LDB(B0, 0, 0); PG8_LDB(B1, 0, 1); PG8_SCHED; PG8_LDA(At, 0, 0); PG8_STAGE(PG8_SA(1, 1), a1 + hstep, voffA);
;             PG8_WAIT_V(8); PG8_WAIT_L(0); PG8_BAR; PG8_MMA(0, 0, At, B0); PG8_MMA(0, 1, At, B1); PG8_BAR; PG8_SCHED;
;             PG8_LDA(At, 0, 1); PG8_STAGE(PG8_SB(0, 0), b2, voffB); PG8_STAGE(PG8_SB(0, 1), b2 + hstep, voffB); PG8_STAGE(PG8_SA(0, 0), a2, voffA);
.LBB0_739:
	ds_read_b128 v[152:155], v149
	ds_read_b128 v[156:159], v149 offset:1024
	ds_read_b128 v[160:163], v149 offset:2048
	ds_read_b128 v[164:167], v149 offset:3072
	ds_read_b128 v[168:171], v150
	ds_read_b128 v[172:175], v150 offset:1024
	ds_read_b128 v[176:179], v150 offset:2048
	ds_read_b128 v[180:183], v150 offset:3072
	s_add_u32 s30, s0, 0xfffc0080
	s_addc_u32 s31, s1, -1
	s_cmp_eq_u32 s68, 12
	s_cselect_b32 s35, s23, s31
	s_cselect_b32 s34, s64, s30
	s_cselect_b32 s31, s21, s67
	s_cselect_b32 s30, s65, s66
	v_lshl_add_u64 v[144:145], s[0:1], 0, v[136:137]
	s_add_i32 m0, s29, 0xc000
	ds_read_b128 v[184:187], v151
	ds_read_b128 v[188:191], v151 offset:1024
	ds_read_b128 v[192:195], v151 offset:2048
	ds_read_b128 v[196:199], v151 offset:3072
	ds_read_b128 v[200:203], v151 offset:4096
	ds_read_b128 v[204:207], v151 offset:5120
	ds_read_b128 v[208:211], v151 offset:6144
	ds_read_b128 v[212:215], v151 offset:7168
	global_load_lds_dwordx4 v[144:145], off
	v_lshl_add_u64 v[144:145], s[0:1], 0, v[138:139]
	s_add_i32 m0, s29, 0xe000
	s_nop 0
	global_load_lds_dwordx4 v[144:145], off
	s_waitcnt vmcnt(8)
	s_waitcnt lgkmcnt(0)
	s_barrier
	s_waitcnt lgkmcnt(0)
	v_mfma_f32_16x16x32_bf16 v[124:127], v[152:155], v[184:187], v[124:127]
	v_mfma_f32_16x16x32_bf16 v[120:123], v[160:163], v[184:187], v[120:123]
	v_mfma_f32_16x16x32_bf16 v[116:119], v[152:155], v[192:195], v[116:119]
	v_mfma_f32_16x16x32_bf16 v[108:111], v[160:163], v[192:195], v[108:111]
	v_mfma_f32_16x16x32_bf16 v[100:103], v[152:155], v[200:203], v[100:103]
	v_mfma_f32_16x16x32_bf16 v[92:95], v[160:163], v[200:203], v[92:95]
	v_mfma_f32_16x16x32_bf16 v[84:87], v[152:155], v[208:211], v[84:87]
	v_mfma_f32_16x16x32_bf16 v[76:79], v[160:163], v[208:211], v[76:79]
	v_mfma_f32_16x16x32_bf16 v[124:127], v[156:159], v[188:191], v[124:127]
	v_mfma_f32_16x16x32_bf16 v[120:123], v[164:167], v[188:191], v[120:123]
	v_mfma_f32_16x16x32_bf16 v[116:119], v[156:159], v[196:199], v[116:119]
	v_mfma_f32_16x16x32_bf16 v[108:111], v[164:167], v[196:199], v[108:111]
	v_mfma_f32_16x16x32_bf16 v[100:103], v[156:159], v[204:207], v[100:103]
	v_mfma_f32_16x16x32_bf16 v[92:95], v[164:167], v[204:207], v[92:95]
	v_mfma_f32_16x16x32_bf16 v[84:87], v[156:159], v[212:215], v[84:87]
	v_mfma_f32_16x16x32_bf16 v[76:79], v[164:167], v[212:215], v[76:79]
	v_mfma_f32_16x16x32_bf16 v[112:115], v[168:171], v[184:187], v[112:115]
	v_mfma_f32_16x16x32_bf16 v[104:107], v[176:179], v[184:187], v[104:107]
	v_mfma_f32_16x16x32_bf16 v[96:99], v[168:171], v[192:195], v[96:99]
	v_mfma_f32_16x16x32_bf16 v[88:91], v[176:179], v[192:195], v[88:91]
	v_mfma_f32_16x16x32_bf16 v[80:83], v[168:171], v[200:203], v[80:83]
	v_mfma_f32_16x16x32_bf16 v[72:75], v[176:179], v[200:203], v[72:75]
	v_mfma_f32_16x16x32_bf16 v[68:71], v[168:171], v[208:211], v[68:71]
	v_mfma_f32_16x16x32_bf16 v[64:67], v[176:179], v[208:211], v[64:67]
	v_mfma_f32_16x16x32_bf16 v[112:115], v[172:175], v[188:191], v[112:115]
	v_mfma_f32_16x16x32_bf16 v[104:107], v[180:183], v[188:191], v[104:107]
	v_mfma_f32_16x16x32_bf16 v[96:99], v[172:175], v[196:199], v[96:99]
	v_mfma_f32_16x16x32_bf16 v[88:91], v[180:183], v[196:199], v[88:91]
	v_mfma_f32_16x16x32_bf16 v[80:83], v[172:175], v[204:207], v[80:83]
	v_mfma_f32_16x16x32_bf16 v[72:75], v[180:183], v[204:207], v[72:75]
	v_mfma_f32_16x16x32_bf16 v[68:71], v[172:175], v[212:215], v[68:71]
	v_mfma_f32_16x16x32_bf16 v[64:67], v[180:183], v[212:215], v[64:67]
	s_barrier
	s_add_i32 s69, s57, s41
	v_lshl_add_u64 v[144:145], s[30:31], 0, v[132:133]
	s_mov_b32 m0, s69
	ds_read_b128 v[184:187], v151 offset:16384
	ds_read_b128 v[188:191], v151 offset:17408
	ds_read_b128 v[192:195], v151 offset:18432
	ds_read_b128 v[196:199], v151 offset:19456
	ds_read_b128 v[200:203], v151 offset:20480
	ds_read_b128 v[204:207], v151 offset:21504
	ds_read_b128 v[208:211], v151 offset:22528
	ds_read_b128 v[212:215], v151 offset:23552
	global_load_lds_dwordx4 v[144:145], off
	s_add_i32 m0, s69, 0x2000
	s_add_u32 s70, s30, 0x40000
	v_lshl_add_u64 v[216:217], s[30:31], 0, v[128:129]
	s_addc_u32 s71, s31, 0
	s_add_i32 s69, s58, s41
	global_load_lds_dwordx4 v[216:217], off
	v_lshl_add_u64 v[218:219], s[70:71], 0, v[132:133]
	s_mov_b32 m0, s69
	v_lshl_add_u64 v[220:221], s[34:35], 0, v[130:131]
	global_load_lds_dwordx4 v[218:219], off
	v_lshl_add_u64 v[218:219], s[70:71], 0, v[128:129]
	s_add_i32 m0, s69, 0x2000
	s_nop 0
	global_load_lds_dwordx4 v[218:219], off
	v_lshl_add_u64 v[218:219], s[34:35], 0, v[134:135]
	s_mov_b32 m0, s29
	s_nop 0
	global_load_lds_dwordx4 v[218:219], off
	s_mov_b32 m0, s43
	s_nop 0
	global_load_lds_dwordx4 v[220:221], off
	s_waitcnt vmcnt(8)
	s_waitcnt lgkmcnt(0)
	s_barrier
; #define PG8_STAGE(bufoff, gbase, voff) do { _Pragma("unroll") for (int _i = 0; _i < 2; ++_i) \
;         __builtin_amdgcn_global_load_lds((const unsigned*)((const char*)(gbase) + (voff)[_i]), (PG8_LAS unsigned*)(lds + (bufoff) + ldsw + _i * 8192), 16, 0, 0); } while (0)
; #define PG8_LDA(dst, b, h) do { _Pragma("unroll") for (int m = 0; m < 4; ++m) _Pragma("unroll") for (int k = 0; k < 2; ++k) dst[m][k] = *(const PG8_LAS bf16x8*)(lds + PG8_SA(b, h) + aoff + m * 2048 + k * 1024); } while (0)
; #define PG8_LDB(dst, b, h) do { _Pragma("unroll") for (int n = 0; n < 2; ++n) _Pragma("unroll") for (int k = 0; k < 2; ++k) dst[n][k] = *(const PG8_LAS bf16x8*)(lds + PG8_SB(b, h) + boff + n * 2048 + k * 1024); } while (0)
; #define PG8_MMA(ai, bj, At, Bt) do { __builtin_amdgcn_s_setprio(1); _Pragma("unroll") for (int m = 0; m < 4; ++m) _Pragma("unroll") for (int n = 0; n < 2; ++n) _Pragma("unroll") for (int k = 0; k < 2; ++k) \
;         acc[ai][bj][m][n] = __builtin_amdgcn_mfma_f32_16x16x32_bf16(Bt[n][k], At[m][k], acc[ai][bj][m][n], 0, 0, 0); __builtin_amdgcn_s_setprio(0); } while (0)
; #define PG8_WAIT_V(n) asm volatile("s_waitcnt vmcnt(" #n ")" ::: "memory")
; #define PG8_WAIT_L(n) asm volatile("s_waitcnt lgkmcnt(" #n ")" ::: "memory")
; #define PG8_BAR __builtin_amdgcn_s_barrier()
; #define PG8_SCHED __builtin_amdgcn_sched_barrier(0)
; template <class Epi, class Sched, bool ALIGN_EPI = false, bool SP2 = false>
; __device__ __forceinline__ void gemm_phase(PG8_LAS unsigned char* lds, const Gemm g, const Sched& S, const Epi& E, const int tid_in) {
;     ...
;             PG8_WAIT_V(8); PG8_WAIT_L(0); PG8_BAR; PG8_MMA(1, 0, At, B0); PG8_MMA(1, 1, At, B1); PG8_BAR; PG8_SCHED;
;             PG8_LDB(B0, 1, 0); PG8_LDB(B1, 1, 1); PG8_SCHED; PG8_LDA(At, 1, 0); PG8_STAGE(PG8_SA(0, 1), a2 + hstep, voffA);
;             PG8_WAIT_V(8); PG8_WAIT_L(0); PG8_BAR; PG8_MMA(0, 0, At, B0); PG8_MMA(0, 1, At, B1); PG8_BAR; PG8_SCHED;
	s_waitcnt lgkmcnt(0)
	v_mfma_f32_16x16x32_bf16 v[60:63], v[152:155], v[184:187], v[60:63]
	v_mfma_f32_16x16x32_bf16 v[56:59], v[160:163], v[184:187], v[56:59]
	v_mfma_f32_16x16x32_bf16 v[52:55], v[152:155], v[192:195], v[52:55]
	v_mfma_f32_16x16x32_bf16 v[44:47], v[160:163], v[192:195], v[44:47]
	v_mfma_f32_16x16x32_bf16 v[36:39], v[152:155], v[200:203], v[36:39]
	v_mfma_f32_16x16x32_bf16 v[28:31], v[160:163], v[200:203], v[28:31]
	v_mfma_f32_16x16x32_bf16 v[20:23], v[152:155], v[208:211], v[20:23]
	v_mfma_f32_16x16x32_bf16 v[12:15], v[160:163], v[208:211], v[12:15]
	v_mfma_f32_16x16x32_bf16 v[60:63], v[156:159], v[188:191], v[60:63]
	v_mfma_f32_16x16x32_bf16 v[56:59], v[164:167], v[188:191], v[56:59]
	v_mfma_f32_16x16x32_bf16 v[52:55], v[156:159], v[196:199], v[52:55]
	v_mfma_f32_16x16x32_bf16 v[44:47], v[164:167], v[196:199], v[44:47]
	v_mfma_f32_16x16x32_bf16 v[36:39], v[156:159], v[204:207], v[36:39]
	v_mfma_f32_16x16x32_bf16 v[28:31], v[164:167], v[204:207], v[28:31]
	v_mfma_f32_16x16x32_bf16 v[20:23], v[156:159], v[212:215], v[20:23]
	v_mfma_f32_16x16x32_bf16 v[12:15], v[164:167], v[212:215], v[12:15]
	v_mfma_f32_16x16x32_bf16 v[48:51], v[168:171], v[184:187], v[48:51]
	v_mfma_f32_16x16x32_bf16 v[40:43], v[176:179], v[184:187], v[40:43]
	v_mfma_f32_16x16x32_bf16 v[32:35], v[168:171], v[192:195], v[32:35]
	v_mfma_f32_16x16x32_bf16 v[24:27], v[176:179], v[192:195], v[24:27]
	v_mfma_f32_16x16x32_bf16 v[16:19], v[168:171], v[200:203], v[16:19]
	v_mfma_f32_16x16x32_bf16 v[8:11], v[176:179], v[200:203], v[8:11]
	v_mfma_f32_16x16x32_bf16 v[4:7], v[168:171], v[208:211], v[4:7]
	v_mfma_f32_16x16x32_bf16 v[0:3], v[176:179], v[208:211], v[0:3]
	v_mfma_f32_16x16x32_bf16 v[48:51], v[172:175], v[188:191], v[48:51]
	v_mfma_f32_16x16x32_bf16 v[40:43], v[180:183], v[188:191], v[40:43]
	v_mfma_f32_16x16x32_bf16 v[32:35], v[172:175], v[196:199], v[32:35]
	v_mfma_f32_16x16x32_bf16 v[24:27], v[180:183], v[196:199], v[24:27]
	v_mfma_f32_16x16x32_bf16 v[16:19], v[172:175], v[204:207], v[16:19]
	v_mfma_f32_16x16x32_bf16 v[8:11], v[180:183], v[204:207], v[8:11]
	v_mfma_f32_16x16x32_bf16 v[4:7], v[172:175], v[212:215], v[4:7]
	v_mfma_f32_16x16x32_bf16 v[0:3], v[180:183], v[212:215], v[0:3]
	s_barrier
	s_add_i32 s69, 0, 0x18000
	s_add_i32 s70, 0, 0x1c000
	v_add_u32_e32 v164, s69, v147
	v_add_u32_e32 v180, s70, v147
	ds_read_b128 v[152:155], v164
	ds_read_b128 v[156:159], v164 offset:1024
	ds_read_b128 v[160:163], v164 offset:2048
	ds_read_b128 v[164:167], v164 offset:3072
	ds_read_b128 v[168:171], v180
	ds_read_b128 v[172:175], v180 offset:1024
	ds_read_b128 v[176:179], v180 offset:2048
	ds_read_b128 v[180:183], v180 offset:3072
	s_add_u32 s34, s34, 0x40000
	s_addc_u32 s35, s35, 0
	s_mov_b32 m0, s44
	v_lshl_add_u64 v[222:223], s[34:35], 0, v[134:135]
	ds_read_b128 v[184:187], v151 offset:32768
	ds_read_b128 v[188:191], v151 offset:33792
	ds_read_b128 v[192:195], v151 offset:34816
	ds_read_b128 v[196:199], v151 offset:35840
	ds_read_b128 v[200:203], v151 offset:36864
	ds_read_b128 v[204:207], v151 offset:37888
	ds_read_b128 v[208:211], v151 offset:38912
	ds_read_b128 v[212:215], v151 offset:39936
	global_load_lds_dwordx4 v[222:223], off
	v_lshl_add_u64 v[222:223], s[34:35], 0, v[130:131]
	s_mov_b32 m0, s45
	s_nop 0
	global_load_lds_dwordx4 v[222:223], off
	s_waitcnt vmcnt(8)
	s_waitcnt lgkmcnt(0)
	s_barrier
	s_waitcnt lgkmcnt(0)
	v_mfma_f32_16x16x32_bf16 v[124:127], v[152:155], v[184:187], v[124:127]
	v_mfma_f32_16x16x32_bf16 v[120:123], v[160:163], v[184:187], v[120:123]
	v_mfma_f32_16x16x32_bf16 v[116:119], v[152:155], v[192:195], v[116:119]
	v_mfma_f32_16x16x32_bf16 v[108:111], v[160:163], v[192:195], v[108:111]
	v_mfma_f32_16x16x32_bf16 v[100:103], v[152:155], v[200:203], v[100:103]
	v_mfma_f32_16x16x32_bf16 v[92:95], v[160:163], v[200:203], v[92:95]
	v_mfma_f32_16x16x32_bf16 v[84:87], v[152:155], v[208:211], v[84:87]
	v_mfma_f32_16x16x32_bf16 v[76:79], v[160:163], v[208:211], v[76:79]
	v_mfma_f32_16x16x32_bf16 v[124:127], v[156:159], v[188:191], v[124:127]
	v_mfma_f32_16x16x32_bf16 v[120:123], v[164:167], v[188:191], v[120:123]
	v_mfma_f32_16x16x32_bf16 v[116:119], v[156:159], v[196:199], v[116:119]
	v_mfma_f32_16x16x32_bf16 v[108:111], v[164:167], v[196:199], v[108:111]
	v_mfma_f32_16x16x32_bf16 v[100:103], v[156:159], v[204:207], v[100:103]
	v_mfma_f32_16x16x32_bf16 v[92:95], v[164:167], v[204:207], v[92:95]
	v_mfma_f32_16x16x32_bf16 v[84:87], v[156:159], v[212:215], v[84:87]
	v_mfma_f32_16x16x32_bf16 v[76:79], v[164:167], v[212:215], v[76:79]
	v_mfma_f32_16x16x32_bf16 v[112:115], v[168:171], v[184:187], v[112:115]
	v_mfma_f32_16x16x32_bf16 v[104:107], v[176:179], v[184:187], v[104:107]
	v_mfma_f32_16x16x32_bf16 v[96:99], v[168:171], v[192:195], v[96:99]
	v_mfma_f32_16x16x32_bf16 v[88:91], v[176:179], v[192:195], v[88:91]
	v_mfma_f32_16x16x32_bf16 v[80:83], v[168:171], v[200:203], v[80:83]
	v_mfma_f32_16x16x32_bf16 v[72:75], v[176:179], v[200:203], v[72:75]
	v_mfma_f32_16x16x32_bf16 v[68:71], v[168:171], v[208:211], v[68:71]
	v_mfma_f32_16x16x32_bf16 v[64:67], v[176:179], v[208:211], v[64:67]
	v_mfma_f32_16x16x32_bf16 v[112:115], v[172:175], v[188:191], v[112:115]
	v_mfma_f32_16x16x32_bf16 v[104:107], v[180:183], v[188:191], v[104:107]
	v_mfma_f32_16x16x32_bf16 v[96:99], v[172:175], v[196:199], v[96:99]
	v_mfma_f32_16x16x32_bf16 v[88:91], v[180:183], v[196:199], v[88:91]
	v_mfma_f32_16x16x32_bf16 v[80:83], v[172:175], v[204:207], v[80:83]
	v_mfma_f32_16x16x32_bf16 v[72:75], v[180:183], v[204:207], v[72:75]
	v_mfma_f32_16x16x32_bf16 v[68:71], v[172:175], v[212:215], v[68:71]
	v_mfma_f32_16x16x32_bf16 v[64:67], v[180:183], v[212:215], v[64:67]
	s_barrier
; #define PG8_STAGE(bufoff, gbase, voff) do { _Pragma("unroll") for (int _i = 0; _i < 2; ++_i) \
;         __builtin_amdgcn_global_load_lds((const unsigned*)((const char*)(gbase) + (voff)[_i]), (PG8_LAS unsigned*)(lds + (bufoff) + ldsw + _i * 8192), 16, 0, 0); } while (0)
; #define PG8_LDA(dst, b, h) do { _Pragma("unroll") for (int m = 0; m < 4; ++m) _Pragma("unroll") for (int k = 0; k < 2; ++k) dst[m][k] = *(const PG8_LAS bf16x8*)(lds + PG8_SA(b, h) + aoff + m * 2048 + k * 1024); } while (0)
; #define PG8_MMA(ai, bj, At, Bt) do { __builtin_amdgcn_s_setprio(1); _Pragma("unroll") for (int m = 0; m < 4; ++m) _Pragma("unroll") for (int n = 0; n < 2; ++n) _Pragma("unroll") for (int k = 0; k < 2; ++k) \
;         acc[ai][bj][m][n] = __builtin_amdgcn_mfma_f32_16x16x32_bf16(Bt[n][k], At[m][k], acc[ai][bj][m][n], 0, 0, 0); __builtin_amdgcn_s_setprio(0); } while (0)
; #define PG8_WAIT_V(n) asm volatile("s_waitcnt vmcnt(" #n ")" ::: "memory")
; #define PG8_WAIT_L(n) asm volatile("s_waitcnt lgkmcnt(" #n ")" ::: "memory")
; #define PG8_BAR __builtin_amdgcn_s_barrier()
; #define PG8_SCHED __builtin_amdgcn_sched_barrier(0)
; template <class Epi, class Sched, bool ALIGN_EPI = false, bool SP2 = false>
; __device__ __forceinline__ void gemm_phase(PG8_LAS unsigned char* lds, const Gemm g, const Sched& S, const Epi& E, const int tid_in) {
;     ...
;             PG8_LDA(At, 1, 1); PG8_STAGE(PG8_SB(1, 0), b3, voffB); PG8_STAGE(PG8_SB(1, 1), b3 + hstep, voffB); PG8_STAGE(PG8_SA(1, 0), a3, voffA);
;             PG8_WAIT_V(8); PG8_WAIT_L(0); PG8_BAR; PG8_MMA(1, 0, At, B0); PG8_MMA(1, 1, At, B1); PG8_BAR; PG8_SCHED;
	s_add_i32 s34, s69, s41
	v_lshl_add_u64 v[144:145], v[144:145], 0, s[4:5]
	s_mov_b32 m0, s34
	ds_read_b128 v[184:187], v151 offset:49152
	ds_read_b128 v[188:191], v151 offset:50176
	ds_read_b128 v[192:195], v151 offset:51200
	ds_read_b128 v[196:199], v151 offset:52224
	ds_read_b128 v[200:203], v151 offset:53248
	ds_read_b128 v[204:207], v151 offset:54272
	ds_read_b128 v[208:211], v151 offset:55296
	ds_read_b128 v[212:215], v151 offset:56320
	global_load_lds_dwordx4 v[144:145], off
	s_add_i32 m0, s34, 0x2000
	s_add_u32 s30, s30, 0x40080
	v_lshl_add_u64 v[144:145], v[216:217], 0, s[4:5]
	s_addc_u32 s31, s31, 0
	s_add_i32 s34, s70, s41
	global_load_lds_dwordx4 v[144:145], off
	v_lshl_add_u64 v[144:145], s[30:31], 0, v[132:133]
	s_mov_b32 m0, s34
	s_nop 0
	global_load_lds_dwordx4 v[144:145], off
	v_lshl_add_u64 v[144:145], s[30:31], 0, v[128:129]
	s_add_i32 m0, s34, 0x2000
	s_nop 0
	global_load_lds_dwordx4 v[144:145], off
	v_lshl_add_u64 v[144:145], v[218:219], 0, s[4:5]
	s_mov_b32 m0, s52
	s_nop 0
	global_load_lds_dwordx4 v[144:145], off
	v_lshl_add_u64 v[144:145], v[220:221], 0, s[4:5]
	s_mov_b32 m0, s53
	s_nop 0
	global_load_lds_dwordx4 v[144:145], off
	s_waitcnt vmcnt(8)
	s_waitcnt lgkmcnt(0)
	s_barrier
	s_waitcnt lgkmcnt(0)
	v_mfma_f32_16x16x32_bf16 v[60:63], v[152:155], v[184:187], v[60:63]
	v_mfma_f32_16x16x32_bf16 v[56:59], v[160:163], v[184:187], v[56:59]
	v_mfma_f32_16x16x32_bf16 v[52:55], v[152:155], v[192:195], v[52:55]
	v_mfma_f32_16x16x32_bf16 v[44:47], v[160:163], v[192:195], v[44:47]
	v_mfma_f32_16x16x32_bf16 v[36:39], v[152:155], v[200:203], v[36:39]
	v_mfma_f32_16x16x32_bf16 v[28:31], v[160:163], v[200:203], v[28:31]
	v_mfma_f32_16x16x32_bf16 v[20:23], v[152:155], v[208:211], v[20:23]
	v_mfma_f32_16x16x32_bf16 v[12:15], v[160:163], v[208:211], v[12:15]
	v_mfma_f32_16x16x32_bf16 v[60:63], v[156:159], v[188:191], v[60:63]
	v_mfma_f32_16x16x32_bf16 v[56:59], v[164:167], v[188:191], v[56:59]
	v_mfma_f32_16x16x32_bf16 v[52:55], v[156:159], v[196:199], v[52:55]
	v_mfma_f32_16x16x32_bf16 v[44:47], v[164:167], v[196:199], v[44:47]
	v_mfma_f32_16x16x32_bf16 v[36:39], v[156:159], v[204:207], v[36:39]
	v_mfma_f32_16x16x32_bf16 v[28:31], v[164:167], v[204:207], v[28:31]
	v_mfma_f32_16x16x32_bf16 v[20:23], v[156:159], v[212:215], v[20:23]
	v_mfma_f32_16x16x32_bf16 v[12:15], v[164:167], v[212:215], v[12:15]
	v_mfma_f32_16x16x32_bf16 v[48:51], v[168:171], v[184:187], v[48:51]
	v_mfma_f32_16x16x32_bf16 v[40:43], v[176:179], v[184:187], v[40:43]
	v_mfma_f32_16x16x32_bf16 v[32:35], v[168:171], v[192:195], v[32:35]
	v_mfma_f32_16x16x32_bf16 v[24:27], v[176:179], v[192:195], v[24:27]
	v_mfma_f32_16x16x32_bf16 v[16:19], v[168:171], v[200:203], v[16:19]
	v_mfma_f32_16x16x32_bf16 v[8:11], v[176:179], v[200:203], v[8:11]
	v_mfma_f32_16x16x32_bf16 v[4:7], v[168:171], v[208:211], v[4:7]
	v_mfma_f32_16x16x32_bf16 v[0:3], v[176:179], v[208:211], v[0:3]
	v_mfma_f32_16x16x32_bf16 v[48:51], v[172:175], v[188:191], v[48:51]
	v_mfma_f32_16x16x32_bf16 v[40:43], v[180:183], v[188:191], v[40:43]
	v_mfma_f32_16x16x32_bf16 v[32:35], v[172:175], v[196:199], v[32:35]
	v_mfma_f32_16x16x32_bf16 v[24:27], v[180:183], v[196:199], v[24:27]
	v_mfma_f32_16x16x32_bf16 v[16:19], v[172:175], v[204:207], v[16:19]
	v_mfma_f32_16x16x32_bf16 v[8:11], v[180:183], v[204:207], v[8:11]
	v_mfma_f32_16x16x32_bf16 v[4:7], v[172:175], v[212:215], v[4:7]
	v_mfma_f32_16x16x32_bf16 v[0:3], v[180:183], v[212:215], v[0:3]
	s_barrier
	s_add_i32 s68, s68, 2
	s_add_u32 s0, s0, 0x100
	s_addc_u32 s1, s1, 0
	s_add_u32 s66, s66, 0x100
	s_addc_u32 s67, s67, 0
	s_cmp_gt_u32 s68, 13
	s_cbranch_scc0 .LBB0_739
	s_and_b64 vcc, exec, s[6:7]
	s_cbranch_vccz .LBB0_742
	s_barrier

; #define PG8_STAGE(bufoff, gbase, voff) do { _Pragma("unroll") for (int _i = 0; _i < 2; ++_i) \
;         __builtin_amdgcn_global_load_lds((const unsigned*)((const char*)(gbase) + (voff)[_i]), (PG8_LAS unsigned*)(lds + (bufoff) + ldsw + _i * 8192), 16, 0, 0); } while (0)
; #define PG8_LDA(dst, b, h) do { _Pragma("unroll") for (int m = 0; m < 4; ++m) _Pragma("unroll") for (int k = 0; k < 2; ++k) dst[m][k] = *(const PG8_LAS bf16x8*)(lds + PG8_SA(b, h) + aoff + m * 2048 + k * 1024); } while (0)
; #define PG8_LDB(dst, b, h) do { _Pragma("unroll") for (int n = 0; n < 2; ++n) _Pragma("unroll") for (int k = 0; k < 2; ++k) dst[n][k] = *(const PG8_LAS bf16x8*)(lds + PG8_SB(b, h) + boff + n * 2048 + k * 1024); } while (0)
; #define PG8_MMA(ai, bj, At, Bt) do { __builtin_amdgcn_s_setprio(1); _Pragma("unroll") for (int m = 0; m < 4; ++m) _Pragma("unroll") for (int n = 0; n < 2; ++n) _Pragma("unroll") for (int k = 0; k < 2; ++k) \
;         acc[ai][bj][m][n] = __builtin_amdgcn_mfma_f32_16x16x32_bf16(Bt[n][k], At[m][k], acc[ai][bj][m][n], 0, 0, 0); __builtin_amdgcn_s_setprio(0); } while (0)
; template <class Epi, class Sched, bool ALIGN_EPI = false, bool SP2 = false>
; __device__ __forceinline__ void gemm_phase(PG8_LAS unsigned char* lds, const Gemm g, const Sched& S, const Epi& E, const int tid_in) {
;     ...
;         const bool has_next = S.next(ui + 1, nxt);
;         const char* nA = has_next ? (const char*)g.asel(nxt.pn) + (size_t)nxt.pm * tstep : cA; const char* nB = has_next ? (const char*)g.Bt + (size_t)nxt.pn * tstep : cB;
;         for (int t = 0; t < nt; t += 2) {
;             const bool last = (t == nt - 2);
;             const char* a1 = cA + (size_t)(t + 1) * kstep;
;             const char* a2 = last ? nA : cA + (size_t)(t + 2) * kstep; const char* b2 = last ? nB : cB + (size_t)(t + 2) * kstep;
;             const char* a3 = a2 + kstep; const char* b3 = b2 + kstep;
;             if (last && has_next) S.a_ready(nxt);
;             if constexpr (SP2) {
;             PG8_LDB(B0, 0, 0); PG8_LDB(B1, 0, 1); PG8_SCHED; PG8_LDA(At, 0, 0); PG8_STAGE(PG8_SA(1, 1), a1 + hstep, voffA);
;             PG8_WAIT_V(8); PG8_WAIT_L(0); PG8_BAR; PG8_MMA(0, 0, At, B0); PG8_MMA(0, 1, At, B1); PG8_BAR; PG8_SCHED;
;             PG8_LDA(At, 0, 1); PG8_STAGE(PG8_SB(0, 0), b2, voffB); PG8_STAGE(PG8_SB(0, 1), b2 + hstep, voffB); PG8_STAGE(PG8_SA(0, 0), a2, voffA);
.LBB0_813:
	s_ashr_i32 s35, s34, 31
	s_lshl_b64 s[36:37], s[34:35], 16
	s_add_u32 s36, s33, s36
	s_addc_u32 s37, s46, s37
	s_and_b64 s[38:39], s[2:3], exec
	s_cselect_b32 s45, s37, s43
	s_cselect_b32 s44, s36, s42
	s_ashr_i32 s31, s30, 31
	s_lshl_b64 s[38:39], s[30:31], 16
	s_add_u32 s38, s47, s38
	s_addc_u32 s39, s48, s39
	s_add_u32 s66, s42, 0x8080
	ds_read_b128 v[0:3], v153
	ds_read_b128 v[4:7], v153 offset:1024
	ds_read_b128 v[8:11], v153 offset:2048
	ds_read_b128 v[12:15], v153 offset:3072
	ds_read_b128 v[16:19], v154
	ds_read_b128 v[20:23], v154 offset:1024
	ds_read_b128 v[24:27], v154 offset:2048
	ds_read_b128 v[28:31], v154 offset:3072
	s_addc_u32 s67, s43, 0
	s_add_u32 s42, s44, 0x8000
	s_addc_u32 s43, s45, 0
	s_and_b64 s[68:69], s[2:3], exec
	s_cselect_b32 s40, s38, s40
	s_cselect_b32 s41, s39, s41
	s_add_u32 s68, s40, 0x8000
	s_addc_u32 s69, s41, 0
	v_lshl_add_u64 v[64:65], s[66:67], 0, v[134:135]
	s_add_i32 m0, s50, 0xc000
	ds_read_b128 v[32:35], v155
	ds_read_b128 v[36:39], v155 offset:1024
	ds_read_b128 v[40:43], v155 offset:2048
	ds_read_b128 v[44:47], v155 offset:3072
	ds_read_b128 v[48:51], v155 offset:4096
	ds_read_b128 v[52:55], v155 offset:5120
	ds_read_b128 v[56:59], v155 offset:6144
	ds_read_b128 v[60:63], v155 offset:7168
	global_load_lds_dwordx4 v[64:65], off
	v_lshl_add_u64 v[64:65], s[66:67], 0, v[130:131]
	s_add_i32 m0, s50, 0xe000
	s_nop 0
	global_load_lds_dwordx4 v[64:65], off
	s_waitcnt vmcnt(8)
	s_waitcnt lgkmcnt(0)
	s_barrier
	s_waitcnt lgkmcnt(0)
	v_mfma_f32_16x16x32_bf16 v[88:91], v[0:3], v[56:59], 0
	v_mfma_f32_16x16x32_bf16 v[64:67], v[0:3], v[32:35], 0
	v_mfma_f32_16x16x32_bf16 v[68:71], v[8:11], v[32:35], 0
	v_mfma_f32_16x16x32_bf16 v[72:75], v[0:3], v[40:43], 0
	v_mfma_f32_16x16x32_bf16 v[76:79], v[8:11], v[40:43], 0
	v_mfma_f32_16x16x32_bf16 v[80:83], v[0:3], v[48:51], 0
	v_mfma_f32_16x16x32_bf16 v[84:87], v[8:11], v[48:51], 0
	v_mfma_f32_16x16x32_bf16 v[96:99], v[4:7], v[60:63], v[88:91]
	v_mfma_f32_16x16x32_bf16 v[88:91], v[8:11], v[56:59], 0
	v_mfma_f32_16x16x32_bf16 v[64:67], v[4:7], v[36:39], v[64:67]
	v_mfma_f32_16x16x32_bf16 v[68:71], v[12:15], v[36:39], v[68:71]
	v_mfma_f32_16x16x32_bf16 v[72:75], v[4:7], v[44:47], v[72:75]
	v_mfma_f32_16x16x32_bf16 v[76:79], v[12:15], v[44:47], v[76:79]
	v_mfma_f32_16x16x32_bf16 v[80:83], v[4:7], v[52:55], v[80:83]
	v_mfma_f32_16x16x32_bf16 v[84:87], v[12:15], v[52:55], v[84:87]
	v_mfma_f32_16x16x32_bf16 v[100:103], v[12:15], v[60:63], v[88:91]
	v_mfma_f32_16x16x32_bf16 v[88:91], v[16:19], v[32:35], 0
	v_mfma_f32_16x16x32_bf16 v[32:35], v[24:27], v[32:35], 0
	v_mfma_f32_16x16x32_bf16 v[112:115], v[20:23], v[36:39], v[88:91]
	v_mfma_f32_16x16x32_bf16 v[32:35], v[28:31], v[36:39], v[32:35]
	v_mfma_f32_16x16x32_bf16 v[36:39], v[16:19], v[40:43], 0
	v_mfma_f32_16x16x32_bf16 v[40:43], v[24:27], v[40:43], 0
	v_mfma_f32_16x16x32_bf16 v[36:39], v[20:23], v[44:47], v[36:39]
	v_mfma_f32_16x16x32_bf16 v[40:43], v[28:31], v[44:47], v[40:43]
	v_mfma_f32_16x16x32_bf16 v[44:47], v[16:19], v[48:51], 0
	v_mfma_f32_16x16x32_bf16 v[48:51], v[24:27], v[48:51], 0
	v_mfma_f32_16x16x32_bf16 v[44:47], v[20:23], v[52:55], v[44:47]
	v_mfma_f32_16x16x32_bf16 v[48:51], v[28:31], v[52:55], v[48:51]
	v_mfma_f32_16x16x32_bf16 v[52:55], v[16:19], v[56:59], 0
	v_mfma_f32_16x16x32_bf16 v[56:59], v[24:27], v[56:59], 0
	v_mfma_f32_16x16x32_bf16 v[52:55], v[20:23], v[60:63], v[52:55]
	v_mfma_f32_16x16x32_bf16 v[56:59], v[28:31], v[60:63], v[56:59]
	s_barrier
	s_add_i32 s31, s60, s49
	v_lshl_add_u64 v[246:247], s[40:41], 0, v[132:133]
	s_mov_b32 m0, s31
	ds_read_b128 v[60:63], v155 offset:16384
	ds_read_b128 v[88:91], v155 offset:17408
	ds_read_b128 v[92:95], v155 offset:18432
	ds_read_b128 v[104:107], v155 offset:19456
	ds_read_b128 v[108:111], v155 offset:20480
	ds_read_b128 v[116:119], v155 offset:21504
	ds_read_b128 v[120:123], v155 offset:22528
	ds_read_b128 v[124:127], v155 offset:23552
	global_load_lds_dwordx4 v[246:247], off
	v_lshl_add_u64 v[248:249], s[40:41], 0, v[128:129]
	s_add_i32 m0, s31, 0x2000
	s_add_i32 s31, s61, s49
	global_load_lds_dwordx4 v[248:249], off
	v_lshl_add_u64 v[142:143], s[68:69], 0, v[132:133]
	s_mov_b32 m0, s31
	v_lshl_add_u64 v[250:251], s[44:45], 0, v[134:135]
	global_load_lds_dwordx4 v[142:143], off
	v_lshl_add_u64 v[142:143], s[68:69], 0, v[128:129]
	s_add_i32 m0, s31, 0x2000
	v_lshl_add_u64 v[252:253], s[44:45], 0, v[130:131]
	global_load_lds_dwordx4 v[142:143], off
	s_mov_b32 m0, s50
	s_nop 0
	global_load_lds_dwordx4 v[250:251], off
	s_mov_b32 m0, s51
	s_nop 0
	global_load_lds_dwordx4 v[252:253], off
	s_waitcnt vmcnt(8)
	s_waitcnt lgkmcnt(0)
	s_barrier
; #define PG8_STAGE(bufoff, gbase, voff) do { _Pragma("unroll") for (int _i = 0; _i < 2; ++_i) \
;         __builtin_amdgcn_global_load_lds((const unsigned*)((const char*)(gbase) + (voff)[_i]), (PG8_LAS unsigned*)(lds + (bufoff) + ldsw + _i * 8192), 16, 0, 0); } while (0)
; #define PG8_LDA(dst, b, h) do { _Pragma("unroll") for (int m = 0; m < 4; ++m) _Pragma("unroll") for (int k = 0; k < 2; ++k) dst[m][k] = *(const PG8_LAS bf16x8*)(lds + PG8_SA(b, h) + aoff + m * 2048 + k * 1024); } while (0)
; #define PG8_LDB(dst, b, h) do { _Pragma("unroll") for (int n = 0; n < 2; ++n) _Pragma("unroll") for (int k = 0; k < 2; ++k) dst[n][k] = *(const PG8_LAS bf16x8*)(lds + PG8_SB(b, h) + boff + n * 2048 + k * 1024); } while (0)
; #define PG8_MMA(ai, bj, At, Bt) do { __builtin_amdgcn_s_setprio(1); _Pragma("unroll") for (int m = 0; m < 4; ++m) _Pragma("unroll") for (int n = 0; n < 2; ++n) _Pragma("unroll") for (int k = 0; k < 2; ++k) \
;         acc[ai][bj][m][n] = __builtin_amdgcn_mfma_f32_16x16x32_bf16(Bt[n][k], At[m][k], acc[ai][bj][m][n], 0, 0, 0); __builtin_amdgcn_s_setprio(0); } while (0)
; #define PG8_WAIT_V(n) asm volatile("s_waitcnt vmcnt(" #n ")" ::: "memory")
; #define PG8_WAIT_L(n) asm volatile("s_waitcnt lgkmcnt(" #n ")" ::: "memory")
; #define PG8_BAR __builtin_amdgcn_s_barrier()
; #define PG8_SCHED __builtin_amdgcn_sched_barrier(0)
; template <class Epi, class Sched, bool ALIGN_EPI = false, bool SP2 = false>
; __device__ __forceinline__ void gemm_phase(PG8_LAS unsigned char* lds, const Gemm g, const Sched& S, const Epi& E, const int tid_in) {
;     ...
;             PG8_WAIT_V(8); PG8_WAIT_L(0); PG8_BAR; PG8_MMA(1, 0, At, B0); PG8_MMA(1, 1, At, B1); PG8_BAR; PG8_SCHED;
;             PG8_LDB(B0, 1, 0); PG8_LDB(B1, 1, 1); PG8_SCHED; PG8_LDA(At, 1, 0); PG8_STAGE(PG8_SA(0, 1), a2 + hstep, voffA);
;             PG8_WAIT_V(8); PG8_WAIT_L(0); PG8_BAR; PG8_MMA(0, 0, At, B0); PG8_MMA(0, 1, At, B1); PG8_BAR; PG8_SCHED;
	s_waitcnt lgkmcnt(0)
	v_mfma_f32_16x16x32_bf16 v[142:145], v[0:3], v[60:63], 0
	v_mfma_f32_16x16x32_bf16 v[158:161], v[0:3], v[92:95], 0
	v_mfma_f32_16x16x32_bf16 v[166:169], v[0:3], v[108:111], 0
	v_mfma_f32_16x16x32_bf16 v[0:3], v[0:3], v[120:123], 0
	v_mfma_f32_16x16x32_bf16 v[142:145], v[4:7], v[88:91], v[142:145]
	v_mfma_f32_16x16x32_bf16 v[158:161], v[4:7], v[104:107], v[158:161]
	v_mfma_f32_16x16x32_bf16 v[166:169], v[4:7], v[116:119], v[166:169]
	v_mfma_f32_16x16x32_bf16 v[0:3], v[4:7], v[124:127], v[0:3]
	v_mfma_f32_16x16x32_bf16 v[4:7], v[8:11], v[120:123], 0
	v_mfma_f32_16x16x32_bf16 v[146:149], v[8:11], v[60:63], 0
	v_mfma_f32_16x16x32_bf16 v[162:165], v[8:11], v[92:95], 0
	v_mfma_f32_16x16x32_bf16 v[170:173], v[8:11], v[108:111], 0
	v_mfma_f32_16x16x32_bf16 v[4:7], v[12:15], v[124:127], v[4:7]
	v_mfma_f32_16x16x32_bf16 v[146:149], v[12:15], v[88:91], v[146:149]
	v_mfma_f32_16x16x32_bf16 v[162:165], v[12:15], v[104:107], v[162:165]
	v_mfma_f32_16x16x32_bf16 v[170:173], v[12:15], v[116:119], v[170:173]
	v_mfma_f32_16x16x32_bf16 v[8:11], v[16:19], v[60:63], 0
	v_mfma_f32_16x16x32_bf16 v[174:177], v[20:23], v[88:91], v[8:11]
	v_mfma_f32_16x16x32_bf16 v[8:11], v[24:27], v[60:63], 0
	v_mfma_f32_16x16x32_bf16 v[178:181], v[28:31], v[88:91], v[8:11]
	v_mfma_f32_16x16x32_bf16 v[8:11], v[16:19], v[92:95], 0
	v_mfma_f32_16x16x32_bf16 v[182:185], v[20:23], v[104:107], v[8:11]
	v_mfma_f32_16x16x32_bf16 v[8:11], v[24:27], v[92:95], 0
	v_mfma_f32_16x16x32_bf16 v[186:189], v[28:31], v[104:107], v[8:11]
	v_mfma_f32_16x16x32_bf16 v[8:11], v[16:19], v[108:111], 0
	v_mfma_f32_16x16x32_bf16 v[190:193], v[20:23], v[116:119], v[8:11]
	v_mfma_f32_16x16x32_bf16 v[8:11], v[24:27], v[108:111], 0
	v_mfma_f32_16x16x32_bf16 v[194:197], v[28:31], v[116:119], v[8:11]
	v_mfma_f32_16x16x32_bf16 v[8:11], v[16:19], v[120:123], 0
	v_mfma_f32_16x16x32_bf16 v[198:201], v[20:23], v[124:127], v[8:11]
	v_mfma_f32_16x16x32_bf16 v[8:11], v[24:27], v[120:123], 0
	v_mfma_f32_16x16x32_bf16 v[202:205], v[28:31], v[124:127], v[8:11]
	s_barrier
	s_add_i32 s31, 0, 0x18000
	s_add_i32 s35, 0, 0x1c000
	v_add_u32_e32 v20, s31, v151
	v_add_u32_e32 v24, s35, v151
	s_nop 0
	ds_read_b128 v[8:11], v20
	ds_read_b128 v[12:15], v20 offset:1024
	ds_read_b128 v[16:19], v20 offset:2048
	ds_read_b128 v[20:23], v20 offset:3072
	ds_read_b128 v[206:209], v24
	ds_read_b128 v[210:213], v24 offset:1024
	ds_read_b128 v[214:217], v24 offset:2048
	ds_read_b128 v[218:221], v24 offset:3072
	s_mov_b32 m0, s52
	v_lshl_add_u64 v[88:89], s[42:43], 0, v[134:135]
	ds_read_b128 v[24:27], v155 offset:32768
	ds_read_b128 v[28:31], v155 offset:33792
	ds_read_b128 v[60:63], v155 offset:34816
	ds_read_b128 v[222:225], v155 offset:35840
	ds_read_b128 v[226:229], v155 offset:36864
	ds_read_b128 v[230:233], v155 offset:37888
	ds_read_b128 v[234:237], v155 offset:38912
	ds_read_b128 v[238:241], v155 offset:39936
	global_load_lds_dwordx4 v[88:89], off
	v_lshl_add_u64 v[88:89], s[42:43], 0, v[130:131]
	s_mov_b32 m0, s53
	s_nop 0
	global_load_lds_dwordx4 v[88:89], off
	s_waitcnt vmcnt(8)
	s_waitcnt lgkmcnt(0)
	s_barrier
	s_waitcnt lgkmcnt(0)
	v_mfma_f32_16x16x32_bf16 v[64:67], v[8:11], v[24:27], v[64:67]
	v_mfma_f32_16x16x32_bf16 v[124:127], v[12:15], v[28:31], v[64:67]
	v_mfma_f32_16x16x32_bf16 v[64:67], v[16:19], v[24:27], v[68:71]
	v_mfma_f32_16x16x32_bf16 v[120:123], v[20:23], v[28:31], v[64:67]
	v_mfma_f32_16x16x32_bf16 v[64:67], v[8:11], v[60:63], v[72:75]
	v_mfma_f32_16x16x32_bf16 v[108:111], v[12:15], v[222:225], v[64:67]
	v_mfma_f32_16x16x32_bf16 v[64:67], v[16:19], v[60:63], v[76:79]
	v_mfma_f32_16x16x32_bf16 v[104:107], v[20:23], v[222:225], v[64:67]
	v_mfma_f32_16x16x32_bf16 v[64:67], v[8:11], v[226:229], v[80:83]
	v_mfma_f32_16x16x32_bf16 v[92:95], v[12:15], v[230:233], v[64:67]
	v_mfma_f32_16x16x32_bf16 v[64:67], v[16:19], v[226:229], v[84:87]
	v_mfma_f32_16x16x32_bf16 v[88:91], v[20:23], v[230:233], v[64:67]
	v_mfma_f32_16x16x32_bf16 v[64:67], v[8:11], v[234:237], v[96:99]
	v_mfma_f32_16x16x32_bf16 v[76:79], v[12:15], v[238:241], v[64:67]
	v_mfma_f32_16x16x32_bf16 v[64:67], v[16:19], v[234:237], v[100:103]
	v_mfma_f32_16x16x32_bf16 v[72:75], v[20:23], v[238:241], v[64:67]
	v_mfma_f32_16x16x32_bf16 v[64:67], v[206:209], v[24:27], v[112:115]
	v_mfma_f32_16x16x32_bf16 v[24:27], v[214:217], v[24:27], v[32:35]
	v_mfma_f32_16x16x32_bf16 v[112:115], v[218:221], v[28:31], v[24:27]
	v_mfma_f32_16x16x32_bf16 v[24:27], v[206:209], v[60:63], v[36:39]
	v_mfma_f32_16x16x32_bf16 v[100:103], v[210:213], v[222:225], v[24:27]
	v_mfma_f32_16x16x32_bf16 v[24:27], v[214:217], v[60:63], v[40:43]
	v_mfma_f32_16x16x32_bf16 v[96:99], v[218:221], v[222:225], v[24:27]
	v_mfma_f32_16x16x32_bf16 v[24:27], v[206:209], v[226:229], v[44:47]
	v_mfma_f32_16x16x32_bf16 v[84:87], v[210:213], v[230:233], v[24:27]
	v_mfma_f32_16x16x32_bf16 v[24:27], v[214:217], v[226:229], v[48:51]
	v_mfma_f32_16x16x32_bf16 v[80:83], v[218:221], v[230:233], v[24:27]
	v_mfma_f32_16x16x32_bf16 v[24:27], v[206:209], v[234:237], v[52:55]
	v_mfma_f32_16x16x32_bf16 v[68:71], v[210:213], v[238:241], v[24:27]
	v_mfma_f32_16x16x32_bf16 v[24:27], v[214:217], v[234:237], v[56:59]
	v_mfma_f32_16x16x32_bf16 v[116:119], v[210:213], v[28:31], v[64:67]
	v_mfma_f32_16x16x32_bf16 v[64:67], v[218:221], v[238:241], v[24:27]
	s_barrier
; #define PG8_STAGE(bufoff, gbase, voff) do { _Pragma("unroll") for (int _i = 0; _i < 2; ++_i) \
;         __builtin_amdgcn_global_load_lds((const unsigned*)((const char*)(gbase) + (voff)[_i]), (PG8_LAS unsigned*)(lds + (bufoff) + ldsw + _i * 8192), 16, 0, 0); } while (0)
; #define PG8_LDA(dst, b, h) do { _Pragma("unroll") for (int m = 0; m < 4; ++m) _Pragma("unroll") for (int k = 0; k < 2; ++k) dst[m][k] = *(const PG8_LAS bf16x8*)(lds + PG8_SA(b, h) + aoff + m * 2048 + k * 1024); } while (0)
; #define PG8_MMA(ai, bj, At, Bt) do { __builtin_amdgcn_s_setprio(1); _Pragma("unroll") for (int m = 0; m < 4; ++m) _Pragma("unroll") for (int n = 0; n < 2; ++n) _Pragma("unroll") for (int k = 0; k < 2; ++k) \
;         acc[ai][bj][m][n] = __builtin_amdgcn_mfma_f32_16x16x32_bf16(Bt[n][k], At[m][k], acc[ai][bj][m][n], 0, 0, 0); __builtin_amdgcn_s_setprio(0); } while (0)
; #define PG8_WAIT_V(n) asm volatile("s_waitcnt vmcnt(" #n ")" ::: "memory")
; #define PG8_WAIT_L(n) asm volatile("s_waitcnt lgkmcnt(" #n ")" ::: "memory")
; #define PG8_BAR __builtin_amdgcn_s_barrier()
; #define PG8_SCHED __builtin_amdgcn_sched_barrier(0)
; template <class Epi, class Sched, bool ALIGN_EPI = false, bool SP2 = false>
; __device__ __forceinline__ void gemm_phase(PG8_LAS unsigned char* lds, const Gemm g, const Sched& S, const Epi& E, const int tid_in) {
;     ...
;             PG8_LDA(At, 1, 1); PG8_STAGE(PG8_SB(1, 0), b3, voffB); PG8_STAGE(PG8_SB(1, 1), b3 + hstep, voffB); PG8_STAGE(PG8_SA(1, 0), a3, voffA);
;             PG8_WAIT_V(8); PG8_WAIT_L(0); PG8_BAR; PG8_MMA(1, 0, At, B0); PG8_MMA(1, 1, At, B1); PG8_BAR; PG8_SCHED;
;     ...
;         if constexpr (ALIGN_EPI) { if (wr == 0) PG8_BAR; }
	s_add_i32 s31, s31, s49
	s_nop 2
	v_lshl_add_u64 v[24:25], v[246:247], 0, s[14:15]
	s_mov_b32 m0, s31
	ds_read_b128 v[32:35], v155 offset:49152
	ds_read_b128 v[36:39], v155 offset:50176
	ds_read_b128 v[222:225], v155 offset:51200
	ds_read_b128 v[226:229], v155 offset:52224
	ds_read_b128 v[230:233], v155 offset:53248
	ds_read_b128 v[234:237], v155 offset:54272
	ds_read_b128 v[238:241], v155 offset:55296
	ds_read_b128 v[242:245], v155 offset:56320
	global_load_lds_dwordx4 v[24:25], off
	s_add_i32 m0, s31, 0x2000
	s_add_u32 s40, s40, 0x8080
	v_lshl_add_u64 v[24:25], v[248:249], 0, s[14:15]
	s_addc_u32 s41, s41, 0
	s_add_i32 s31, s35, s49
	global_load_lds_dwordx4 v[24:25], off
	v_lshl_add_u64 v[24:25], s[40:41], 0, v[132:133]
	s_mov_b32 m0, s31
	s_nop 0
	global_load_lds_dwordx4 v[24:25], off
	v_lshl_add_u64 v[24:25], s[40:41], 0, v[128:129]
	s_add_i32 m0, s31, 0x2000
	s_nop 0
	global_load_lds_dwordx4 v[24:25], off
	v_lshl_add_u64 v[24:25], v[250:251], 0, s[14:15]
	s_mov_b32 m0, s57
	s_nop 0
	global_load_lds_dwordx4 v[24:25], off
	v_lshl_add_u64 v[24:25], v[252:253], 0, s[14:15]
	s_mov_b32 m0, s58
	s_nop 0
	global_load_lds_dwordx4 v[24:25], off
	s_waitcnt vmcnt(8)
	s_waitcnt lgkmcnt(0)
	s_barrier
	s_waitcnt lgkmcnt(0)
	v_mfma_f32_16x16x32_bf16 v[24:27], v[8:11], v[32:35], v[142:145]
	v_mfma_f32_16x16x32_bf16 v[56:59], v[12:15], v[36:39], v[24:27]
	v_mfma_f32_16x16x32_bf16 v[24:27], v[16:19], v[32:35], v[146:149]
	v_mfma_f32_16x16x32_bf16 v[60:63], v[20:23], v[36:39], v[24:27]
	v_mfma_f32_16x16x32_bf16 v[24:27], v[8:11], v[222:225], v[158:161]
	v_mfma_f32_16x16x32_bf16 v[40:43], v[12:15], v[226:229], v[24:27]
	v_mfma_f32_16x16x32_bf16 v[24:27], v[16:19], v[222:225], v[162:165]
	v_mfma_f32_16x16x32_bf16 v[0:3], v[8:11], v[238:241], v[0:3]
	v_mfma_f32_16x16x32_bf16 v[44:47], v[20:23], v[226:229], v[24:27]
	v_mfma_f32_16x16x32_bf16 v[24:27], v[8:11], v[230:233], v[166:169]
	v_mfma_f32_16x16x32_bf16 v[28:31], v[16:19], v[230:233], v[170:173]
	v_mfma_f32_16x16x32_bf16 v[8:11], v[12:15], v[242:245], v[0:3]
	v_mfma_f32_16x16x32_bf16 v[0:3], v[16:19], v[238:241], v[4:7]
	v_mfma_f32_16x16x32_bf16 v[24:27], v[12:15], v[234:237], v[24:27]
	v_mfma_f32_16x16x32_bf16 v[28:31], v[20:23], v[234:237], v[28:31]
	v_mfma_f32_16x16x32_bf16 v[12:15], v[20:23], v[242:245], v[0:3]
	v_mfma_f32_16x16x32_bf16 v[0:3], v[206:209], v[32:35], v[174:177]
	v_mfma_f32_16x16x32_bf16 v[52:55], v[210:213], v[36:39], v[0:3]
	v_mfma_f32_16x16x32_bf16 v[0:3], v[214:217], v[32:35], v[178:181]
	v_mfma_f32_16x16x32_bf16 v[48:51], v[218:221], v[36:39], v[0:3]
	v_mfma_f32_16x16x32_bf16 v[0:3], v[206:209], v[222:225], v[182:185]
	v_mfma_f32_16x16x32_bf16 v[36:39], v[210:213], v[226:229], v[0:3]
	v_mfma_f32_16x16x32_bf16 v[0:3], v[214:217], v[222:225], v[186:189]
	v_mfma_f32_16x16x32_bf16 v[32:35], v[218:221], v[226:229], v[0:3]
	v_mfma_f32_16x16x32_bf16 v[0:3], v[206:209], v[230:233], v[190:193]
	v_mfma_f32_16x16x32_bf16 v[20:23], v[210:213], v[234:237], v[0:3]
	v_mfma_f32_16x16x32_bf16 v[0:3], v[214:217], v[230:233], v[194:197]
	v_mfma_f32_16x16x32_bf16 v[16:19], v[218:221], v[234:237], v[0:3]
	v_mfma_f32_16x16x32_bf16 v[0:3], v[206:209], v[238:241], v[198:201]
	v_mfma_f32_16x16x32_bf16 v[4:7], v[214:217], v[238:241], v[202:205]
	v_mfma_f32_16x16x32_bf16 v[0:3], v[210:213], v[242:245], v[0:3]
	v_mfma_f32_16x16x32_bf16 v[4:7], v[218:221], v[242:245], v[4:7]
	s_barrier
	s_andn2_b64 vcc, exec, s[16:17]
	s_cbranch_vccnz .LBB0_815
	s_barrier

; __device__ __forceinline__ void unpack8(const u32x4 w, f32x4& a, f32x4& b) { a = (f32x4){bflo(w.x), bfhi(w.x), bflo(w.y), bfhi(w.y)}; b = (f32x4){bflo(w.z), bfhi(w.z), bflo(w.w), bfhi(w.w)}; }
; #define PG8_STAGE(bufoff, gbase, voff) do { _Pragma("unroll") for (int _i = 0; _i < 2; ++_i) \
;         __builtin_amdgcn_global_load_lds((const unsigned*)((const char*)(gbase) + (voff)[_i]), (PG8_LAS unsigned*)(lds + (bufoff) + ldsw + _i * 8192), 16, 0, 0); } while (0)
; #define PG8_LDA(dst, b, h) do { _Pragma("unroll") for (int m = 0; m < 4; ++m) _Pragma("unroll") for (int k = 0; k < 2; ++k) dst[m][k] = *(const PG8_LAS bf16x8*)(lds + PG8_SA(b, h) + aoff + m * 2048 + k * 1024); } while (0)
; #define PG8_MMA(ai, bj, At, Bt) do { __builtin_amdgcn_s_setprio(1); _Pragma("unroll") for (int m = 0; m < 4; ++m) _Pragma("unroll") for (int n = 0; n < 2; ++n) _Pragma("unroll") for (int k = 0; k < 2; ++k) \
;         acc[ai][bj][m][n] = __builtin_amdgcn_mfma_f32_16x16x32_bf16(Bt[n][k], At[m][k], acc[ai][bj][m][n], 0, 0, 0); __builtin_amdgcn_s_setprio(0); } while (0)
; #define PG8_WAIT_V(n) asm volatile("s_waitcnt vmcnt(" #n ")" ::: "memory")
; #define PG8_WAIT_L(n) asm volatile("s_waitcnt lgkmcnt(" #n ")" ::: "memory")
; #define PG8_BAR __builtin_amdgcn_s_barrier()
; #define PG8_SCHED __builtin_amdgcn_sched_barrier(0)
;     __device__ __forceinline__ void operator()(const f32x4 (&acc)[2][2][4][2], const Unit& u, int wr, int wc, int fr, int fq) const {
;     ...
;             for (int m = 0; m < 4; ++m) { const size_t off = (size_t)(row0 + ai * HALF + m * 16) * 1024 + col0;
; #pragma unroll
;                 for (int bj = 0; bj < 2; ++bj) { f32x4 b0, b1;
;                     if (BF) { unpack8(*(const u32x4*)((const bf16_t*)base + off + bj * HALF), b0, b1); }
; template <class Epi, class Sched, bool ALIGN_EPI = false, bool SP2 = false>
; __device__ __forceinline__ void gemm_phase(PG8_LAS unsigned char* lds, const Gemm g, const Sched& S, const Epi& E, const int tid_in) {
;     ...
;             PG8_WAIT_V(8); PG8_WAIT_L(0); PG8_BAR; PG8_MMA(0, 0, At, B0); PG8_MMA(0, 1, At, B1); PG8_BAR; PG8_SCHED;
;             PG8_LDA(At, 0, 1); PG8_STAGE(PG8_SB(0, 0), b2, voffB); PG8_STAGE(PG8_SB(0, 1), b2 + hstep, voffB); PG8_STAGE(PG8_SA(0, 0), a2, voffA);
;             PG8_WAIT_V(8); PG8_WAIT_L(0); PG8_BAR; PG8_MMA(1, 0, At, B0); PG8_MMA(1, 1, At, B1); PG8_BAR; PG8_SCHED;
.Lmy_rb_done:
	s_barrier
	s_waitcnt lgkmcnt(0)
	v_mfma_f32_16x16x32_bf16 v[124:127], v[144:147], v[200:203], v[124:127]
	v_mfma_f32_16x16x32_bf16 v[120:123], v[176:179], v[200:203], v[120:123]
	v_mfma_f32_16x16x32_bf16 v[116:119], v[144:147], v[208:211], v[116:119]
	v_mfma_f32_16x16x32_bf16 v[104:107], v[176:179], v[208:211], v[104:107]
	v_mfma_f32_16x16x32_bf16 v[100:103], v[144:147], v[216:219], v[100:103]
	v_mfma_f32_16x16x32_bf16 v[88:91], v[176:179], v[216:219], v[88:91]
	v_mfma_f32_16x16x32_bf16 v[84:87], v[144:147], v[224:227], v[84:87]
	v_mfma_f32_16x16x32_bf16 v[72:75], v[176:179], v[224:227], v[72:75]
	v_mfma_f32_16x16x32_bf16 v[124:127], v[172:175], v[204:207], v[124:127]
	v_mfma_f32_16x16x32_bf16 v[120:123], v[180:183], v[204:207], v[120:123]
	v_mfma_f32_16x16x32_bf16 v[116:119], v[172:175], v[212:215], v[116:119]
	v_mfma_f32_16x16x32_bf16 v[104:107], v[180:183], v[212:215], v[104:107]
	v_mfma_f32_16x16x32_bf16 v[100:103], v[172:175], v[220:223], v[100:103]
	v_mfma_f32_16x16x32_bf16 v[88:91], v[180:183], v[220:223], v[88:91]
	v_mfma_f32_16x16x32_bf16 v[84:87], v[172:175], v[228:231], v[84:87]
	v_mfma_f32_16x16x32_bf16 v[72:75], v[180:183], v[228:231], v[72:75]
	v_mfma_f32_16x16x32_bf16 v[112:115], v[184:187], v[200:203], v[112:115]
	v_mfma_f32_16x16x32_bf16 v[108:111], v[192:195], v[200:203], v[108:111]
	v_mfma_f32_16x16x32_bf16 v[96:99], v[184:187], v[208:211], v[96:99]
	v_mfma_f32_16x16x32_bf16 v[92:95], v[192:195], v[208:211], v[92:95]
	v_mfma_f32_16x16x32_bf16 v[80:83], v[184:187], v[216:219], v[80:83]
	v_mfma_f32_16x16x32_bf16 v[76:79], v[192:195], v[216:219], v[76:79]
	v_mfma_f32_16x16x32_bf16 v[68:71], v[184:187], v[224:227], v[68:71]
	v_mfma_f32_16x16x32_bf16 v[64:67], v[192:195], v[224:227], v[64:67]
	v_mfma_f32_16x16x32_bf16 v[112:115], v[188:191], v[204:207], v[112:115]
	v_mfma_f32_16x16x32_bf16 v[108:111], v[196:199], v[204:207], v[108:111]
	v_mfma_f32_16x16x32_bf16 v[96:99], v[188:191], v[212:215], v[96:99]
	v_mfma_f32_16x16x32_bf16 v[92:95], v[196:199], v[212:215], v[92:95]
	v_mfma_f32_16x16x32_bf16 v[80:83], v[188:191], v[220:223], v[80:83]
	v_mfma_f32_16x16x32_bf16 v[76:79], v[196:199], v[220:223], v[76:79]
	v_mfma_f32_16x16x32_bf16 v[68:71], v[188:191], v[228:231], v[68:71]
	v_mfma_f32_16x16x32_bf16 v[64:67], v[196:199], v[228:231], v[64:67]
	s_barrier
	s_add_i32 s71, s63, s56
	v_lshl_add_u64 v[148:149], s[42:43], 0, v[132:133]
	s_mov_b32 m0, s71
	ds_read_b128 v[200:203], v170 offset:16384
	ds_read_b128 v[204:207], v170 offset:17408
	ds_read_b128 v[208:211], v170 offset:18432
	ds_read_b128 v[212:215], v170 offset:19456
	ds_read_b128 v[216:219], v170 offset:20480
	ds_read_b128 v[220:223], v170 offset:21504
	ds_read_b128 v[224:227], v170 offset:22528
	ds_read_b128 v[228:231], v170 offset:23552
	global_load_lds_dwordx4 v[148:149], off
	s_add_i32 m0, s71, 0x2000
	s_add_u32 s72, s42, 0x40000
	v_lshl_add_u64 v[232:233], s[42:43], 0, v[128:129]
	s_addc_u32 s73, s43, 0
	s_add_i32 s71, s64, s56
	global_load_lds_dwordx4 v[232:233], off
	v_lshl_add_u64 v[234:235], s[72:73], 0, v[132:133]
	s_mov_b32 m0, s71
	v_lshl_add_u64 v[236:237], s[44:45], 0, v[130:131]
	global_load_lds_dwordx4 v[234:235], off
	v_lshl_add_u64 v[234:235], s[72:73], 0, v[128:129]
	s_add_i32 m0, s71, 0x2000
	s_nop 0
	global_load_lds_dwordx4 v[234:235], off
	v_lshl_add_u64 v[234:235], s[44:45], 0, v[134:135]
	s_mov_b32 m0, s41
	s_nop 0
	global_load_lds_dwordx4 v[234:235], off
	s_mov_b32 m0, s57
	s_nop 0
	global_load_lds_dwordx4 v[236:237], off
	s_waitcnt vmcnt(8)
	s_waitcnt lgkmcnt(0)
	global_load_dwordx4 v[242:245], v[240:241], off
	global_load_dwordx4 v[246:249], v[240:241], off offset:256
	s_mov_b32 s98, 0x8000
	s_cmp_eq_u32 s70, 4
	s_cselect_b32 s98, 0x28000, s98
	v_add_co_u32_e32 v240, vcc, s98, v240
	s_nop 1
	v_addc_co_u32_e32 v241, vcc, 0, v241, vcc
	s_barrier
	s_waitcnt lgkmcnt(0)
	v_mfma_f32_16x16x32_bf16 v[60:63], v[144:147], v[200:203], v[60:63]
	v_mfma_f32_16x16x32_bf16 v[56:59], v[176:179], v[200:203], v[56:59]
	v_mfma_f32_16x16x32_bf16 v[52:55], v[144:147], v[208:211], v[52:55]
	v_mfma_f32_16x16x32_bf16 v[40:43], v[176:179], v[208:211], v[40:43]
	v_mfma_f32_16x16x32_bf16 v[36:39], v[144:147], v[216:219], v[36:39]
	v_mfma_f32_16x16x32_bf16 v[24:27], v[176:179], v[216:219], v[24:27]
	v_mfma_f32_16x16x32_bf16 v[20:23], v[144:147], v[224:227], v[20:23]
	v_mfma_f32_16x16x32_bf16 v[8:11], v[176:179], v[224:227], v[8:11]
	v_mfma_f32_16x16x32_bf16 v[60:63], v[172:175], v[204:207], v[60:63]
	v_mfma_f32_16x16x32_bf16 v[56:59], v[180:183], v[204:207], v[56:59]
	v_mfma_f32_16x16x32_bf16 v[52:55], v[172:175], v[212:215], v[52:55]
	v_mfma_f32_16x16x32_bf16 v[40:43], v[180:183], v[212:215], v[40:43]
	v_mfma_f32_16x16x32_bf16 v[36:39], v[172:175], v[220:223], v[36:39]
	v_mfma_f32_16x16x32_bf16 v[24:27], v[180:183], v[220:223], v[24:27]
	v_mfma_f32_16x16x32_bf16 v[20:23], v[172:175], v[228:231], v[20:23]
	v_mfma_f32_16x16x32_bf16 v[8:11], v[180:183], v[228:231], v[8:11]
	v_mfma_f32_16x16x32_bf16 v[48:51], v[184:187], v[200:203], v[48:51]
	v_mfma_f32_16x16x32_bf16 v[44:47], v[192:195], v[200:203], v[44:47]
	v_mfma_f32_16x16x32_bf16 v[32:35], v[184:187], v[208:211], v[32:35]
	v_mfma_f32_16x16x32_bf16 v[28:31], v[192:195], v[208:211], v[28:31]
	v_mfma_f32_16x16x32_bf16 v[16:19], v[184:187], v[216:219], v[16:19]
	v_mfma_f32_16x16x32_bf16 v[12:15], v[192:195], v[216:219], v[12:15]
	v_mfma_f32_16x16x32_bf16 v[4:7], v[184:187], v[224:227], v[4:7]
	v_mfma_f32_16x16x32_bf16 v[0:3], v[192:195], v[224:227], v[0:3]
	v_mfma_f32_16x16x32_bf16 v[48:51], v[188:191], v[204:207], v[48:51]
	v_mfma_f32_16x16x32_bf16 v[44:47], v[196:199], v[204:207], v[44:47]
	v_mfma_f32_16x16x32_bf16 v[32:35], v[188:191], v[212:215], v[32:35]
	v_mfma_f32_16x16x32_bf16 v[28:31], v[196:199], v[212:215], v[28:31]
	v_mfma_f32_16x16x32_bf16 v[16:19], v[188:191], v[220:223], v[16:19]
	v_mfma_f32_16x16x32_bf16 v[12:15], v[196:199], v[220:223], v[12:15]
	v_mfma_f32_16x16x32_bf16 v[4:7], v[188:191], v[228:231], v[4:7]
	v_mfma_f32_16x16x32_bf16 v[0:3], v[196:199], v[228:231], v[0:3]
	s_barrier
; #define PG8_STAGE(bufoff, gbase, voff) do { _Pragma("unroll") for (int _i = 0; _i < 2; ++_i) \
;         __builtin_amdgcn_global_load_lds((const unsigned*)((const char*)(gbase) + (voff)[_i]), (PG8_LAS unsigned*)(lds + (bufoff) + ldsw + _i * 8192), 16, 0, 0); } while (0)
; #define PG8_LDA(dst, b, h) do { _Pragma("unroll") for (int m = 0; m < 4; ++m) _Pragma("unroll") for (int k = 0; k < 2; ++k) dst[m][k] = *(const PG8_LAS bf16x8*)(lds + PG8_SA(b, h) + aoff + m * 2048 + k * 1024); } while (0)
; #define PG8_LDB(dst, b, h) do { _Pragma("unroll") for (int n = 0; n < 2; ++n) _Pragma("unroll") for (int k = 0; k < 2; ++k) dst[n][k] = *(const PG8_LAS bf16x8*)(lds + PG8_SB(b, h) + boff + n * 2048 + k * 1024); } while (0)
; #define PG8_MMA(ai, bj, At, Bt) do { __builtin_amdgcn_s_setprio(1); _Pragma("unroll") for (int m = 0; m < 4; ++m) _Pragma("unroll") for (int n = 0; n < 2; ++n) _Pragma("unroll") for (int k = 0; k < 2; ++k) \
;         acc[ai][bj][m][n] = __builtin_amdgcn_mfma_f32_16x16x32_bf16(Bt[n][k], At[m][k], acc[ai][bj][m][n], 0, 0, 0); __builtin_amdgcn_s_setprio(0); } while (0)
; #define PG8_WAIT_V(n) asm volatile("s_waitcnt vmcnt(" #n ")" ::: "memory")
; #define PG8_WAIT_L(n) asm volatile("s_waitcnt lgkmcnt(" #n ")" ::: "memory")
; #define PG8_BAR __builtin_amdgcn_s_barrier()
; #define PG8_SCHED __builtin_amdgcn_sched_barrier(0)
; template <class Epi, class Sched, bool ALIGN_EPI = false, bool SP2 = false>
; __device__ __forceinline__ void gemm_phase(PG8_LAS unsigned char* lds, const Gemm g, const Sched& S, const Epi& E, const int tid_in) {
;     ...
;             PG8_LDB(B0, 1, 0); PG8_LDB(B1, 1, 1); PG8_SCHED; PG8_LDA(At, 1, 0); PG8_STAGE(PG8_SA(0, 1), a2 + hstep, voffA);
;             PG8_WAIT_V(8); PG8_WAIT_L(0); PG8_BAR; PG8_MMA(0, 0, At, B0); PG8_MMA(0, 1, At, B1); PG8_BAR; PG8_SCHED;
	s_add_i32 s71, 0, 0x18000
	v_add_u32_e32 v171, s71, v166
	s_add_i32 s72, 0, 0x1c000
	ds_read_b128 v[144:147], v171
	ds_read_b128 v[172:175], v171 offset:1024
	ds_read_b128 v[176:179], v171 offset:2048
	ds_read_b128 v[180:183], v171 offset:3072
	v_add_u32_e32 v171, s72, v166
	ds_read_b128 v[184:187], v171
	ds_read_b128 v[188:191], v171 offset:1024
	ds_read_b128 v[192:195], v171 offset:2048
	ds_read_b128 v[196:199], v171 offset:3072
	s_add_u32 s44, s44, 0x40000
	s_addc_u32 s45, s45, 0
	s_mov_b32 m0, s58
	v_lshl_add_u64 v[238:239], s[44:45], 0, v[134:135]
	ds_read_b128 v[200:203], v170 offset:32768
	ds_read_b128 v[204:207], v170 offset:33792
	ds_read_b128 v[208:211], v170 offset:34816
	ds_read_b128 v[212:215], v170 offset:35840
	ds_read_b128 v[216:219], v170 offset:36864
	ds_read_b128 v[220:223], v170 offset:37888
	ds_read_b128 v[224:227], v170 offset:38912
	ds_read_b128 v[228:231], v170 offset:39936
	global_load_lds_dwordx4 v[238:239], off
	v_lshl_add_u64 v[238:239], s[44:45], 0, v[130:131]
	s_mov_b32 m0, s59
	s_nop 0
	global_load_lds_dwordx4 v[238:239], off
	s_waitcnt vmcnt(10)
	s_waitcnt lgkmcnt(0)
	s_barrier
	s_waitcnt lgkmcnt(0)
	v_mfma_f32_16x16x32_bf16 v[124:127], v[144:147], v[200:203], v[124:127]
	v_mfma_f32_16x16x32_bf16 v[120:123], v[176:179], v[200:203], v[120:123]
	v_mfma_f32_16x16x32_bf16 v[116:119], v[144:147], v[208:211], v[116:119]
	v_mfma_f32_16x16x32_bf16 v[104:107], v[176:179], v[208:211], v[104:107]
	v_mfma_f32_16x16x32_bf16 v[100:103], v[144:147], v[216:219], v[100:103]
	v_mfma_f32_16x16x32_bf16 v[88:91], v[176:179], v[216:219], v[88:91]
	v_mfma_f32_16x16x32_bf16 v[84:87], v[144:147], v[224:227], v[84:87]
	v_mfma_f32_16x16x32_bf16 v[72:75], v[176:179], v[224:227], v[72:75]
	v_mfma_f32_16x16x32_bf16 v[124:127], v[172:175], v[204:207], v[124:127]
	v_mfma_f32_16x16x32_bf16 v[120:123], v[180:183], v[204:207], v[120:123]
	v_mfma_f32_16x16x32_bf16 v[116:119], v[172:175], v[212:215], v[116:119]
	v_mfma_f32_16x16x32_bf16 v[104:107], v[180:183], v[212:215], v[104:107]
	v_mfma_f32_16x16x32_bf16 v[100:103], v[172:175], v[220:223], v[100:103]
	v_mfma_f32_16x16x32_bf16 v[88:91], v[180:183], v[220:223], v[88:91]
	v_mfma_f32_16x16x32_bf16 v[84:87], v[172:175], v[228:231], v[84:87]
	v_mfma_f32_16x16x32_bf16 v[72:75], v[180:183], v[228:231], v[72:75]
	v_mfma_f32_16x16x32_bf16 v[112:115], v[184:187], v[200:203], v[112:115]
	v_mfma_f32_16x16x32_bf16 v[108:111], v[192:195], v[200:203], v[108:111]
	v_mfma_f32_16x16x32_bf16 v[96:99], v[184:187], v[208:211], v[96:99]
	v_mfma_f32_16x16x32_bf16 v[92:95], v[192:195], v[208:211], v[92:95]
	v_mfma_f32_16x16x32_bf16 v[80:83], v[184:187], v[216:219], v[80:83]
	v_mfma_f32_16x16x32_bf16 v[76:79], v[192:195], v[216:219], v[76:79]
	v_mfma_f32_16x16x32_bf16 v[68:71], v[184:187], v[224:227], v[68:71]
	v_mfma_f32_16x16x32_bf16 v[64:67], v[192:195], v[224:227], v[64:67]
	v_mfma_f32_16x16x32_bf16 v[112:115], v[188:191], v[204:207], v[112:115]
	v_mfma_f32_16x16x32_bf16 v[108:111], v[196:199], v[204:207], v[108:111]
	v_mfma_f32_16x16x32_bf16 v[96:99], v[188:191], v[212:215], v[96:99]
	v_mfma_f32_16x16x32_bf16 v[92:95], v[196:199], v[212:215], v[92:95]
	v_mfma_f32_16x16x32_bf16 v[80:83], v[188:191], v[220:223], v[80:83]
	v_mfma_f32_16x16x32_bf16 v[76:79], v[196:199], v[220:223], v[76:79]
	v_mfma_f32_16x16x32_bf16 v[68:71], v[188:191], v[228:231], v[68:71]
	v_mfma_f32_16x16x32_bf16 v[64:67], v[196:199], v[228:231], v[64:67]
	s_barrier
; #define PG8_STAGE(bufoff, gbase, voff) do { _Pragma("unroll") for (int _i = 0; _i < 2; ++_i) \
;         __builtin_amdgcn_global_load_lds((const unsigned*)((const char*)(gbase) + (voff)[_i]), (PG8_LAS unsigned*)(lds + (bufoff) + ldsw + _i * 8192), 16, 0, 0); } while (0)
; #define PG8_LDA(dst, b, h) do { _Pragma("unroll") for (int m = 0; m < 4; ++m) _Pragma("unroll") for (int k = 0; k < 2; ++k) dst[m][k] = *(const PG8_LAS bf16x8*)(lds + PG8_SA(b, h) + aoff + m * 2048 + k * 1024); } while (0)
; #define PG8_MMA(ai, bj, At, Bt) do { __builtin_amdgcn_s_setprio(1); _Pragma("unroll") for (int m = 0; m < 4; ++m) _Pragma("unroll") for (int n = 0; n < 2; ++n) _Pragma("unroll") for (int k = 0; k < 2; ++k) \
;         acc[ai][bj][m][n] = __builtin_amdgcn_mfma_f32_16x16x32_bf16(Bt[n][k], At[m][k], acc[ai][bj][m][n], 0, 0, 0); __builtin_amdgcn_s_setprio(0); } while (0)
; #define PG8_WAIT_V(n) asm volatile("s_waitcnt vmcnt(" #n ")" ::: "memory")
; #define PG8_WAIT_L(n) asm volatile("s_waitcnt lgkmcnt(" #n ")" ::: "memory")
; #define PG8_BAR __builtin_amdgcn_s_barrier()
; #define PG8_SCHED __builtin_amdgcn_sched_barrier(0)
; template <class Epi, class Sched, bool ALIGN_EPI = false, bool SP2 = false>
; __device__ __forceinline__ void gemm_phase(PG8_LAS unsigned char* lds, const Gemm g, const Sched& S, const Epi& E, const int tid_in) {
;     ...
;         for (int t = 0; t < nt; t += 2) {
;     ...
;             PG8_LDA(At, 1, 1); PG8_STAGE(PG8_SB(1, 0), b3, voffB); PG8_STAGE(PG8_SB(1, 1), b3 + hstep, voffB); PG8_STAGE(PG8_SA(1, 0), a3, voffA);
;             PG8_WAIT_V(8); PG8_WAIT_L(0); PG8_BAR; PG8_MMA(1, 0, At, B0); PG8_MMA(1, 1, At, B1); PG8_BAR; PG8_SCHED;
	s_add_i32 s44, s71, s56
	v_lshl_add_u64 v[148:149], v[148:149], 0, s[20:21]
	s_mov_b32 m0, s44
	ds_read_b128 v[200:203], v170 offset:49152
	ds_read_b128 v[204:207], v170 offset:50176
	ds_read_b128 v[208:211], v170 offset:51200
	ds_read_b128 v[212:215], v170 offset:52224
	ds_read_b128 v[216:219], v170 offset:53248
	ds_read_b128 v[220:223], v170 offset:54272
	ds_read_b128 v[224:227], v170 offset:55296
	ds_read_b128 v[228:231], v170 offset:56320
	global_load_lds_dwordx4 v[148:149], off
	s_add_i32 m0, s44, 0x2000
	s_add_u32 s42, s42, 0x40080
	v_lshl_add_u64 v[148:149], v[232:233], 0, s[20:21]
	s_addc_u32 s43, s43, 0
	s_add_i32 s44, s72, s56
	global_load_lds_dwordx4 v[148:149], off
	v_lshl_add_u64 v[148:149], s[42:43], 0, v[132:133]
	s_mov_b32 m0, s44
	s_nop 0
	global_load_lds_dwordx4 v[148:149], off
	v_lshl_add_u64 v[148:149], s[42:43], 0, v[128:129]
	s_add_i32 m0, s44, 0x2000
	s_nop 0
	global_load_lds_dwordx4 v[148:149], off
	v_lshl_add_u64 v[148:149], v[234:235], 0, s[20:21]
	s_mov_b32 m0, s60
	s_nop 0
	global_load_lds_dwordx4 v[148:149], off
	v_lshl_add_u64 v[148:149], v[236:237], 0, s[20:21]
	s_mov_b32 m0, s61
	s_nop 0
	global_load_lds_dwordx4 v[148:149], off
	s_waitcnt vmcnt(10)
	s_waitcnt lgkmcnt(0)
	s_barrier
	s_waitcnt lgkmcnt(0)
	v_mfma_f32_16x16x32_bf16 v[60:63], v[144:147], v[200:203], v[60:63]
	v_mfma_f32_16x16x32_bf16 v[56:59], v[176:179], v[200:203], v[56:59]
	v_mfma_f32_16x16x32_bf16 v[52:55], v[144:147], v[208:211], v[52:55]
	v_mfma_f32_16x16x32_bf16 v[40:43], v[176:179], v[208:211], v[40:43]
	v_mfma_f32_16x16x32_bf16 v[36:39], v[144:147], v[216:219], v[36:39]
	v_mfma_f32_16x16x32_bf16 v[24:27], v[176:179], v[216:219], v[24:27]
	v_mfma_f32_16x16x32_bf16 v[20:23], v[144:147], v[224:227], v[20:23]
	v_mfma_f32_16x16x32_bf16 v[8:11], v[176:179], v[224:227], v[8:11]
	v_mfma_f32_16x16x32_bf16 v[60:63], v[172:175], v[204:207], v[60:63]
	v_mfma_f32_16x16x32_bf16 v[56:59], v[180:183], v[204:207], v[56:59]
	v_mfma_f32_16x16x32_bf16 v[52:55], v[172:175], v[212:215], v[52:55]
	v_mfma_f32_16x16x32_bf16 v[40:43], v[180:183], v[212:215], v[40:43]
	v_mfma_f32_16x16x32_bf16 v[36:39], v[172:175], v[220:223], v[36:39]
	v_mfma_f32_16x16x32_bf16 v[24:27], v[180:183], v[220:223], v[24:27]
	v_mfma_f32_16x16x32_bf16 v[20:23], v[172:175], v[228:231], v[20:23]
	v_mfma_f32_16x16x32_bf16 v[8:11], v[180:183], v[228:231], v[8:11]
	v_mfma_f32_16x16x32_bf16 v[48:51], v[184:187], v[200:203], v[48:51]
	v_mfma_f32_16x16x32_bf16 v[44:47], v[192:195], v[200:203], v[44:47]
	v_mfma_f32_16x16x32_bf16 v[32:35], v[184:187], v[208:211], v[32:35]
	v_mfma_f32_16x16x32_bf16 v[28:31], v[192:195], v[208:211], v[28:31]
	v_mfma_f32_16x16x32_bf16 v[16:19], v[184:187], v[216:219], v[16:19]
	v_mfma_f32_16x16x32_bf16 v[12:15], v[192:195], v[216:219], v[12:15]
	v_mfma_f32_16x16x32_bf16 v[4:7], v[184:187], v[224:227], v[4:7]
	v_mfma_f32_16x16x32_bf16 v[0:3], v[192:195], v[224:227], v[0:3]
	v_mfma_f32_16x16x32_bf16 v[48:51], v[188:191], v[204:207], v[48:51]
	v_mfma_f32_16x16x32_bf16 v[44:47], v[196:199], v[204:207], v[44:47]
	v_mfma_f32_16x16x32_bf16 v[32:35], v[188:191], v[212:215], v[32:35]
	v_mfma_f32_16x16x32_bf16 v[28:31], v[196:199], v[212:215], v[28:31]
	v_mfma_f32_16x16x32_bf16 v[16:19], v[188:191], v[220:223], v[16:19]
	v_mfma_f32_16x16x32_bf16 v[12:15], v[196:199], v[220:223], v[12:15]
	v_mfma_f32_16x16x32_bf16 v[4:7], v[188:191], v[228:231], v[4:7]
	v_mfma_f32_16x16x32_bf16 v[0:3], v[196:199], v[228:231], v[0:3]
	s_barrier
	s_add_i32 s70, s70, 2
	s_add_u32 s0, s0, 0x100
	s_addc_u32 s1, s1, 0
	s_add_u32 s68, s68, 0x100
	s_addc_u32 s69, s69, 0
	s_cmp_gt_u32 s70, 13
	s_cbranch_scc0 .LBB0_1080
	s_and_b64 vcc, exec, s[22:23]
	s_cbranch_vccz .LBB0_1083
	s_barrier
